# as v53 + K-loop load segments: scalar set-up and the two LDS-DMA loads issued before the segment's ds_reads
# baseline (speedup 1.0000x reference)
; #define PG8_STAGE(bufoff, gbase, voff) do { _Pragma("unroll") for (int _i = 0; _i < 2; ++_i) \
;         __builtin_amdgcn_global_load_lds((const unsigned*)((const char*)(gbase) + (voff)[_i]), (LAS unsigned*)(lds + (bufoff) + ldsw + _i * 8192), 16, 0, 0); } while (0)
; #define PG8_LDA(dst, b, h) do { _Pragma("unroll") for (int m = 0; m < 4; ++m) _Pragma("unroll") for (int k = 0; k < 2; ++k) dst[m][k] = *(const LAS bf16x8*)(lds + PG8_SA(b, h) + aoff + m * 2048 + k * 1024); } while (0)
; #define PG8_LDB(dst, b, h) do { _Pragma("unroll") for (int n = 0; n < 2; ++n) _Pragma("unroll") for (int k = 0; k < 2; ++k) dst[n][k] = *(const LAS bf16x8*)(lds + PG8_SB(b, h) + boff + n * 2048 + k * 1024); } while (0)
; #define PG8_MMA(ai, bj, At, Bt) do { __builtin_amdgcn_s_setprio(1); _Pragma("unroll") for (int m = 0; m < 4; ++m) _Pragma("unroll") for (int n = 0; n < 2; ++n) _Pragma("unroll") for (int k = 0; k < 2; ++k) \
;         acc[ai][bj][m][n] = __builtin_amdgcn_mfma_f32_16x16x32_bf16(Bt[n][k], At[m][k], acc[ai][bj][m][n], 0, 0, 0); __builtin_amdgcn_s_setprio(0); } while (0)
; #define PG8_WAIT_V(n) asm volatile("s_waitcnt vmcnt(" #n ")" ::: "memory")
; #define PG8_BAR __builtin_amdgcn_s_barrier()
; template <class Epi>
; __device__ __forceinline__ void gemm_phase(LAS unsigned char* lds, const Gemm g, const StaticOrder& S, const Epi& E) {
;     ...
;             const bool last = (t == nt - 2);
;             const char* a1 = cA + (size_t)(t + 1) * kstepA;
;             const char* a2 = last ? nA : cA + (size_t)(t + 2) * kstepA; const char* b2 = last ? nB : cB + (size_t)(t + 2) * kstep;
;             const char* a3 = a2 + kstepA; const char* b3 = b2 + kstep;
;             PG8_LDB(B0, 0, 0); PG8_SCHED; PG8_LDA(At, 0, 0); PG8_STAGE(PG8_SA(1, 1), a1 + hstepA, voffA);
;             PG8_WAIT_L(8); PG8_BAR; PG8_WAIT_L(0); PG8_MMA(0, 0, At, B0); PG8_BAR; PG8_SCHED;
;             PG8_LDB(B1, 0, 1); PG8_STAGE(PG8_SB(0, 0), b2, voffB);
;             PG8_BAR; PG8_WAIT_L(0); PG8_MMA(0, 1, At, B1); PG8_BAR;
;             PG8_LDA(At, 0, 1); PG8_STAGE(PG8_SA(0, 0), a2, voffA);
;             PG8_BAR; PG8_WAIT_L(0); PG8_MMA(1, 0, At, B0); PG8_BAR; PG8_SCHED;
;             PG8_STAGE(PG8_SB(0, 1), b2 + hstepB, voffB);
;             PG8_WAIT_V(6); PG8_BAR; PG8_MMA(1, 1, At, B1); PG8_BAR;
;             PG8_LDB(B0, 1, 0); PG8_SCHED; PG8_LDA(At, 1, 0); PG8_STAGE(PG8_SA(0, 1), a2 + hstepA, voffA);
.LBB0_158:
	s_add_u32 s42, s38, 0x100
	s_addc_u32 s43, s39, 0
	s_add_i32 s60, 0, 0x10000
	s_cmp_eq_u32 s59, 28
	s_cselect_b32 s25, s23, s43
	s_cselect_b32 s24, s55, s42
	s_cselect_b32 s5, s21, s58
	s_cselect_b32 s4, s56, s57
	s_add_i32 m0, s46, 0xc000
	s_nop 0
	global_load_lds_dwordx4 v140, s[38:39]
	s_add_i32 m0, s46, 0xe000
	s_nop 0
	global_load_lds_dwordx4 v142, s[38:39]
	ds_read_b128 v[146:149], v250
	ds_read_b128 v[162:165], v250 offset:1024
	ds_read_b128 v[166:169], v250 offset:2048
	ds_read_b128 v[170:173], v250 offset:3072
	ds_read_b128 v[174:177], v154
	ds_read_b128 v[188:191], v154 offset:1024
	ds_read_b128 v[192:195], v154 offset:2048
	ds_read_b128 v[196:199], v154 offset:3072
	ds_read_b128 v[200:203], v154 offset:4096
	ds_read_b128 v[204:207], v154 offset:5120
	ds_read_b128 v[208:211], v154 offset:6144
	ds_read_b128 v[212:215], v154 offset:7168
	s_waitcnt lgkmcnt(8)
	s_barrier
	s_waitcnt lgkmcnt(0)
	v_mfma_f32_16x16x32_bf16 v[126:129], v[146:149], v[174:177], v[126:129]
	v_mfma_f32_16x16x32_bf16 v[122:125], v[166:169], v[174:177], v[122:125]
	v_mfma_f32_16x16x32_bf16 v[110:113], v[146:149], v[192:195], v[110:113]
	v_mfma_f32_16x16x32_bf16 v[106:109], v[166:169], v[192:195], v[106:109]
	v_mfma_f32_16x16x32_bf16 v[94:97], v[146:149], v[200:203], v[94:97]
	v_mfma_f32_16x16x32_bf16 v[90:93], v[166:169], v[200:203], v[90:93]
	v_mfma_f32_16x16x32_bf16 v[78:81], v[146:149], v[208:211], v[78:81]
	v_mfma_f32_16x16x32_bf16 v[74:77], v[166:169], v[208:211], v[74:77]
	v_mfma_f32_16x16x32_bf16 v[126:129], v[162:165], v[188:191], v[126:129]
	v_mfma_f32_16x16x32_bf16 v[122:125], v[170:173], v[188:191], v[122:125]
	v_mfma_f32_16x16x32_bf16 v[110:113], v[162:165], v[196:199], v[110:113]
	v_mfma_f32_16x16x32_bf16 v[106:109], v[170:173], v[196:199], v[106:109]
	v_mfma_f32_16x16x32_bf16 v[94:97], v[162:165], v[204:207], v[94:97]
	v_mfma_f32_16x16x32_bf16 v[90:93], v[170:173], v[204:207], v[90:93]
	v_mfma_f32_16x16x32_bf16 v[78:81], v[162:165], v[212:215], v[78:81]
	v_mfma_f32_16x16x32_bf16 v[74:77], v[170:173], v[212:215], v[74:77]
	s_barrier
	s_add_i32 s61, 0, 0x14000
	s_add_i32 s38, s60, s45
	s_add_u32 s100, s4, s6
	s_addc_u32 s101, s5, s7
	s_mov_b32 m0, s38
	s_nop 0
	global_load_lds_dwordx4 v134, s[4:5]
	s_add_i32 m0, s38, 0x2000
	s_nop 0
	global_load_lds_dwordx4 v130, s[4:5]
	ds_read_b128 v[216:219], v250 offset:16384
	ds_read_b128 v[220:223], v250 offset:17408
	ds_read_b128 v[224:227], v250 offset:18432
	ds_read_b128 v[228:231], v250 offset:19456
	s_barrier
	s_waitcnt lgkmcnt(0)
	v_mfma_f32_16x16x32_bf16 v[118:121], v[216:219], v[174:177], v[118:121]
	v_mfma_f32_16x16x32_bf16 v[114:117], v[224:227], v[174:177], v[114:117]
	v_mfma_f32_16x16x32_bf16 v[102:105], v[216:219], v[192:195], v[102:105]
	v_mfma_f32_16x16x32_bf16 v[98:101], v[224:227], v[192:195], v[98:101]
	v_mfma_f32_16x16x32_bf16 v[86:89], v[216:219], v[200:203], v[86:89]
	v_mfma_f32_16x16x32_bf16 v[82:85], v[224:227], v[200:203], v[82:85]
	v_mfma_f32_16x16x32_bf16 v[70:73], v[216:219], v[208:211], v[70:73]
	v_mfma_f32_16x16x32_bf16 v[66:69], v[224:227], v[208:211], v[66:69]
	v_mfma_f32_16x16x32_bf16 v[118:121], v[220:223], v[188:191], v[118:121]
	v_mfma_f32_16x16x32_bf16 v[114:117], v[228:231], v[188:191], v[114:117]
	v_mfma_f32_16x16x32_bf16 v[102:105], v[220:223], v[196:199], v[102:105]
	v_mfma_f32_16x16x32_bf16 v[98:101], v[228:231], v[196:199], v[98:101]
	v_mfma_f32_16x16x32_bf16 v[86:89], v[220:223], v[204:207], v[86:89]
	v_mfma_f32_16x16x32_bf16 v[82:85], v[228:231], v[204:207], v[82:85]
	v_mfma_f32_16x16x32_bf16 v[70:73], v[220:223], v[212:215], v[70:73]
	v_mfma_f32_16x16x32_bf16 v[66:69], v[228:231], v[212:215], v[66:69]
	s_mov_b32 m0, s46
	s_add_u32 vcc_lo, s24, s6
	s_addc_u32 vcc_hi, s25, s7
	s_barrier
	global_load_lds_dwordx4 v136, s[24:25]
	s_mov_b32 m0, s47
	s_nop 0
	global_load_lds_dwordx4 v132, s[24:25]
	ds_read_b128 v[174:177], v154 offset:16384
	ds_read_b128 v[188:191], v154 offset:17408
	ds_read_b128 v[192:195], v154 offset:18432
	ds_read_b128 v[196:199], v154 offset:19456
	ds_read_b128 v[200:203], v154 offset:20480
	ds_read_b128 v[204:207], v154 offset:21504
	ds_read_b128 v[208:211], v154 offset:22528
	ds_read_b128 v[212:215], v154 offset:23552
	s_barrier
	s_waitcnt lgkmcnt(0)
	v_mfma_f32_16x16x32_bf16 v[62:65], v[146:149], v[174:177], v[62:65]
	v_mfma_f32_16x16x32_bf16 v[58:61], v[166:169], v[174:177], v[58:61]
	v_mfma_f32_16x16x32_bf16 v[46:49], v[146:149], v[192:195], v[46:49]
	v_mfma_f32_16x16x32_bf16 v[42:45], v[166:169], v[192:195], v[42:45]
	v_mfma_f32_16x16x32_bf16 v[30:33], v[146:149], v[200:203], v[30:33]
	v_mfma_f32_16x16x32_bf16 v[26:29], v[166:169], v[200:203], v[26:29]
	v_mfma_f32_16x16x32_bf16 v[14:17], v[146:149], v[208:211], v[14:17]
	v_mfma_f32_16x16x32_bf16 v[10:13], v[166:169], v[208:211], v[10:13]
	v_mfma_f32_16x16x32_bf16 v[62:65], v[162:165], v[188:191], v[62:65]
	v_mfma_f32_16x16x32_bf16 v[58:61], v[170:173], v[188:191], v[58:61]
	v_mfma_f32_16x16x32_bf16 v[46:49], v[162:165], v[196:199], v[46:49]
	v_mfma_f32_16x16x32_bf16 v[42:45], v[170:173], v[196:199], v[42:45]
	v_mfma_f32_16x16x32_bf16 v[30:33], v[162:165], v[204:207], v[30:33]
	v_mfma_f32_16x16x32_bf16 v[26:29], v[170:173], v[204:207], v[26:29]
	v_mfma_f32_16x16x32_bf16 v[14:17], v[162:165], v[212:215], v[14:17]
	v_mfma_f32_16x16x32_bf16 v[10:13], v[170:173], v[212:215], v[10:13]
	s_barrier
	s_add_u32 s38, s4, 0x80000
	s_addc_u32 s39, s5, 0
	s_add_i32 s60, s61, s45
	s_mov_b32 m0, s60
	s_nop 0
	global_load_lds_dwordx4 v134, s[38:39]
	s_add_i32 m0, s60, 0x2000
	s_nop 0
	global_load_lds_dwordx4 v130, s[38:39]
	s_waitcnt vmcnt(6)
	s_barrier
; #define PG8_STAGE(bufoff, gbase, voff) do { _Pragma("unroll") for (int _i = 0; _i < 2; ++_i) \
;         __builtin_amdgcn_global_load_lds((const unsigned*)((const char*)(gbase) + (voff)[_i]), (LAS unsigned*)(lds + (bufoff) + ldsw + _i * 8192), 16, 0, 0); } while (0)
; #define PG8_LDA(dst, b, h) do { _Pragma("unroll") for (int m = 0; m < 4; ++m) _Pragma("unroll") for (int k = 0; k < 2; ++k) dst[m][k] = *(const LAS bf16x8*)(lds + PG8_SA(b, h) + aoff + m * 2048 + k * 1024); } while (0)
; #define PG8_LDB(dst, b, h) do { _Pragma("unroll") for (int n = 0; n < 2; ++n) _Pragma("unroll") for (int k = 0; k < 2; ++k) dst[n][k] = *(const LAS bf16x8*)(lds + PG8_SB(b, h) + boff + n * 2048 + k * 1024); } while (0)
; #define PG8_MMA(ai, bj, At, Bt) do { __builtin_amdgcn_s_setprio(1); _Pragma("unroll") for (int m = 0; m < 4; ++m) _Pragma("unroll") for (int n = 0; n < 2; ++n) _Pragma("unroll") for (int k = 0; k < 2; ++k) \
;         acc[ai][bj][m][n] = __builtin_amdgcn_mfma_f32_16x16x32_bf16(Bt[n][k], At[m][k], acc[ai][bj][m][n], 0, 0, 0); __builtin_amdgcn_s_setprio(0); } while (0)
; #define PG8_WAIT_V(n) asm volatile("s_waitcnt vmcnt(" #n ")" ::: "memory")
; #define PG8_WAIT_L(n) asm volatile("s_waitcnt lgkmcnt(" #n ")" ::: "memory")
; #define PG8_BAR __builtin_amdgcn_s_barrier()
; #define PG8_SCHED __builtin_amdgcn_sched_barrier(0)
; template <class Epi>
; __device__ __forceinline__ void gemm_phase(LAS unsigned char* lds, const Gemm g, const StaticOrder& S, const Epi& E) {
;     ...
;             PG8_WAIT_V(6); PG8_BAR; PG8_MMA(1, 1, At, B1); PG8_BAR;
;             PG8_LDB(B0, 1, 0); PG8_SCHED; PG8_LDA(At, 1, 0); PG8_STAGE(PG8_SA(0, 1), a2 + hstepA, voffA);
;             PG8_WAIT_L(8); PG8_BAR; PG8_WAIT_L(0); PG8_MMA(0, 0, At, B0); PG8_BAR; PG8_SCHED;
;             PG8_LDB(B1, 1, 1); PG8_STAGE(PG8_SB(1, 0), b3, voffB);
;             PG8_BAR; PG8_WAIT_L(0); PG8_MMA(0, 1, At, B1); PG8_BAR;
;             PG8_LDA(At, 1, 1); PG8_STAGE(PG8_SA(1, 0), a3, voffA);
;             PG8_BAR; PG8_WAIT_L(0); PG8_MMA(1, 0, At, B0); PG8_BAR; PG8_SCHED;
	v_mfma_f32_16x16x32_bf16 v[54:57], v[216:219], v[174:177], v[54:57]
	v_mfma_f32_16x16x32_bf16 v[50:53], v[224:227], v[174:177], v[50:53]
	v_mfma_f32_16x16x32_bf16 v[38:41], v[216:219], v[192:195], v[38:41]
	v_mfma_f32_16x16x32_bf16 v[34:37], v[224:227], v[192:195], v[34:37]
	v_mfma_f32_16x16x32_bf16 v[22:25], v[216:219], v[200:203], v[22:25]
	v_mfma_f32_16x16x32_bf16 v[18:21], v[224:227], v[200:203], v[18:21]
	v_mfma_f32_16x16x32_bf16 v[6:9], v[216:219], v[208:211], v[6:9]
	v_mfma_f32_16x16x32_bf16 v[2:5], v[224:227], v[208:211], v[2:5]
	v_mfma_f32_16x16x32_bf16 v[54:57], v[220:223], v[188:191], v[54:57]
	v_mfma_f32_16x16x32_bf16 v[50:53], v[228:231], v[188:191], v[50:53]
	v_mfma_f32_16x16x32_bf16 v[38:41], v[220:223], v[196:199], v[38:41]
	v_mfma_f32_16x16x32_bf16 v[34:37], v[228:231], v[196:199], v[34:37]
	v_mfma_f32_16x16x32_bf16 v[22:25], v[220:223], v[204:207], v[22:25]
	v_mfma_f32_16x16x32_bf16 v[18:21], v[228:231], v[204:207], v[18:21]
	v_mfma_f32_16x16x32_bf16 v[6:9], v[220:223], v[212:215], v[6:9]
	v_mfma_f32_16x16x32_bf16 v[2:5], v[228:231], v[212:215], v[2:5]
	s_add_i32 s38, 0, 0x18000
	s_barrier
	s_add_u32 s24, s24, 0x80000
	s_addc_u32 s25, s25, 0
	s_mov_b32 m0, s48
	s_nop 0
	global_load_lds_dwordx4 v136, s[24:25]
	s_mov_b32 m0, s49
	s_nop 0
	global_load_lds_dwordx4 v132, s[24:25]
	ds_read_b128 v[146:149], v250 offset:32768
	ds_read_b128 v[162:165], v250 offset:33792
	ds_read_b128 v[166:169], v250 offset:34816
	ds_read_b128 v[170:173], v250 offset:35840
	ds_read_b128 v[174:177], v154 offset:32768
	ds_read_b128 v[188:191], v154 offset:33792
	ds_read_b128 v[192:195], v154 offset:34816
	ds_read_b128 v[196:199], v154 offset:35840
	ds_read_b128 v[200:203], v154 offset:36864
	ds_read_b128 v[204:207], v154 offset:37888
	ds_read_b128 v[208:211], v154 offset:38912
	ds_read_b128 v[212:215], v154 offset:39936
	s_waitcnt lgkmcnt(8)
	s_barrier
	s_waitcnt lgkmcnt(0)
	v_mfma_f32_16x16x32_bf16 v[126:129], v[146:149], v[174:177], v[126:129]
	v_mfma_f32_16x16x32_bf16 v[122:125], v[166:169], v[174:177], v[122:125]
	v_mfma_f32_16x16x32_bf16 v[110:113], v[146:149], v[192:195], v[110:113]
	v_mfma_f32_16x16x32_bf16 v[106:109], v[166:169], v[192:195], v[106:109]
	v_mfma_f32_16x16x32_bf16 v[94:97], v[146:149], v[200:203], v[94:97]
	v_mfma_f32_16x16x32_bf16 v[90:93], v[166:169], v[200:203], v[90:93]
	v_mfma_f32_16x16x32_bf16 v[78:81], v[146:149], v[208:211], v[78:81]
	v_mfma_f32_16x16x32_bf16 v[74:77], v[166:169], v[208:211], v[74:77]
	v_mfma_f32_16x16x32_bf16 v[126:129], v[162:165], v[188:191], v[126:129]
	v_mfma_f32_16x16x32_bf16 v[122:125], v[170:173], v[188:191], v[122:125]
	v_mfma_f32_16x16x32_bf16 v[110:113], v[162:165], v[196:199], v[110:113]
	v_mfma_f32_16x16x32_bf16 v[106:109], v[170:173], v[196:199], v[106:109]
	v_mfma_f32_16x16x32_bf16 v[94:97], v[162:165], v[204:207], v[94:97]
	v_mfma_f32_16x16x32_bf16 v[90:93], v[170:173], v[204:207], v[90:93]
	v_mfma_f32_16x16x32_bf16 v[78:81], v[162:165], v[212:215], v[78:81]
	v_mfma_f32_16x16x32_bf16 v[74:77], v[170:173], v[212:215], v[74:77]
	s_barrier
	s_add_i32 s24, 0, 0x1c000
	s_add_i32 s25, s38, s45
	s_mov_b32 m0, s25
	s_nop 0
	global_load_lds_dwordx4 v134, s[100:101]
	s_add_i32 m0, s25, 0x2000
	s_nop 0
	global_load_lds_dwordx4 v130, s[100:101]
	ds_read_b128 v[216:219], v250 offset:49152
	ds_read_b128 v[220:223], v250 offset:50176
	ds_read_b128 v[224:227], v250 offset:51200
	ds_read_b128 v[228:231], v250 offset:52224
	s_barrier
	s_waitcnt lgkmcnt(0)
	v_mfma_f32_16x16x32_bf16 v[118:121], v[216:219], v[174:177], v[118:121]
	v_mfma_f32_16x16x32_bf16 v[114:117], v[224:227], v[174:177], v[114:117]
	v_mfma_f32_16x16x32_bf16 v[102:105], v[216:219], v[192:195], v[102:105]
	v_mfma_f32_16x16x32_bf16 v[98:101], v[224:227], v[192:195], v[98:101]
	v_mfma_f32_16x16x32_bf16 v[86:89], v[216:219], v[200:203], v[86:89]
	v_mfma_f32_16x16x32_bf16 v[82:85], v[224:227], v[200:203], v[82:85]
	v_mfma_f32_16x16x32_bf16 v[70:73], v[216:219], v[208:211], v[70:73]
	v_mfma_f32_16x16x32_bf16 v[66:69], v[224:227], v[208:211], v[66:69]
	v_mfma_f32_16x16x32_bf16 v[118:121], v[220:223], v[188:191], v[118:121]
	v_mfma_f32_16x16x32_bf16 v[114:117], v[228:231], v[188:191], v[114:117]
	v_mfma_f32_16x16x32_bf16 v[102:105], v[220:223], v[196:199], v[102:105]
	v_mfma_f32_16x16x32_bf16 v[98:101], v[228:231], v[196:199], v[98:101]
	v_mfma_f32_16x16x32_bf16 v[86:89], v[220:223], v[204:207], v[86:89]
	v_mfma_f32_16x16x32_bf16 v[82:85], v[228:231], v[204:207], v[82:85]
	v_mfma_f32_16x16x32_bf16 v[70:73], v[220:223], v[212:215], v[70:73]
	v_mfma_f32_16x16x32_bf16 v[66:69], v[228:231], v[212:215], v[66:69]
	s_mov_b32 m0, s50
	s_barrier
; __device__ __forceinline__ unsigned cvt_pk_bf16(float lo, float hi) { unsigned r; asm volatile("v_cvt_pk_bf16_f32 %0, %1, %2" : "=v"(r) : "v"(lo), "v"(hi)); return r; }
; #define PG8_STAGE(bufoff, gbase, voff) do { _Pragma("unroll") for (int _i = 0; _i < 2; ++_i) \
;         __builtin_amdgcn_global_load_lds((const unsigned*)((const char*)(gbase) + (voff)[_i]), (LAS unsigned*)(lds + (bufoff) + ldsw + _i * 8192), 16, 0, 0); } while (0)
; #define PG8_MMA(ai, bj, At, Bt) do { __builtin_amdgcn_s_setprio(1); _Pragma("unroll") for (int m = 0; m < 4; ++m) _Pragma("unroll") for (int n = 0; n < 2; ++n) _Pragma("unroll") for (int k = 0; k < 2; ++k) \
;         acc[ai][bj][m][n] = __builtin_amdgcn_mfma_f32_16x16x32_bf16(Bt[n][k], At[m][k], acc[ai][bj][m][n], 0, 0, 0); __builtin_amdgcn_s_setprio(0); } while (0)
; #define PG8_WAIT_V(n) asm volatile("s_waitcnt vmcnt(" #n ")" ::: "memory")
; #define PG8_WAIT_L(n) asm volatile("s_waitcnt lgkmcnt(" #n ")" ::: "memory")
; template <class Epi>
; __device__ __forceinline__ void gemm_phase(LAS unsigned char* lds, const Gemm g, const StaticOrder& S, const Epi& E) {
;     ...
;             PG8_BAR; PG8_WAIT_L(0); PG8_MMA(1, 0, At, B0); PG8_BAR; PG8_SCHED;
;             PG8_STAGE(PG8_SB(1, 1), b3 + hstepB, voffB);
;             PG8_WAIT_V(6); PG8_BAR; PG8_MMA(1, 1, At, B1); PG8_BAR;
;     __device__ __forceinline__ void operator()(const f32x4 (&acc)[2][2][4][2], const Unit& u, int wr, int wc, int fr, int fq, const Pre& pp) const {
;         const int row0 = u.pm * BM + wr * 64 + fr, col0 = u.pn * BM + wc * 32 + 8 * fq;
;         const bool gm = (UG != nullptr) && (u.pn < DE / BM);
;         const float (&rs)[8] = pp.rs;
; #pragma unroll
;         for (int ai = 0; ai < 2; ++ai)
; #pragma unroll
;             for (int m = 0; m < 4; ++m) { const int r = row0 + ai * HALF + m * 16; const float inv = rsqrtf(rs[ai * 4 + m] * (1.0f / DM) + EPS);
; #pragma unroll
;                 for (int bj = 0; bj < 2; ++bj) { const f32x4 v0 = acc[ai][bj][m][0] * inv, v1 = acc[ai][bj][m][1] * inv; const int c = col0 + bj * HALF;
;                     u32x4 w; w.x = cvt_pk_bf16(v0[0], v0[1]); w.y = cvt_pk_bf16(v0[2], v0[3]); w.z = cvt_pk_bf16(v1[0], v1[1]); w.w = cvt_pk_bf16(v1[2], v1[3]);
;                     bf16_t* dst = gm ? UG + (size_t)(c >> 4) * GSTR + r * 16 + (c & 15) : O + (size_t)r * DE2 + c;
;                     *(u32x4*)dst = w; } }
	global_load_lds_dwordx4 v136, vcc
	s_mov_b32 m0, s51
	s_nop 0
	global_load_lds_dwordx4 v132, vcc
	ds_read_b128 v[174:177], v154 offset:49152
	ds_read_b128 v[188:191], v154 offset:50176
	ds_read_b128 v[192:195], v154 offset:51200
	ds_read_b128 v[196:199], v154 offset:52224
	ds_read_b128 v[200:203], v154 offset:53248
	ds_read_b128 v[204:207], v154 offset:54272
	ds_read_b128 v[208:211], v154 offset:55296
	ds_read_b128 v[212:215], v154 offset:56320
	s_barrier
	s_waitcnt lgkmcnt(0)
	v_mfma_f32_16x16x32_bf16 v[62:65], v[146:149], v[174:177], v[62:65]
	v_mfma_f32_16x16x32_bf16 v[58:61], v[166:169], v[174:177], v[58:61]
	v_mfma_f32_16x16x32_bf16 v[46:49], v[146:149], v[192:195], v[46:49]
	v_mfma_f32_16x16x32_bf16 v[42:45], v[166:169], v[192:195], v[42:45]
	v_mfma_f32_16x16x32_bf16 v[30:33], v[146:149], v[200:203], v[30:33]
	v_mfma_f32_16x16x32_bf16 v[26:29], v[166:169], v[200:203], v[26:29]
	v_mfma_f32_16x16x32_bf16 v[14:17], v[146:149], v[208:211], v[14:17]
	v_mfma_f32_16x16x32_bf16 v[10:13], v[166:169], v[208:211], v[10:13]
	v_mfma_f32_16x16x32_bf16 v[62:65], v[162:165], v[188:191], v[62:65]
	v_mfma_f32_16x16x32_bf16 v[58:61], v[170:173], v[188:191], v[58:61]
	v_mfma_f32_16x16x32_bf16 v[46:49], v[162:165], v[196:199], v[46:49]
	v_mfma_f32_16x16x32_bf16 v[42:45], v[170:173], v[196:199], v[42:45]
	v_mfma_f32_16x16x32_bf16 v[30:33], v[162:165], v[204:207], v[30:33]
	v_mfma_f32_16x16x32_bf16 v[26:29], v[170:173], v[204:207], v[26:29]
	v_mfma_f32_16x16x32_bf16 v[14:17], v[162:165], v[212:215], v[14:17]
	v_mfma_f32_16x16x32_bf16 v[10:13], v[170:173], v[212:215], v[10:13]
	s_barrier
	s_add_u32 s4, s4, 0x80080
	s_addc_u32 s5, s5, 0
	s_add_i32 s24, s24, s45
	s_mov_b32 m0, s24
	s_nop 0
	global_load_lds_dwordx4 v134, s[4:5]
	s_add_i32 m0, s24, 0x2000
	s_nop 0
	global_load_lds_dwordx4 v130, s[4:5]
	s_waitcnt vmcnt(6)
	s_barrier
	v_mfma_f32_16x16x32_bf16 v[54:57], v[216:219], v[174:177], v[54:57]
	v_mfma_f32_16x16x32_bf16 v[50:53], v[224:227], v[174:177], v[50:53]
	v_mfma_f32_16x16x32_bf16 v[38:41], v[216:219], v[192:195], v[38:41]
	v_mfma_f32_16x16x32_bf16 v[34:37], v[224:227], v[192:195], v[34:37]
	v_mfma_f32_16x16x32_bf16 v[22:25], v[216:219], v[200:203], v[22:25]
	v_mfma_f32_16x16x32_bf16 v[18:21], v[224:227], v[200:203], v[18:21]
	v_mfma_f32_16x16x32_bf16 v[6:9], v[216:219], v[208:211], v[6:9]
	v_mfma_f32_16x16x32_bf16 v[2:5], v[224:227], v[208:211], v[2:5]
	v_mfma_f32_16x16x32_bf16 v[54:57], v[220:223], v[188:191], v[54:57]
	v_mfma_f32_16x16x32_bf16 v[50:53], v[228:231], v[188:191], v[50:53]
	v_mfma_f32_16x16x32_bf16 v[38:41], v[220:223], v[196:199], v[38:41]
	v_mfma_f32_16x16x32_bf16 v[34:37], v[228:231], v[196:199], v[34:37]
	v_mfma_f32_16x16x32_bf16 v[22:25], v[220:223], v[204:207], v[22:25]
	v_mfma_f32_16x16x32_bf16 v[18:21], v[228:231], v[204:207], v[18:21]
	v_mfma_f32_16x16x32_bf16 v[6:9], v[220:223], v[212:215], v[6:9]
	v_mfma_f32_16x16x32_bf16 v[2:5], v[228:231], v[212:215], v[2:5]
	s_add_i32 s59, s59, 2
	s_add_u32 s57, s57, 0x100
	s_addc_u32 s58, s58, 0
	s_cmp_gt_u32 s59, 29
	s_mov_b64 s[38:39], s[42:43]
	s_barrier
	s_cbranch_scc0 .LBB0_158
	v_fmamk_f32 v0, v145, 0x3a000000, v233
	v_cmp_gt_f32_e32 vcc, s66, v0
	v_mul_f32_e32 v145, 0x4b800000, v0
	v_readlane_b32 s38, v254, 47
	v_cndmask_b32_e32 v0, v0, v145, vcc
	v_rsq_f32_e32 v0, v0
	v_lshl_add_u32 v146, s54, 8, v139
	s_cmp_gt_i32 s53, 15
	v_readlane_b32 s39, v254, 48
	v_mul_f32_e32 v145, 0x45800000, v0
	s_cselect_b64 s[4:5], -1, 0
	s_xor_b64 s[38:39], s[38:39], -1
	v_cndmask_b32_e32 v148, v0, v145, vcc
	v_ashrrev_i32_e32 v147, 31, v146
	s_or_b64 s[4:5], s[38:39], s[4:5]
	v_lshl_or_b32 v144, s53, 8, v153
	v_lshlrev_b64 v[150:151], 14, v[146:147]
	v_pk_mul_f32 v[128:129], v[148:149], v[128:129] op_sel_hi:[0,1]
	s_mov_b64 s[24:25], -1
	v_pk_mul_f32 v[126:127], v[148:149], v[126:127] op_sel_hi:[0,1]
	v_pk_mul_f32 v[162:163], v[148:149], v[124:125] op_sel_hi:[0,1]
	v_pk_mul_f32 v[124:125], v[148:149], v[122:123] op_sel_hi:[0,1]
	v_cvt_pk_bf16_f32 v122, v126, v127
	v_cvt_pk_bf16_f32 v123, v128, v129
	s_and_b64 vcc, exec, s[4:5]
	v_lshl_add_u64 v[128:129], s[16:17], 0, v[150:151]
	v_ashrrev_i32_e32 v145, 31, v144
	v_cvt_pk_bf16_f32 v124, v124, v125
	v_cvt_pk_bf16_f32 v125, v162, v163
	s_cbranch_vccz .LBB0_161
	v_lshl_add_u64 v[150:151], v[144:145], 1, v[128:129]
	s_mov_b64 s[24:25], 0

; #define PG8_STAGE(bufoff, gbase, voff) do { _Pragma("unroll") for (int _i = 0; _i < 2; ++_i) \
;         __builtin_amdgcn_global_load_lds((const unsigned*)((const char*)(gbase) + (voff)[_i]), (LAS unsigned*)(lds + (bufoff) + ldsw + _i * 8192), 16, 0, 0); } while (0)
; #define PG8_LDA(dst, b, h) do { _Pragma("unroll") for (int m = 0; m < 4; ++m) _Pragma("unroll") for (int k = 0; k < 2; ++k) dst[m][k] = *(const LAS bf16x8*)(lds + PG8_SA(b, h) + aoff + m * 2048 + k * 1024); } while (0)
; #define PG8_LDB(dst, b, h) do { _Pragma("unroll") for (int n = 0; n < 2; ++n) _Pragma("unroll") for (int k = 0; k < 2; ++k) dst[n][k] = *(const LAS bf16x8*)(lds + PG8_SB(b, h) + boff + n * 2048 + k * 1024); } while (0)
; #define PG8_MMA(ai, bj, At, Bt) do { __builtin_amdgcn_s_setprio(1); _Pragma("unroll") for (int m = 0; m < 4; ++m) _Pragma("unroll") for (int n = 0; n < 2; ++n) _Pragma("unroll") for (int k = 0; k < 2; ++k) \
;         acc[ai][bj][m][n] = __builtin_amdgcn_mfma_f32_16x16x32_bf16(Bt[n][k], At[m][k], acc[ai][bj][m][n], 0, 0, 0); __builtin_amdgcn_s_setprio(0); } while (0)
; #define PG8_WAIT_V(n) asm volatile("s_waitcnt vmcnt(" #n ")" ::: "memory")
; #define PG8_WAIT_L(n) asm volatile("s_waitcnt lgkmcnt(" #n ")" ::: "memory")
; #define PG8_BAR __builtin_amdgcn_s_barrier()
; template <class Epi>
; __device__ __forceinline__ void gemm_phase(LAS unsigned char* lds, const Gemm g, const StaticOrder& S, const Epi& E) {
;     ...
;             const bool last = (t == nt - 2);
;             const char* a1 = cA + (size_t)(t + 1) * kstepA;
;             const char* a2 = last ? nA : cA + (size_t)(t + 2) * kstepA; const char* b2 = last ? nB : cB + (size_t)(t + 2) * kstep;
;             const char* a3 = a2 + kstepA; const char* b3 = b2 + kstep;
;             PG8_LDB(B0, 0, 0); PG8_SCHED; PG8_LDA(At, 0, 0); PG8_STAGE(PG8_SA(1, 1), a1 + hstepA, voffA);
;             PG8_WAIT_L(8); PG8_BAR; PG8_WAIT_L(0); PG8_MMA(0, 0, At, B0); PG8_BAR; PG8_SCHED;
;             PG8_LDB(B1, 0, 1); PG8_STAGE(PG8_SB(0, 0), b2, voffB);
;             PG8_BAR; PG8_WAIT_L(0); PG8_MMA(0, 1, At, B1); PG8_BAR;
;             PG8_LDA(At, 0, 1); PG8_STAGE(PG8_SA(0, 0), a2, voffA);
;             PG8_BAR; PG8_WAIT_L(0); PG8_MMA(1, 0, At, B0); PG8_BAR; PG8_SCHED;
;             PG8_STAGE(PG8_SB(0, 1), b2 + hstepB, voffB);
;             PG8_WAIT_V(6); PG8_BAR; PG8_MMA(1, 1, At, B1); PG8_BAR;
.LBB0_359:
	s_add_u32 s26, s22, 0x100
	s_addc_u32 s27, s23, 0
	s_add_i32 s65, 0, 0x10000
	s_cmp_eq_u32 s64, 60
	s_cselect_b32 s25, s17, s27
	s_cselect_b32 s24, s60, s26
	s_cselect_b32 s37, s15, s63
	s_cselect_b32 s36, s61, s62
	s_add_i32 m0, s53, 0xc000
	s_nop 0
	global_load_lds_dwordx4 v190, s[22:23]
	s_add_i32 m0, s53, 0xe000
	s_nop 0
	global_load_lds_dwordx4 v192, s[22:23]
	ds_read_b128 v[70:73], v250
	ds_read_b128 v[74:77], v250 offset:1024
	ds_read_b128 v[82:85], v250 offset:2048
	ds_read_b128 v[86:89], v250 offset:3072
	ds_read_b128 v[146:149], v211
	ds_read_b128 v[150:153], v211 offset:1024
	ds_read_b128 v[154:157], v211 offset:2048
	ds_read_b128 v[158:161], v211 offset:3072
	ds_read_b128 v[162:165], v211 offset:4096
	ds_read_b128 v[166:169], v211 offset:5120
	ds_read_b128 v[170:173], v211 offset:6144
	ds_read_b128 v[184:187], v211 offset:7168
	s_waitcnt lgkmcnt(8)
	s_barrier
	s_waitcnt lgkmcnt(0)
	v_mfma_f32_16x16x32_bf16 v[142:145], v[70:73], v[146:149], v[142:145]
	v_mfma_f32_16x16x32_bf16 v[138:141], v[82:85], v[146:149], v[138:141]
	v_mfma_f32_16x16x32_bf16 v[126:129], v[70:73], v[154:157], v[126:129]
	v_mfma_f32_16x16x32_bf16 v[122:125], v[82:85], v[154:157], v[122:125]
	v_mfma_f32_16x16x32_bf16 v[110:113], v[70:73], v[162:165], v[110:113]
	v_mfma_f32_16x16x32_bf16 v[106:109], v[82:85], v[162:165], v[106:109]
	v_mfma_f32_16x16x32_bf16 v[94:97], v[70:73], v[170:173], v[94:97]
	v_mfma_f32_16x16x32_bf16 v[90:93], v[82:85], v[170:173], v[90:93]
	v_mfma_f32_16x16x32_bf16 v[142:145], v[74:77], v[150:153], v[142:145]
	v_mfma_f32_16x16x32_bf16 v[138:141], v[86:89], v[150:153], v[138:141]
	v_mfma_f32_16x16x32_bf16 v[126:129], v[74:77], v[158:161], v[126:129]
	v_mfma_f32_16x16x32_bf16 v[122:125], v[86:89], v[158:161], v[122:125]
	v_mfma_f32_16x16x32_bf16 v[110:113], v[74:77], v[166:169], v[110:113]
	v_mfma_f32_16x16x32_bf16 v[106:109], v[86:89], v[166:169], v[106:109]
	v_mfma_f32_16x16x32_bf16 v[94:97], v[74:77], v[184:187], v[94:97]
	v_mfma_f32_16x16x32_bf16 v[90:93], v[86:89], v[184:187], v[90:93]
	s_barrier
	s_add_i32 s66, 0, 0x14000
	s_add_i32 s22, s65, s52
	s_add_u32 s100, s36, s6
	s_addc_u32 s101, s37, s7
	s_mov_b32 m0, s22
	s_nop 0
	global_load_lds_dwordx4 v0, s[36:37]
	s_add_i32 m0, s22, 0x2000
	s_nop 0
	global_load_lds_dwordx4 v174, s[36:37]
	ds_read_b128 v[194:197], v250 offset:16384
	ds_read_b128 v[198:201], v250 offset:17408
	ds_read_b128 v[202:205], v250 offset:18432
	ds_read_b128 v[212:215], v250 offset:19456
	s_barrier
	s_waitcnt lgkmcnt(0)
	v_mfma_f32_16x16x32_bf16 v[134:137], v[194:197], v[146:149], v[134:137]
	v_mfma_f32_16x16x32_bf16 v[130:133], v[202:205], v[146:149], v[130:133]
	v_mfma_f32_16x16x32_bf16 v[118:121], v[194:197], v[154:157], v[118:121]
	v_mfma_f32_16x16x32_bf16 v[114:117], v[202:205], v[154:157], v[114:117]
	v_mfma_f32_16x16x32_bf16 v[102:105], v[194:197], v[162:165], v[102:105]
	v_mfma_f32_16x16x32_bf16 v[98:101], v[202:205], v[162:165], v[98:101]
	v_mfma_f32_16x16x32_bf16 v[78:81], v[194:197], v[170:173], v[78:81]
	v_mfma_f32_16x16x32_bf16 v[66:69], v[202:205], v[170:173], v[66:69]
	v_mfma_f32_16x16x32_bf16 v[134:137], v[198:201], v[150:153], v[134:137]
	v_mfma_f32_16x16x32_bf16 v[130:133], v[212:215], v[150:153], v[130:133]
	v_mfma_f32_16x16x32_bf16 v[118:121], v[198:201], v[158:161], v[118:121]
	v_mfma_f32_16x16x32_bf16 v[114:117], v[212:215], v[158:161], v[114:117]
	v_mfma_f32_16x16x32_bf16 v[102:105], v[198:201], v[166:169], v[102:105]
	v_mfma_f32_16x16x32_bf16 v[98:101], v[212:215], v[166:169], v[98:101]
	v_mfma_f32_16x16x32_bf16 v[78:81], v[198:201], v[184:187], v[78:81]
	v_mfma_f32_16x16x32_bf16 v[66:69], v[212:215], v[184:187], v[66:69]
	s_mov_b32 m0, s53
	s_add_u32 vcc_lo, s24, s6
	s_addc_u32 vcc_hi, s25, s7
	s_barrier
	global_load_lds_dwordx4 v188, s[24:25]
	s_mov_b32 m0, s54
	s_nop 0
	global_load_lds_dwordx4 v176, s[24:25]
	ds_read_b128 v[146:149], v211 offset:16384
	ds_read_b128 v[150:153], v211 offset:17408
	ds_read_b128 v[154:157], v211 offset:18432
	ds_read_b128 v[158:161], v211 offset:19456
	ds_read_b128 v[162:165], v211 offset:20480
	ds_read_b128 v[166:169], v211 offset:21504
	ds_read_b128 v[170:173], v211 offset:22528
	ds_read_b128 v[184:187], v211 offset:23552
	s_barrier
	s_waitcnt lgkmcnt(0)
	v_mfma_f32_16x16x32_bf16 v[62:65], v[70:73], v[146:149], v[62:65]
	v_mfma_f32_16x16x32_bf16 v[58:61], v[82:85], v[146:149], v[58:61]
	v_mfma_f32_16x16x32_bf16 v[46:49], v[70:73], v[154:157], v[46:49]
	v_mfma_f32_16x16x32_bf16 v[42:45], v[82:85], v[154:157], v[42:45]
	v_mfma_f32_16x16x32_bf16 v[30:33], v[70:73], v[162:165], v[30:33]
	v_mfma_f32_16x16x32_bf16 v[26:29], v[82:85], v[162:165], v[26:29]
	v_mfma_f32_16x16x32_bf16 v[14:17], v[70:73], v[170:173], v[14:17]
	v_mfma_f32_16x16x32_bf16 v[10:13], v[82:85], v[170:173], v[10:13]
	v_mfma_f32_16x16x32_bf16 v[62:65], v[74:77], v[150:153], v[62:65]
	v_mfma_f32_16x16x32_bf16 v[58:61], v[86:89], v[150:153], v[58:61]
	v_mfma_f32_16x16x32_bf16 v[46:49], v[74:77], v[158:161], v[46:49]
	v_mfma_f32_16x16x32_bf16 v[42:45], v[86:89], v[158:161], v[42:45]
	v_mfma_f32_16x16x32_bf16 v[30:33], v[74:77], v[166:169], v[30:33]
	v_mfma_f32_16x16x32_bf16 v[26:29], v[86:89], v[166:169], v[26:29]
	v_mfma_f32_16x16x32_bf16 v[14:17], v[74:77], v[184:187], v[14:17]
	v_mfma_f32_16x16x32_bf16 v[10:13], v[86:89], v[184:187], v[10:13]
	s_barrier
	s_add_u32 s22, s36, 0x100000
	s_addc_u32 s23, s37, 0
	s_add_i32 s65, s66, s52
	s_mov_b32 m0, s65
	s_nop 0
	global_load_lds_dwordx4 v0, s[22:23]
	s_add_i32 m0, s65, 0x2000
	s_nop 0
	global_load_lds_dwordx4 v174, s[22:23]
	s_waitcnt vmcnt(6)
	s_barrier
; #define PG8_STAGE(bufoff, gbase, voff) do { _Pragma("unroll") for (int _i = 0; _i < 2; ++_i) \
;         __builtin_amdgcn_global_load_lds((const unsigned*)((const char*)(gbase) + (voff)[_i]), (LAS unsigned*)(lds + (bufoff) + ldsw + _i * 8192), 16, 0, 0); } while (0)
; #define PG8_LDA(dst, b, h) do { _Pragma("unroll") for (int m = 0; m < 4; ++m) _Pragma("unroll") for (int k = 0; k < 2; ++k) dst[m][k] = *(const LAS bf16x8*)(lds + PG8_SA(b, h) + aoff + m * 2048 + k * 1024); } while (0)
; #define PG8_LDB(dst, b, h) do { _Pragma("unroll") for (int n = 0; n < 2; ++n) _Pragma("unroll") for (int k = 0; k < 2; ++k) dst[n][k] = *(const LAS bf16x8*)(lds + PG8_SB(b, h) + boff + n * 2048 + k * 1024); } while (0)
; #define PG8_MMA(ai, bj, At, Bt) do { __builtin_amdgcn_s_setprio(1); _Pragma("unroll") for (int m = 0; m < 4; ++m) _Pragma("unroll") for (int n = 0; n < 2; ++n) _Pragma("unroll") for (int k = 0; k < 2; ++k) \
;         acc[ai][bj][m][n] = __builtin_amdgcn_mfma_f32_16x16x32_bf16(Bt[n][k], At[m][k], acc[ai][bj][m][n], 0, 0, 0); __builtin_amdgcn_s_setprio(0); } while (0)
; #define PG8_WAIT_V(n) asm volatile("s_waitcnt vmcnt(" #n ")" ::: "memory")
; #define PG8_WAIT_L(n) asm volatile("s_waitcnt lgkmcnt(" #n ")" ::: "memory")
; #define PG8_BAR __builtin_amdgcn_s_barrier()
; #define PG8_SCHED __builtin_amdgcn_sched_barrier(0)
; template <class Epi>
; __device__ __forceinline__ void gemm_phase(LAS unsigned char* lds, const Gemm g, const StaticOrder& S, const Epi& E) {
;     ...
;             PG8_WAIT_V(6); PG8_BAR; PG8_MMA(1, 1, At, B1); PG8_BAR;
;             PG8_LDB(B0, 1, 0); PG8_SCHED; PG8_LDA(At, 1, 0); PG8_STAGE(PG8_SA(0, 1), a2 + hstepA, voffA);
;             PG8_WAIT_L(8); PG8_BAR; PG8_WAIT_L(0); PG8_MMA(0, 0, At, B0); PG8_BAR; PG8_SCHED;
;             PG8_LDB(B1, 1, 1); PG8_STAGE(PG8_SB(1, 0), b3, voffB);
;             PG8_BAR; PG8_WAIT_L(0); PG8_MMA(0, 1, At, B1); PG8_BAR;
;             PG8_LDA(At, 1, 1); PG8_STAGE(PG8_SA(1, 0), a3, voffA);
;             PG8_BAR; PG8_WAIT_L(0); PG8_MMA(1, 0, At, B0); PG8_BAR; PG8_SCHED;
	v_mfma_f32_16x16x32_bf16 v[54:57], v[194:197], v[146:149], v[54:57]
	v_mfma_f32_16x16x32_bf16 v[50:53], v[202:205], v[146:149], v[50:53]
	v_mfma_f32_16x16x32_bf16 v[38:41], v[194:197], v[154:157], v[38:41]
	v_mfma_f32_16x16x32_bf16 v[34:37], v[202:205], v[154:157], v[34:37]
	v_mfma_f32_16x16x32_bf16 v[22:25], v[194:197], v[162:165], v[22:25]
	v_mfma_f32_16x16x32_bf16 v[18:21], v[202:205], v[162:165], v[18:21]
	v_mfma_f32_16x16x32_bf16 v[6:9], v[194:197], v[170:173], v[6:9]
	v_mfma_f32_16x16x32_bf16 v[2:5], v[202:205], v[170:173], v[2:5]
	v_mfma_f32_16x16x32_bf16 v[54:57], v[198:201], v[150:153], v[54:57]
	v_mfma_f32_16x16x32_bf16 v[50:53], v[212:215], v[150:153], v[50:53]
	v_mfma_f32_16x16x32_bf16 v[38:41], v[198:201], v[158:161], v[38:41]
	v_mfma_f32_16x16x32_bf16 v[34:37], v[212:215], v[158:161], v[34:37]
	v_mfma_f32_16x16x32_bf16 v[22:25], v[198:201], v[166:169], v[22:25]
	v_mfma_f32_16x16x32_bf16 v[18:21], v[212:215], v[166:169], v[18:21]
	v_mfma_f32_16x16x32_bf16 v[6:9], v[198:201], v[184:187], v[6:9]
	v_mfma_f32_16x16x32_bf16 v[2:5], v[212:215], v[184:187], v[2:5]
	s_add_i32 s65, 0, 0x18000
	s_barrier
	s_add_u32 s22, s24, 0x100000
	s_addc_u32 s23, s25, 0
	s_mov_b32 m0, s55
	s_nop 0
	global_load_lds_dwordx4 v188, s[22:23]
	s_mov_b32 m0, s56
	s_nop 0
	global_load_lds_dwordx4 v176, s[22:23]
	ds_read_b128 v[70:73], v250 offset:32768
	ds_read_b128 v[74:77], v250 offset:33792
	ds_read_b128 v[82:85], v250 offset:34816
	ds_read_b128 v[86:89], v250 offset:35840
	ds_read_b128 v[146:149], v211 offset:32768
	ds_read_b128 v[150:153], v211 offset:33792
	ds_read_b128 v[154:157], v211 offset:34816
	ds_read_b128 v[158:161], v211 offset:35840
	ds_read_b128 v[162:165], v211 offset:36864
	ds_read_b128 v[166:169], v211 offset:37888
	ds_read_b128 v[170:173], v211 offset:38912
	ds_read_b128 v[184:187], v211 offset:39936
	s_waitcnt lgkmcnt(8)
	s_barrier
	s_waitcnt lgkmcnt(0)
	v_mfma_f32_16x16x32_bf16 v[142:145], v[70:73], v[146:149], v[142:145]
	v_mfma_f32_16x16x32_bf16 v[138:141], v[82:85], v[146:149], v[138:141]
	v_mfma_f32_16x16x32_bf16 v[126:129], v[70:73], v[154:157], v[126:129]
	v_mfma_f32_16x16x32_bf16 v[122:125], v[82:85], v[154:157], v[122:125]
	v_mfma_f32_16x16x32_bf16 v[110:113], v[70:73], v[162:165], v[110:113]
	v_mfma_f32_16x16x32_bf16 v[106:109], v[82:85], v[162:165], v[106:109]
	v_mfma_f32_16x16x32_bf16 v[94:97], v[70:73], v[170:173], v[94:97]
	v_mfma_f32_16x16x32_bf16 v[90:93], v[82:85], v[170:173], v[90:93]
	v_mfma_f32_16x16x32_bf16 v[142:145], v[74:77], v[150:153], v[142:145]
	v_mfma_f32_16x16x32_bf16 v[138:141], v[86:89], v[150:153], v[138:141]
	v_mfma_f32_16x16x32_bf16 v[126:129], v[74:77], v[158:161], v[126:129]
	v_mfma_f32_16x16x32_bf16 v[122:125], v[86:89], v[158:161], v[122:125]
	v_mfma_f32_16x16x32_bf16 v[110:113], v[74:77], v[166:169], v[110:113]
	v_mfma_f32_16x16x32_bf16 v[106:109], v[86:89], v[166:169], v[106:109]
	v_mfma_f32_16x16x32_bf16 v[94:97], v[74:77], v[184:187], v[94:97]
	v_mfma_f32_16x16x32_bf16 v[90:93], v[86:89], v[184:187], v[90:93]
	s_barrier
	s_add_i32 s24, 0, 0x1c000
	s_add_i32 s22, s65, s52
	s_mov_b32 m0, s22
	s_nop 0
	global_load_lds_dwordx4 v0, s[100:101]
	s_add_i32 m0, s22, 0x2000
	s_nop 0
	global_load_lds_dwordx4 v174, s[100:101]
	ds_read_b128 v[194:197], v250 offset:49152
	ds_read_b128 v[198:201], v250 offset:50176
	ds_read_b128 v[202:205], v250 offset:51200
	ds_read_b128 v[212:215], v250 offset:52224
	s_barrier
	s_waitcnt lgkmcnt(0)
	v_mfma_f32_16x16x32_bf16 v[134:137], v[194:197], v[146:149], v[134:137]
	v_mfma_f32_16x16x32_bf16 v[130:133], v[202:205], v[146:149], v[130:133]
	v_mfma_f32_16x16x32_bf16 v[118:121], v[194:197], v[154:157], v[118:121]
	v_mfma_f32_16x16x32_bf16 v[114:117], v[202:205], v[154:157], v[114:117]
	v_mfma_f32_16x16x32_bf16 v[102:105], v[194:197], v[162:165], v[102:105]
	v_mfma_f32_16x16x32_bf16 v[98:101], v[202:205], v[162:165], v[98:101]
	v_mfma_f32_16x16x32_bf16 v[78:81], v[194:197], v[170:173], v[78:81]
	v_mfma_f32_16x16x32_bf16 v[66:69], v[202:205], v[170:173], v[66:69]
	v_mfma_f32_16x16x32_bf16 v[134:137], v[198:201], v[150:153], v[134:137]
	v_mfma_f32_16x16x32_bf16 v[130:133], v[212:215], v[150:153], v[130:133]
	v_mfma_f32_16x16x32_bf16 v[118:121], v[198:201], v[158:161], v[118:121]
	v_mfma_f32_16x16x32_bf16 v[114:117], v[212:215], v[158:161], v[114:117]
	v_mfma_f32_16x16x32_bf16 v[102:105], v[198:201], v[166:169], v[102:105]
	v_mfma_f32_16x16x32_bf16 v[98:101], v[212:215], v[166:169], v[98:101]
	v_mfma_f32_16x16x32_bf16 v[78:81], v[198:201], v[184:187], v[78:81]
	v_mfma_f32_16x16x32_bf16 v[66:69], v[212:215], v[184:187], v[66:69]
	s_mov_b32 m0, s58
	s_barrier
	global_load_lds_dwordx4 v188, vcc
	s_mov_b32 m0, s59
	s_nop 0
	global_load_lds_dwordx4 v176, vcc
	ds_read_b128 v[146:149], v211 offset:49152
	ds_read_b128 v[150:153], v211 offset:50176
	ds_read_b128 v[154:157], v211 offset:51200
	ds_read_b128 v[158:161], v211 offset:52224
	ds_read_b128 v[162:165], v211 offset:53248
	ds_read_b128 v[166:169], v211 offset:54272
	ds_read_b128 v[170:173], v211 offset:55296
	ds_read_b128 v[184:187], v211 offset:56320
	s_barrier
; __device__ __forceinline__ unsigned cvt_pk_bf16(float lo, float hi) { unsigned r; asm volatile("v_cvt_pk_bf16_f32 %0, %1, %2" : "=v"(r) : "v"(lo), "v"(hi)); return r; }
; #define PG8_WAIT_V(n) asm volatile("s_waitcnt vmcnt(" #n ")" ::: "memory")
; template <class Epi>
; __device__ __forceinline__ void gemm_phase(LAS unsigned char* lds, const Gemm g, const StaticOrder& S, const Epi& E) {
;     ...
;             PG8_BAR; PG8_WAIT_L(0); PG8_MMA(1, 0, At, B0); PG8_BAR; PG8_SCHED;
;             PG8_STAGE(PG8_SB(1, 1), b3 + hstepB, voffB);
;             PG8_WAIT_V(6); PG8_BAR; PG8_MMA(1, 1, At, B1); PG8_BAR;
;     __device__ __forceinline__ void operator()(const f32x4 (&acc)[2][2][4][2], const Unit& u, int wr, int wc, int fr, int fq, const Pre&) const {
;         const int row0 = u.pm * BM + wr * 64 + fr, col0 = u.pn * BM + wc * 32 + 4 * fq;
;         f32x4 gv[2][2];
; #pragma unroll
;         for (int bj = 0; bj < 2; ++bj)
; #pragma unroll
;             for (int n = 0; n < 2; ++n) gv[bj][n] = *(const f32x4*)(gnext + col0 + bj * HALF + n * 16);
;         f32x4 xb[2][2][2];
; #pragma unroll
;         for (int bj = 0; bj < 2; ++bj)
; #pragma unroll
;             for (int n = 0; n < 2; ++n) xb[0][bj][n] = *(const f32x4*)(Xin + (size_t)row0 * DM + col0 + bj * HALF + n * 16);
; #pragma unroll
;         for (int grp = 0; grp < 8; ++grp) { const int ai = grp >> 2, m = grp & 3, cur = grp & 1; const int r = row0 + ai * HALF + m * 16; float ss = 0.f;
;             if (grp < 7) { const int rn = row0 + ((grp + 1) >> 2) * HALF + ((grp + 1) & 3) * 16;
; #pragma unroll
;                 for (int bj = 0; bj < 2; ++bj)
; #pragma unroll
;                     for (int n = 0; n < 2; ++n) xb[cur ^ 1][bj][n] = *(const f32x4*)(Xin + (size_t)rn * DM + col0 + bj * HALF + n * 16); }
; #pragma unroll
;             for (int bj = 0; bj < 2; ++bj)
; #pragma unroll
;                 for (int n = 0; n < 2; ++n) { const int c = col0 + bj * HALF + n * 16;
;                     const f32x4 xv = xb[cur][bj][n] + acc[ai][bj][m][n]; *(f32x4*)(X + (size_t)r * DM + c) = xv;
;                     ss += (xv[0] * xv[0] + xv[1] * xv[1]) + (xv[2] * xv[2] + xv[3] * xv[3]);
;                     if (H) { const f32x4 hv = xv * gv[bj][n]; u32x2 w; w.x = cvt_pk_bf16(hv[0], hv[1]); w.y = cvt_pk_bf16(hv[2], hv[3]);
;                         *(u32x2*)(H + (size_t)r * DM + c) = w; } }
	s_waitcnt lgkmcnt(0)
	v_mfma_f32_16x16x32_bf16 v[62:65], v[70:73], v[146:149], v[62:65]
	v_mfma_f32_16x16x32_bf16 v[58:61], v[82:85], v[146:149], v[58:61]
	v_mfma_f32_16x16x32_bf16 v[46:49], v[70:73], v[154:157], v[46:49]
	v_mfma_f32_16x16x32_bf16 v[42:45], v[82:85], v[154:157], v[42:45]
	v_mfma_f32_16x16x32_bf16 v[30:33], v[70:73], v[162:165], v[30:33]
	v_mfma_f32_16x16x32_bf16 v[26:29], v[82:85], v[162:165], v[26:29]
	v_mfma_f32_16x16x32_bf16 v[14:17], v[70:73], v[170:173], v[14:17]
	v_mfma_f32_16x16x32_bf16 v[10:13], v[82:85], v[170:173], v[10:13]
	v_mfma_f32_16x16x32_bf16 v[62:65], v[74:77], v[150:153], v[62:65]
	v_mfma_f32_16x16x32_bf16 v[58:61], v[86:89], v[150:153], v[58:61]
	v_mfma_f32_16x16x32_bf16 v[46:49], v[74:77], v[158:161], v[46:49]
	v_mfma_f32_16x16x32_bf16 v[42:45], v[86:89], v[158:161], v[42:45]
	v_mfma_f32_16x16x32_bf16 v[30:33], v[74:77], v[166:169], v[30:33]
	v_mfma_f32_16x16x32_bf16 v[26:29], v[86:89], v[166:169], v[26:29]
	v_mfma_f32_16x16x32_bf16 v[14:17], v[74:77], v[184:187], v[14:17]
	v_mfma_f32_16x16x32_bf16 v[10:13], v[86:89], v[184:187], v[10:13]
	s_barrier
	s_add_u32 s22, s36, 0x100080
	s_addc_u32 s23, s37, 0
	s_add_i32 s24, s24, s52
	s_mov_b32 m0, s24
	s_nop 0
	global_load_lds_dwordx4 v0, s[22:23]
	s_add_i32 m0, s24, 0x2000
	s_nop 0
	global_load_lds_dwordx4 v174, s[22:23]
	s_waitcnt vmcnt(6)
	s_barrier
	v_mfma_f32_16x16x32_bf16 v[54:57], v[194:197], v[146:149], v[54:57]
	v_mfma_f32_16x16x32_bf16 v[50:53], v[202:205], v[146:149], v[50:53]
	v_mfma_f32_16x16x32_bf16 v[38:41], v[194:197], v[154:157], v[38:41]
	v_mfma_f32_16x16x32_bf16 v[34:37], v[202:205], v[154:157], v[34:37]
	v_mfma_f32_16x16x32_bf16 v[22:25], v[194:197], v[162:165], v[22:25]
	v_mfma_f32_16x16x32_bf16 v[18:21], v[202:205], v[162:165], v[18:21]
	v_mfma_f32_16x16x32_bf16 v[6:9], v[194:197], v[170:173], v[6:9]
	v_mfma_f32_16x16x32_bf16 v[2:5], v[202:205], v[170:173], v[2:5]
	v_mfma_f32_16x16x32_bf16 v[54:57], v[198:201], v[150:153], v[54:57]
	v_mfma_f32_16x16x32_bf16 v[50:53], v[212:215], v[150:153], v[50:53]
	v_mfma_f32_16x16x32_bf16 v[38:41], v[198:201], v[158:161], v[38:41]
	v_mfma_f32_16x16x32_bf16 v[34:37], v[212:215], v[158:161], v[34:37]
	v_mfma_f32_16x16x32_bf16 v[22:25], v[198:201], v[166:169], v[22:25]
	v_mfma_f32_16x16x32_bf16 v[18:21], v[212:215], v[166:169], v[18:21]
	v_mfma_f32_16x16x32_bf16 v[6:9], v[198:201], v[184:187], v[6:9]
	v_mfma_f32_16x16x32_bf16 v[2:5], v[212:215], v[184:187], v[2:5]
	s_add_i32 s64, s64, 2
	s_add_u32 s62, s62, 0x100
	s_addc_u32 s63, s63, 0
	s_cmp_gt_u32 s64, 61
	s_mov_b64 s[22:23], s[26:27]
	s_barrier
	s_cbranch_scc0 .LBB0_359
	v_lshl_add_u32 v198, s44, 8, v208
	v_lshl_or_b32 v194, s45, 8, v210
	v_ashrrev_i32_e32 v199, 31, v198
	v_ashrrev_i32_e32 v195, 31, v194
	v_lshlrev_b64 v[204:205], 13, v[198:199]
	v_or_b32_e32 v202, 16, v198
	v_lshlrev_b64 v[196:197], 2, v[194:195]
	v_lshl_add_u64 v[146:147], s[0:1], 0, v[204:205]
	v_ashrrev_i32_e32 v203, 31, v202
	v_lshl_add_u64 v[70:71], s[4:5], 0, v[196:197]
	v_lshl_add_u64 v[146:147], v[146:147], 0, v[196:197]
	v_lshlrev_b64 v[200:201], 13, v[202:203]
	global_load_dwordx4 v[86:89], v[70:71], off
	global_load_dwordx4 v[82:85], v[70:71], off offset:64
	global_load_dwordx4 v[74:77], v[70:71], off offset:512
	s_nop 0
	global_load_dwordx4 v[70:73], v[70:71], off offset:576
	s_nop 0
	global_load_dwordx4 v[184:187], v[146:147], off
	global_load_dwordx4 v[170:173], v[146:147], off offset:64
	global_load_dwordx4 v[166:169], v[146:147], off offset:512
	global_load_dwordx4 v[162:165], v[146:147], off offset:576
	v_lshl_add_u64 v[146:147], s[0:1], 0, v[200:201]
	v_lshl_add_u64 v[146:147], v[146:147], 0, v[196:197]
	global_load_dwordx4 v[158:161], v[146:147], off
	global_load_dwordx4 v[154:157], v[146:147], off offset:64
	global_load_dwordx4 v[150:153], v[146:147], off offset:512
	s_nop 0
	global_load_dwordx4 v[146:149], v[146:147], off offset:576
	v_cndmask_b32_e64 v206, 0, 1, s[10:11]
	v_lshlrev_b64 v[212:213], 11, v[198:199]
	v_lshl_add_u64 v[204:205], s[48:49], 0, v[204:205]
	v_cmp_ne_u32_e64 s[44:45], 1, v206
	s_andn2_b64 vcc, exec, s[10:11]
	v_lshl_add_u64 v[206:207], v[204:205], 0, v[196:197]
	v_lshl_add_u64 v[204:205], v[212:213], 1, s[50:51]
	s_waitcnt vmcnt(0)
	v_pk_add_f32 v[144:145], v[144:145], v[186:187]
	v_pk_add_f32 v[142:143], v[142:143], v[184:185]
	global_store_dwordx4 v[206:207], v[142:145], off
	s_cbranch_vccnz .LBB0_362
	v_pk_mul_f32 v[184:185], v[88:89], v[144:145]
	v_pk_mul_f32 v[186:187], v[86:87], v[142:143]
	s_nop 0
	v_cvt_pk_bf16_f32 v186, v186, v187
	v_cvt_pk_bf16_f32 v187, v184, v185
	v_lshl_add_u64 v[184:185], v[194:195], 1, v[204:205]
	global_store_dwordx2 v[184:185], v[186:187], off

; #define PG8_STAGE(bufoff, gbase, voff) do { _Pragma("unroll") for (int _i = 0; _i < 2; ++_i) \
;         __builtin_amdgcn_global_load_lds((const unsigned*)((const char*)(gbase) + (voff)[_i]), (LAS unsigned*)(lds + (bufoff) + ldsw + _i * 8192), 16, 0, 0); } while (0)
; #define PG8_LDA(dst, b, h) do { _Pragma("unroll") for (int m = 0; m < 4; ++m) _Pragma("unroll") for (int k = 0; k < 2; ++k) dst[m][k] = *(const LAS bf16x8*)(lds + PG8_SA(b, h) + aoff + m * 2048 + k * 1024); } while (0)
; #define PG8_LDB(dst, b, h) do { _Pragma("unroll") for (int n = 0; n < 2; ++n) _Pragma("unroll") for (int k = 0; k < 2; ++k) dst[n][k] = *(const LAS bf16x8*)(lds + PG8_SB(b, h) + boff + n * 2048 + k * 1024); } while (0)
; #define PG8_MMA(ai, bj, At, Bt) do { __builtin_amdgcn_s_setprio(1); _Pragma("unroll") for (int m = 0; m < 4; ++m) _Pragma("unroll") for (int n = 0; n < 2; ++n) _Pragma("unroll") for (int k = 0; k < 2; ++k) \
;         acc[ai][bj][m][n] = __builtin_amdgcn_mfma_f32_16x16x32_bf16(Bt[n][k], At[m][k], acc[ai][bj][m][n], 0, 0, 0); __builtin_amdgcn_s_setprio(0); } while (0)
; #define PG8_WAIT_V(n) asm volatile("s_waitcnt vmcnt(" #n ")" ::: "memory")
; #define PG8_WAIT_L(n) asm volatile("s_waitcnt lgkmcnt(" #n ")" ::: "memory")
; #define PG8_BAR __builtin_amdgcn_s_barrier()
; template <class Epi>
; __device__ __forceinline__ void gemm_phase(LAS unsigned char* lds, const Gemm g, const StaticOrder& S, const Epi& E) {
;     ...
;             const bool last = (t == nt - 2);
;             const char* a1 = cA + (size_t)(t + 1) * kstepA;
;             const char* a2 = last ? nA : cA + (size_t)(t + 2) * kstepA; const char* b2 = last ? nB : cB + (size_t)(t + 2) * kstep;
;             const char* a3 = a2 + kstepA; const char* b3 = b2 + kstep;
;             PG8_LDB(B0, 0, 0); PG8_SCHED; PG8_LDA(At, 0, 0); PG8_STAGE(PG8_SA(1, 1), a1 + hstepA, voffA);
;             PG8_WAIT_L(8); PG8_BAR; PG8_WAIT_L(0); PG8_MMA(0, 0, At, B0); PG8_BAR; PG8_SCHED;
;             PG8_LDB(B1, 0, 1); PG8_STAGE(PG8_SB(0, 0), b2, voffB);
;             PG8_BAR; PG8_WAIT_L(0); PG8_MMA(0, 1, At, B1); PG8_BAR;
;             PG8_LDA(At, 0, 1); PG8_STAGE(PG8_SA(0, 0), a2, voffA);
;             PG8_BAR; PG8_WAIT_L(0); PG8_MMA(1, 0, At, B0); PG8_BAR; PG8_SCHED;
;             PG8_STAGE(PG8_SB(0, 1), b2 + hstepB, voffB);
;             PG8_WAIT_V(6); PG8_BAR; PG8_MMA(1, 1, At, B1); PG8_BAR;
.LBB0_472:
	s_add_u32 s22, s4, s20
	s_addc_u32 s23, s5, s21
	s_add_u32 s22, s22, 0x100
	s_addc_u32 s23, s23, 0
	s_add_u32 s62, s17, s20
	s_addc_u32 s63, s58, s21
	s_add_i32 s64, 0, 0x10000
	ds_read_b128 v[148:151], v250
	ds_read_b128 v[152:155], v250 offset:1024
	ds_read_b128 v[156:159], v250 offset:2048
	ds_read_b128 v[160:163], v250 offset:3072
	s_cmpk_eq_i32 s20, 0x1f00
	s_cselect_b32 s25, s11, s23
	s_cselect_b32 s24, s59, s22
	s_cselect_b32 s23, s9, s63
	s_cselect_b32 s22, s60, s62
	v_lshl_add_u64 v[176:177], v[140:141], 0, s[20:21]
	s_add_i32 m0, s48, 0xc000
	s_nop 0
	global_load_lds_dwordx4 v[176:177], off
	ds_read_b128 v[164:167], v147
	ds_read_b128 v[168:171], v147 offset:1024
	ds_read_b128 v[172:175], v147 offset:2048
	ds_read_b128 v[184:187], v147 offset:3072
	ds_read_b128 v[188:191], v147 offset:4096
	ds_read_b128 v[192:195], v147 offset:5120
	ds_read_b128 v[196:199], v147 offset:6144
	ds_read_b128 v[200:203], v147 offset:7168
	v_lshl_add_u64 v[176:177], v[142:143], 0, s[20:21]
	s_add_i32 m0, s48, 0xe000
	s_nop 0
	global_load_lds_dwordx4 v[176:177], off
	s_waitcnt lgkmcnt(8)
	s_barrier
	s_waitcnt lgkmcnt(0)
	v_mfma_f32_16x16x32_bf16 v[126:129], v[148:151], v[164:167], v[126:129]
	v_mfma_f32_16x16x32_bf16 v[122:125], v[156:159], v[164:167], v[122:125]
	v_mfma_f32_16x16x32_bf16 v[110:113], v[148:151], v[172:175], v[110:113]
	v_mfma_f32_16x16x32_bf16 v[106:109], v[156:159], v[172:175], v[106:109]
	v_mfma_f32_16x16x32_bf16 v[94:97], v[148:151], v[188:191], v[94:97]
	v_mfma_f32_16x16x32_bf16 v[90:93], v[156:159], v[188:191], v[90:93]
	v_mfma_f32_16x16x32_bf16 v[78:81], v[148:151], v[196:199], v[78:81]
	v_mfma_f32_16x16x32_bf16 v[74:77], v[156:159], v[196:199], v[74:77]
	v_mfma_f32_16x16x32_bf16 v[126:129], v[152:155], v[168:171], v[126:129]
	v_mfma_f32_16x16x32_bf16 v[122:125], v[160:163], v[168:171], v[122:125]
	v_mfma_f32_16x16x32_bf16 v[110:113], v[152:155], v[184:187], v[110:113]
	v_mfma_f32_16x16x32_bf16 v[106:109], v[160:163], v[184:187], v[106:109]
	v_mfma_f32_16x16x32_bf16 v[94:97], v[152:155], v[192:195], v[94:97]
	v_mfma_f32_16x16x32_bf16 v[90:93], v[160:163], v[192:195], v[90:93]
	v_mfma_f32_16x16x32_bf16 v[78:81], v[152:155], v[200:203], v[78:81]
	v_mfma_f32_16x16x32_bf16 v[74:77], v[160:163], v[200:203], v[74:77]
	s_barrier
	s_add_i32 s65, 0, 0x14000
	s_add_i32 s62, s64, s39
	s_add_u32 s100, s22, s6
	s_addc_u32 s101, s23, s7
	s_mov_b32 m0, s62
	s_nop 0
	global_load_lds_dwordx4 v0, s[22:23]
	s_add_i32 m0, s62, 0x2000
	s_nop 0
	global_load_lds_dwordx4 v130, s[22:23]
	ds_read_b128 v[204:207], v250 offset:16384
	ds_read_b128 v[208:211], v250 offset:17408
	ds_read_b128 v[212:215], v250 offset:18432
	ds_read_b128 v[216:219], v250 offset:19456
	s_barrier
	s_waitcnt lgkmcnt(0)
	v_mfma_f32_16x16x32_bf16 v[118:121], v[204:207], v[164:167], v[118:121]
	v_mfma_f32_16x16x32_bf16 v[114:117], v[212:215], v[164:167], v[114:117]
	v_mfma_f32_16x16x32_bf16 v[102:105], v[204:207], v[172:175], v[102:105]
	v_mfma_f32_16x16x32_bf16 v[98:101], v[212:215], v[172:175], v[98:101]
	v_mfma_f32_16x16x32_bf16 v[86:89], v[204:207], v[188:191], v[86:89]
	v_mfma_f32_16x16x32_bf16 v[82:85], v[212:215], v[188:191], v[82:85]
	v_mfma_f32_16x16x32_bf16 v[70:73], v[204:207], v[196:199], v[70:73]
	v_mfma_f32_16x16x32_bf16 v[66:69], v[212:215], v[196:199], v[66:69]
	v_mfma_f32_16x16x32_bf16 v[118:121], v[208:211], v[168:171], v[118:121]
	v_mfma_f32_16x16x32_bf16 v[114:117], v[216:219], v[168:171], v[114:117]
	v_mfma_f32_16x16x32_bf16 v[102:105], v[208:211], v[184:187], v[102:105]
	v_mfma_f32_16x16x32_bf16 v[98:101], v[216:219], v[184:187], v[98:101]
	v_mfma_f32_16x16x32_bf16 v[86:89], v[208:211], v[192:195], v[86:89]
	v_mfma_f32_16x16x32_bf16 v[82:85], v[216:219], v[192:195], v[82:85]
	v_mfma_f32_16x16x32_bf16 v[70:73], v[208:211], v[200:203], v[70:73]
	v_mfma_f32_16x16x32_bf16 v[66:69], v[216:219], v[200:203], v[66:69]
	s_mov_b32 m0, s48
	s_add_u32 vcc_lo, s24, s6
	s_addc_u32 vcc_hi, s25, s7
	s_barrier
	global_load_lds_dwordx4 v134, s[24:25]
	s_mov_b32 m0, s49
	s_nop 0
	global_load_lds_dwordx4 v132, s[24:25]
	ds_read_b128 v[164:167], v147 offset:16384
	ds_read_b128 v[168:171], v147 offset:17408
	ds_read_b128 v[172:175], v147 offset:18432
	ds_read_b128 v[184:187], v147 offset:19456
	ds_read_b128 v[188:191], v147 offset:20480
	ds_read_b128 v[192:195], v147 offset:21504
	ds_read_b128 v[196:199], v147 offset:22528
	ds_read_b128 v[200:203], v147 offset:23552
	s_barrier
	s_waitcnt lgkmcnt(0)
	v_mfma_f32_16x16x32_bf16 v[62:65], v[148:151], v[164:167], v[62:65]
	v_mfma_f32_16x16x32_bf16 v[58:61], v[156:159], v[164:167], v[58:61]
	v_mfma_f32_16x16x32_bf16 v[46:49], v[148:151], v[172:175], v[46:49]
	v_mfma_f32_16x16x32_bf16 v[42:45], v[156:159], v[172:175], v[42:45]
	v_mfma_f32_16x16x32_bf16 v[30:33], v[148:151], v[188:191], v[30:33]
	v_mfma_f32_16x16x32_bf16 v[26:29], v[156:159], v[188:191], v[26:29]
	v_mfma_f32_16x16x32_bf16 v[18:21], v[148:151], v[196:199], v[18:21]
	v_mfma_f32_16x16x32_bf16 v[10:13], v[156:159], v[196:199], v[10:13]
	v_mfma_f32_16x16x32_bf16 v[62:65], v[152:155], v[168:171], v[62:65]
	v_mfma_f32_16x16x32_bf16 v[58:61], v[160:163], v[168:171], v[58:61]
	v_mfma_f32_16x16x32_bf16 v[46:49], v[152:155], v[184:187], v[46:49]
	v_mfma_f32_16x16x32_bf16 v[42:45], v[160:163], v[184:187], v[42:45]
	v_mfma_f32_16x16x32_bf16 v[30:33], v[152:155], v[192:195], v[30:33]
	v_mfma_f32_16x16x32_bf16 v[26:29], v[160:163], v[192:195], v[26:29]
	v_mfma_f32_16x16x32_bf16 v[18:21], v[152:155], v[200:203], v[18:21]
	v_mfma_f32_16x16x32_bf16 v[10:13], v[160:163], v[200:203], v[10:13]
	s_barrier
; #define PG8_STAGE(bufoff, gbase, voff) do { _Pragma("unroll") for (int _i = 0; _i < 2; ++_i) \
;         __builtin_amdgcn_global_load_lds((const unsigned*)((const char*)(gbase) + (voff)[_i]), (LAS unsigned*)(lds + (bufoff) + ldsw + _i * 8192), 16, 0, 0); } while (0)
; #define PG8_LDA(dst, b, h) do { _Pragma("unroll") for (int m = 0; m < 4; ++m) _Pragma("unroll") for (int k = 0; k < 2; ++k) dst[m][k] = *(const LAS bf16x8*)(lds + PG8_SA(b, h) + aoff + m * 2048 + k * 1024); } while (0)
; #define PG8_LDB(dst, b, h) do { _Pragma("unroll") for (int n = 0; n < 2; ++n) _Pragma("unroll") for (int k = 0; k < 2; ++k) dst[n][k] = *(const LAS bf16x8*)(lds + PG8_SB(b, h) + boff + n * 2048 + k * 1024); } while (0)
; #define PG8_MMA(ai, bj, At, Bt) do { __builtin_amdgcn_s_setprio(1); _Pragma("unroll") for (int m = 0; m < 4; ++m) _Pragma("unroll") for (int n = 0; n < 2; ++n) _Pragma("unroll") for (int k = 0; k < 2; ++k) \
;         acc[ai][bj][m][n] = __builtin_amdgcn_mfma_f32_16x16x32_bf16(Bt[n][k], At[m][k], acc[ai][bj][m][n], 0, 0, 0); __builtin_amdgcn_s_setprio(0); } while (0)
; #define PG8_WAIT_V(n) asm volatile("s_waitcnt vmcnt(" #n ")" ::: "memory")
; #define PG8_WAIT_L(n) asm volatile("s_waitcnt lgkmcnt(" #n ")" ::: "memory")
; #define PG8_BAR __builtin_amdgcn_s_barrier()
; #define PG8_SCHED __builtin_amdgcn_sched_barrier(0)
; template <class Epi>
; __device__ __forceinline__ void gemm_phase(LAS unsigned char* lds, const Gemm g, const StaticOrder& S, const Epi& E) {
;     ...
;             PG8_WAIT_V(6); PG8_BAR; PG8_MMA(1, 1, At, B1); PG8_BAR;
;             PG8_LDB(B0, 1, 0); PG8_SCHED; PG8_LDA(At, 1, 0); PG8_STAGE(PG8_SA(0, 1), a2 + hstepA, voffA);
;             PG8_WAIT_L(8); PG8_BAR; PG8_WAIT_L(0); PG8_MMA(0, 0, At, B0); PG8_BAR; PG8_SCHED;
;             PG8_LDB(B1, 1, 1); PG8_STAGE(PG8_SB(1, 0), b3, voffB);
;             PG8_BAR; PG8_WAIT_L(0); PG8_MMA(0, 1, At, B1); PG8_BAR;
;             PG8_LDA(At, 1, 1); PG8_STAGE(PG8_SA(1, 0), a3, voffA);
;             PG8_BAR; PG8_WAIT_L(0); PG8_MMA(1, 0, At, B0); PG8_BAR; PG8_SCHED;
	s_add_u32 s62, s22, 0x100000
	s_addc_u32 s63, s23, 0
	s_add_i32 s64, s65, s39
	s_mov_b32 m0, s64
	s_nop 0
	global_load_lds_dwordx4 v0, s[62:63]
	s_add_i32 m0, s64, 0x2000
	s_nop 0
	global_load_lds_dwordx4 v130, s[62:63]
	s_waitcnt vmcnt(6)
	s_barrier
	v_mfma_f32_16x16x32_bf16 v[54:57], v[204:207], v[164:167], v[54:57]
	v_mfma_f32_16x16x32_bf16 v[50:53], v[212:215], v[164:167], v[50:53]
	v_mfma_f32_16x16x32_bf16 v[38:41], v[204:207], v[172:175], v[38:41]
	v_mfma_f32_16x16x32_bf16 v[34:37], v[212:215], v[172:175], v[34:37]
	v_mfma_f32_16x16x32_bf16 v[22:25], v[204:207], v[188:191], v[22:25]
	v_mfma_f32_16x16x32_bf16 v[14:17], v[212:215], v[188:191], v[14:17]
	v_mfma_f32_16x16x32_bf16 v[6:9], v[204:207], v[196:199], v[6:9]
	v_mfma_f32_16x16x32_bf16 v[2:5], v[212:215], v[196:199], v[2:5]
	v_mfma_f32_16x16x32_bf16 v[54:57], v[208:211], v[168:171], v[54:57]
	v_mfma_f32_16x16x32_bf16 v[50:53], v[216:219], v[168:171], v[50:53]
	v_mfma_f32_16x16x32_bf16 v[38:41], v[208:211], v[184:187], v[38:41]
	v_mfma_f32_16x16x32_bf16 v[34:37], v[216:219], v[184:187], v[34:37]
	v_mfma_f32_16x16x32_bf16 v[22:25], v[208:211], v[192:195], v[22:25]
	v_mfma_f32_16x16x32_bf16 v[14:17], v[216:219], v[192:195], v[14:17]
	v_mfma_f32_16x16x32_bf16 v[6:9], v[208:211], v[200:203], v[6:9]
	v_mfma_f32_16x16x32_bf16 v[2:5], v[216:219], v[200:203], v[2:5]
	s_add_i32 s62, 0, 0x18000
	s_barrier
	s_add_u32 s24, s24, 0x100000
	s_addc_u32 s25, s25, 0
	s_mov_b32 m0, s50
	s_nop 0
	global_load_lds_dwordx4 v134, s[24:25]
	s_mov_b32 m0, s51
	s_nop 0
	global_load_lds_dwordx4 v132, s[24:25]
	ds_read_b128 v[148:151], v250 offset:32768
	ds_read_b128 v[152:155], v250 offset:33792
	ds_read_b128 v[156:159], v250 offset:34816
	ds_read_b128 v[160:163], v250 offset:35840
	ds_read_b128 v[164:167], v147 offset:32768
	ds_read_b128 v[168:171], v147 offset:33792
	ds_read_b128 v[172:175], v147 offset:34816
	ds_read_b128 v[184:187], v147 offset:35840
	ds_read_b128 v[188:191], v147 offset:36864
	ds_read_b128 v[192:195], v147 offset:37888
	ds_read_b128 v[196:199], v147 offset:38912
	ds_read_b128 v[200:203], v147 offset:39936
	s_waitcnt lgkmcnt(8)
	s_barrier
	s_waitcnt lgkmcnt(0)
	v_mfma_f32_16x16x32_bf16 v[126:129], v[148:151], v[164:167], v[126:129]
	v_mfma_f32_16x16x32_bf16 v[122:125], v[156:159], v[164:167], v[122:125]
	v_mfma_f32_16x16x32_bf16 v[110:113], v[148:151], v[172:175], v[110:113]
	v_mfma_f32_16x16x32_bf16 v[106:109], v[156:159], v[172:175], v[106:109]
	v_mfma_f32_16x16x32_bf16 v[94:97], v[148:151], v[188:191], v[94:97]
	v_mfma_f32_16x16x32_bf16 v[90:93], v[156:159], v[188:191], v[90:93]
	v_mfma_f32_16x16x32_bf16 v[78:81], v[148:151], v[196:199], v[78:81]
	v_mfma_f32_16x16x32_bf16 v[74:77], v[156:159], v[196:199], v[74:77]
	v_mfma_f32_16x16x32_bf16 v[126:129], v[152:155], v[168:171], v[126:129]
	v_mfma_f32_16x16x32_bf16 v[122:125], v[160:163], v[168:171], v[122:125]
	v_mfma_f32_16x16x32_bf16 v[110:113], v[152:155], v[184:187], v[110:113]
	v_mfma_f32_16x16x32_bf16 v[106:109], v[160:163], v[184:187], v[106:109]
	v_mfma_f32_16x16x32_bf16 v[94:97], v[152:155], v[192:195], v[94:97]
	v_mfma_f32_16x16x32_bf16 v[90:93], v[160:163], v[192:195], v[90:93]
	v_mfma_f32_16x16x32_bf16 v[78:81], v[152:155], v[200:203], v[78:81]
	v_mfma_f32_16x16x32_bf16 v[74:77], v[160:163], v[200:203], v[74:77]
	s_barrier
	s_add_i32 s24, 0, 0x1c000
	s_add_i32 s25, s62, s39
	s_mov_b32 m0, s25
	s_nop 0
	global_load_lds_dwordx4 v0, s[100:101]
	s_add_i32 m0, s25, 0x2000
	s_nop 0
	global_load_lds_dwordx4 v130, s[100:101]
	ds_read_b128 v[204:207], v250 offset:49152
	ds_read_b128 v[208:211], v250 offset:50176
	ds_read_b128 v[212:215], v250 offset:51200
	ds_read_b128 v[216:219], v250 offset:52224
	s_barrier
	s_waitcnt lgkmcnt(0)
	v_mfma_f32_16x16x32_bf16 v[118:121], v[204:207], v[164:167], v[118:121]
	v_mfma_f32_16x16x32_bf16 v[114:117], v[212:215], v[164:167], v[114:117]
	v_mfma_f32_16x16x32_bf16 v[102:105], v[204:207], v[172:175], v[102:105]
	v_mfma_f32_16x16x32_bf16 v[98:101], v[212:215], v[172:175], v[98:101]
	v_mfma_f32_16x16x32_bf16 v[86:89], v[204:207], v[188:191], v[86:89]
	v_mfma_f32_16x16x32_bf16 v[82:85], v[212:215], v[188:191], v[82:85]
	v_mfma_f32_16x16x32_bf16 v[70:73], v[204:207], v[196:199], v[70:73]
	v_mfma_f32_16x16x32_bf16 v[66:69], v[212:215], v[196:199], v[66:69]
	v_mfma_f32_16x16x32_bf16 v[118:121], v[208:211], v[168:171], v[118:121]
	v_mfma_f32_16x16x32_bf16 v[114:117], v[216:219], v[168:171], v[114:117]
	v_mfma_f32_16x16x32_bf16 v[102:105], v[208:211], v[184:187], v[102:105]
	v_mfma_f32_16x16x32_bf16 v[98:101], v[216:219], v[184:187], v[98:101]
	v_mfma_f32_16x16x32_bf16 v[86:89], v[208:211], v[192:195], v[86:89]
	v_mfma_f32_16x16x32_bf16 v[82:85], v[216:219], v[192:195], v[82:85]
	v_mfma_f32_16x16x32_bf16 v[70:73], v[208:211], v[200:203], v[70:73]
	v_mfma_f32_16x16x32_bf16 v[66:69], v[216:219], v[200:203], v[66:69]
	s_mov_b32 m0, s54
	s_barrier
	global_load_lds_dwordx4 v134, vcc
	s_mov_b32 m0, s55
	s_nop 0
	global_load_lds_dwordx4 v132, vcc
	ds_read_b128 v[164:167], v147 offset:49152
	ds_read_b128 v[168:171], v147 offset:50176
	ds_read_b128 v[172:175], v147 offset:51200
	ds_read_b128 v[184:187], v147 offset:52224
	ds_read_b128 v[188:191], v147 offset:53248
	ds_read_b128 v[192:195], v147 offset:54272
	ds_read_b128 v[196:199], v147 offset:55296
	ds_read_b128 v[200:203], v147 offset:56320
	s_barrier
; #define PG8_STAGE(bufoff, gbase, voff) do { _Pragma("unroll") for (int _i = 0; _i < 2; ++_i) \
;         __builtin_amdgcn_global_load_lds((const unsigned*)((const char*)(gbase) + (voff)[_i]), (LAS unsigned*)(lds + (bufoff) + ldsw + _i * 8192), 16, 0, 0); } while (0)
; #define PG8_MMA(ai, bj, At, Bt) do { __builtin_amdgcn_s_setprio(1); _Pragma("unroll") for (int m = 0; m < 4; ++m) _Pragma("unroll") for (int n = 0; n < 2; ++n) _Pragma("unroll") for (int k = 0; k < 2; ++k) \
;         acc[ai][bj][m][n] = __builtin_amdgcn_mfma_f32_16x16x32_bf16(Bt[n][k], At[m][k], acc[ai][bj][m][n], 0, 0, 0); __builtin_amdgcn_s_setprio(0); } while (0)
; #define PG8_WAIT_V(n) asm volatile("s_waitcnt vmcnt(" #n ")" ::: "memory")
; #define PG8_WAIT_L(n) asm volatile("s_waitcnt lgkmcnt(" #n ")" ::: "memory")
; #define PG8_BAR __builtin_amdgcn_s_barrier()
; #define PG8_SCHED __builtin_amdgcn_sched_barrier(0)
; template <class Epi>
; __device__ __forceinline__ void gemm_phase(LAS unsigned char* lds, const Gemm g, const StaticOrder& S, const Epi& E) {
;     ...
;             PG8_BAR; PG8_WAIT_L(0); PG8_MMA(1, 0, At, B0); PG8_BAR; PG8_SCHED;
;             PG8_STAGE(PG8_SB(1, 1), b3 + hstepB, voffB);
;             PG8_WAIT_V(6); PG8_BAR; PG8_MMA(1, 1, At, B1); PG8_BAR;
;         }
;         if constexpr (!Epi::AFTER_DRAIN) E(acc, cur, wr, wc, fr, fq, pre);
;         if (!has_next) break;
; #pragma unroll
;         for (int a = 0; a < 2; ++a)
; #pragma unroll
;             for (int b = 0; b < 2; ++b)
; #pragma unroll
;                 for (int m = 0; m < 4; ++m)
; #pragma unroll
;                     for (int n = 0; n < 2; ++n) acc[a][b][m][n] = (f32x4){0.f, 0.f, 0.f, 0.f};
;         cur = nxt; cA = nA; cB = nB; ++ui;
	s_waitcnt lgkmcnt(0)
	v_mfma_f32_16x16x32_bf16 v[62:65], v[148:151], v[164:167], v[62:65]
	v_mfma_f32_16x16x32_bf16 v[58:61], v[156:159], v[164:167], v[58:61]
	v_mfma_f32_16x16x32_bf16 v[46:49], v[148:151], v[172:175], v[46:49]
	v_mfma_f32_16x16x32_bf16 v[42:45], v[156:159], v[172:175], v[42:45]
	v_mfma_f32_16x16x32_bf16 v[30:33], v[148:151], v[188:191], v[30:33]
	v_mfma_f32_16x16x32_bf16 v[26:29], v[156:159], v[188:191], v[26:29]
	v_mfma_f32_16x16x32_bf16 v[18:21], v[148:151], v[196:199], v[18:21]
	v_mfma_f32_16x16x32_bf16 v[10:13], v[156:159], v[196:199], v[10:13]
	v_mfma_f32_16x16x32_bf16 v[62:65], v[152:155], v[168:171], v[62:65]
	v_mfma_f32_16x16x32_bf16 v[58:61], v[160:163], v[168:171], v[58:61]
	v_mfma_f32_16x16x32_bf16 v[46:49], v[152:155], v[184:187], v[46:49]
	v_mfma_f32_16x16x32_bf16 v[42:45], v[160:163], v[184:187], v[42:45]
	v_mfma_f32_16x16x32_bf16 v[30:33], v[152:155], v[192:195], v[30:33]
	v_mfma_f32_16x16x32_bf16 v[26:29], v[160:163], v[192:195], v[26:29]
	v_mfma_f32_16x16x32_bf16 v[18:21], v[152:155], v[200:203], v[18:21]
	v_mfma_f32_16x16x32_bf16 v[10:13], v[160:163], v[200:203], v[10:13]
	s_barrier
	s_add_u32 s22, s22, 0x100080
	s_addc_u32 s23, s23, 0
	s_add_i32 s24, s24, s39
	s_mov_b32 m0, s24
	s_nop 0
	global_load_lds_dwordx4 v0, s[22:23]
	s_add_i32 m0, s24, 0x2000
	s_nop 0
	global_load_lds_dwordx4 v130, s[22:23]
	s_waitcnt vmcnt(6)
	s_barrier
	v_mfma_f32_16x16x32_bf16 v[54:57], v[204:207], v[164:167], v[54:57]
	v_mfma_f32_16x16x32_bf16 v[50:53], v[212:215], v[164:167], v[50:53]
	v_mfma_f32_16x16x32_bf16 v[38:41], v[204:207], v[172:175], v[38:41]
	v_mfma_f32_16x16x32_bf16 v[34:37], v[212:215], v[172:175], v[34:37]
	v_mfma_f32_16x16x32_bf16 v[22:25], v[204:207], v[188:191], v[22:25]
	v_mfma_f32_16x16x32_bf16 v[14:17], v[212:215], v[188:191], v[14:17]
	v_mfma_f32_16x16x32_bf16 v[6:9], v[204:207], v[196:199], v[6:9]
	v_mfma_f32_16x16x32_bf16 v[2:5], v[212:215], v[196:199], v[2:5]
	v_mfma_f32_16x16x32_bf16 v[54:57], v[208:211], v[168:171], v[54:57]
	v_mfma_f32_16x16x32_bf16 v[50:53], v[216:219], v[168:171], v[50:53]
	v_mfma_f32_16x16x32_bf16 v[38:41], v[208:211], v[184:187], v[38:41]
	v_mfma_f32_16x16x32_bf16 v[34:37], v[216:219], v[184:187], v[34:37]
	v_mfma_f32_16x16x32_bf16 v[22:25], v[208:211], v[192:195], v[22:25]
	v_mfma_f32_16x16x32_bf16 v[14:17], v[216:219], v[192:195], v[14:17]
	v_mfma_f32_16x16x32_bf16 v[6:9], v[208:211], v[200:203], v[6:9]
	v_mfma_f32_16x16x32_bf16 v[2:5], v[216:219], v[200:203], v[2:5]
	s_add_i32 s61, s61, 2
	s_add_u32 s20, s20, 0x100
	s_addc_u32 s21, s21, 0
	s_cmp_gt_u32 s61, 61
	s_barrier
	s_cbranch_scc0 .LBB0_472
	s_add_u32 s20, s17, 0xffffff00
	s_addc_u32 s21, s58, -1
	s_andn2_b64 vcc, exec, s[42:43]
	s_cbranch_vccnz .LBB0_463
	v_mov_b32_e32 v2, 0
	s_mov_b32 s57, s8
	s_mov_b32 s26, s10
	s_mov_b64 s[4:5], s[18:19]
	s_mov_b32 s56, s16
	v_mov_b32_e32 v3, v2
	v_mov_b32_e32 v4, v2
	v_mov_b32_e32 v5, v2
	v_mov_b32_e32 v6, v2
	v_mov_b32_e32 v7, v2
	v_mov_b32_e32 v8, v2
	v_mov_b32_e32 v9, v2
	v_mov_b32_e32 v14, v2
	v_mov_b32_e32 v15, v2
	v_mov_b32_e32 v16, v2
	v_mov_b32_e32 v17, v2
	v_mov_b32_e32 v22, v2
	v_mov_b32_e32 v23, v2
	v_mov_b32_e32 v24, v2
	v_mov_b32_e32 v25, v2
	v_mov_b32_e32 v34, v2
	v_mov_b32_e32 v35, v2
	v_mov_b32_e32 v36, v2
	v_mov_b32_e32 v37, v2
	v_mov_b32_e32 v38, v2
	v_mov_b32_e32 v39, v2
	v_mov_b32_e32 v40, v2
	v_mov_b32_e32 v41, v2
	v_mov_b32_e32 v50, v2
	v_mov_b32_e32 v51, v2
	v_mov_b32_e32 v52, v2
	v_mov_b32_e32 v53, v2
	v_mov_b32_e32 v54, v2
	v_mov_b32_e32 v55, v2
	v_mov_b32_e32 v56, v2
	v_mov_b32_e32 v57, v2
	v_mov_b32_e32 v10, v2
	v_mov_b32_e32 v11, v2
	v_mov_b32_e32 v12, v2
	v_mov_b32_e32 v13, v2
	v_mov_b32_e32 v18, v2
	v_mov_b32_e32 v19, v2
	v_mov_b32_e32 v20, v2
	v_mov_b32_e32 v21, v2
	v_mov_b32_e32 v26, v2
	v_mov_b32_e32 v27, v2
	v_mov_b32_e32 v28, v2
	v_mov_b32_e32 v29, v2
	v_mov_b32_e32 v30, v2
	v_mov_b32_e32 v31, v2
	v_mov_b32_e32 v32, v2
	v_mov_b32_e32 v33, v2
	v_mov_b32_e32 v42, v2
	v_mov_b32_e32 v43, v2
	v_mov_b32_e32 v44, v2
	v_mov_b32_e32 v45, v2
	v_mov_b32_e32 v46, v2
	v_mov_b32_e32 v47, v2
	v_mov_b32_e32 v48, v2
	v_mov_b32_e32 v49, v2
	v_mov_b32_e32 v58, v2
	v_mov_b32_e32 v59, v2
	v_mov_b32_e32 v60, v2
	v_mov_b32_e32 v61, v2
	v_mov_b32_e32 v62, v2
	v_mov_b32_e32 v63, v2
	v_mov_b32_e32 v64, v2
	v_mov_b32_e32 v65, v2
	v_mov_b32_e32 v66, v2
	v_mov_b32_e32 v67, v2
	v_mov_b32_e32 v68, v2
	v_mov_b32_e32 v69, v2
	v_mov_b32_e32 v70, v2
	v_mov_b32_e32 v71, v2
	v_mov_b32_e32 v72, v2
	v_mov_b32_e32 v73, v2
	v_mov_b32_e32 v82, v2
	v_mov_b32_e32 v83, v2
	v_mov_b32_e32 v84, v2
	v_mov_b32_e32 v85, v2
	v_mov_b32_e32 v86, v2
	v_mov_b32_e32 v87, v2
	v_mov_b32_e32 v88, v2
	v_mov_b32_e32 v89, v2
	v_mov_b32_e32 v98, v2
	v_mov_b32_e32 v99, v2
	v_mov_b32_e32 v100, v2
	v_mov_b32_e32 v101, v2
	v_mov_b32_e32 v102, v2
	v_mov_b32_e32 v103, v2
	v_mov_b32_e32 v104, v2
	v_mov_b32_e32 v105, v2
	v_mov_b32_e32 v114, v2
	v_mov_b32_e32 v115, v2
	v_mov_b32_e32 v116, v2
	v_mov_b32_e32 v117, v2
	v_mov_b32_e32 v118, v2
	v_mov_b32_e32 v119, v2
	v_mov_b32_e32 v120, v2
	v_mov_b32_e32 v121, v2
	v_mov_b32_e32 v74, v2
	v_mov_b32_e32 v75, v2
	v_mov_b32_e32 v76, v2
	v_mov_b32_e32 v77, v2
	v_mov_b32_e32 v78, v2
	v_mov_b32_e32 v79, v2
	v_mov_b32_e32 v80, v2
	v_mov_b32_e32 v81, v2
	v_mov_b32_e32 v90, v2
	v_mov_b32_e32 v91, v2
	v_mov_b32_e32 v92, v2
	v_mov_b32_e32 v93, v2
	v_mov_b32_e32 v94, v2
	v_mov_b32_e32 v95, v2
	v_mov_b32_e32 v96, v2
	v_mov_b32_e32 v97, v2
	v_mov_b32_e32 v106, v2
	v_mov_b32_e32 v107, v2
	v_mov_b32_e32 v108, v2
	v_mov_b32_e32 v109, v2
	v_mov_b32_e32 v110, v2
	v_mov_b32_e32 v111, v2
	v_mov_b32_e32 v112, v2
	v_mov_b32_e32 v113, v2
	v_mov_b32_e32 v122, v2
	v_mov_b32_e32 v123, v2
	v_mov_b32_e32 v124, v2
	v_mov_b32_e32 v125, v2
	v_mov_b32_e32 v126, v2
	v_mov_b32_e32 v127, v2
	v_mov_b32_e32 v128, v2
	v_mov_b32_e32 v129, v2
	s_andn2_b64 vcc, exec, s[40:41]
	s_cbranch_vccnz .LBB0_464

; #define PG8_STAGE(bufoff, gbase, voff) do { _Pragma("unroll") for (int _i = 0; _i < 2; ++_i) \
;         __builtin_amdgcn_global_load_lds((const unsigned*)((const char*)(gbase) + (voff)[_i]), (LAS unsigned*)(lds + (bufoff) + ldsw + _i * 8192), 16, 0, 0); } while (0)
; #define PG8_LDA(dst, b, h) do { _Pragma("unroll") for (int m = 0; m < 4; ++m) _Pragma("unroll") for (int k = 0; k < 2; ++k) dst[m][k] = *(const LAS bf16x8*)(lds + PG8_SA(b, h) + aoff + m * 2048 + k * 1024); } while (0)
; #define PG8_LDB(dst, b, h) do { _Pragma("unroll") for (int n = 0; n < 2; ++n) _Pragma("unroll") for (int k = 0; k < 2; ++k) dst[n][k] = *(const LAS bf16x8*)(lds + PG8_SB(b, h) + boff + n * 2048 + k * 1024); } while (0)
; #define PG8_MMA(ai, bj, At, Bt) do { __builtin_amdgcn_s_setprio(1); _Pragma("unroll") for (int m = 0; m < 4; ++m) _Pragma("unroll") for (int n = 0; n < 2; ++n) _Pragma("unroll") for (int k = 0; k < 2; ++k) \
;         acc[ai][bj][m][n] = __builtin_amdgcn_mfma_f32_16x16x32_bf16(Bt[n][k], At[m][k], acc[ai][bj][m][n], 0, 0, 0); __builtin_amdgcn_s_setprio(0); } while (0)
; #define PG8_WAIT_V(n) asm volatile("s_waitcnt vmcnt(" #n ")" ::: "memory")
; #define PG8_WAIT_L(n) asm volatile("s_waitcnt lgkmcnt(" #n ")" ::: "memory")
; #define PG8_BAR __builtin_amdgcn_s_barrier()
; template <class Epi>
; __device__ __forceinline__ void gemm_phase(LAS unsigned char* lds, const Gemm g, const StaticOrder& S, const Epi& E) {
;     ...
;             const bool last = (t == nt - 2);
;             const char* a1 = cA + (size_t)(t + 1) * kstepA;
;             const char* a2 = last ? nA : cA + (size_t)(t + 2) * kstepA; const char* b2 = last ? nB : cB + (size_t)(t + 2) * kstep;
;             const char* a3 = a2 + kstepA; const char* b3 = b2 + kstep;
;             PG8_LDB(B0, 0, 0); PG8_SCHED; PG8_LDA(At, 0, 0); PG8_STAGE(PG8_SA(1, 1), a1 + hstepA, voffA);
;             PG8_WAIT_L(8); PG8_BAR; PG8_WAIT_L(0); PG8_MMA(0, 0, At, B0); PG8_BAR; PG8_SCHED;
;             PG8_LDB(B1, 0, 1); PG8_STAGE(PG8_SB(0, 0), b2, voffB);
;             PG8_BAR; PG8_WAIT_L(0); PG8_MMA(0, 1, At, B1); PG8_BAR;
;             PG8_LDA(At, 0, 1); PG8_STAGE(PG8_SA(0, 0), a2, voffA);
;             PG8_BAR; PG8_WAIT_L(0); PG8_MMA(1, 0, At, B0); PG8_BAR; PG8_SCHED;
;             PG8_STAGE(PG8_SB(0, 1), b2 + hstepB, voffB);
;             PG8_WAIT_V(6); PG8_BAR; PG8_MMA(1, 1, At, B1); PG8_BAR;
.LBB0_603:
	s_add_u32 s8, s0, 0x100
	s_addc_u32 s9, s1, 0
	s_add_i32 s60, 0, 0x10000
	s_cmp_eq_u32 s59, 12
	s_cselect_b32 s11, s35, s9
	s_cselect_b32 s10, s36, s8
	s_cselect_b32 s5, s37, s58
	s_cselect_b32 s4, s51, s53
	s_add_i32 m0, s20, 0xc000
	s_nop 0
	global_load_lds_dwordx4 v194, s[0:1]
	s_add_i32 m0, s20, 0xe000
	s_nop 0
	global_load_lds_dwordx4 v196, s[0:1]
	ds_read_b128 v[34:37], v250
	ds_read_b128 v[38:41], v250 offset:1024
	ds_read_b128 v[98:101], v250 offset:2048
	ds_read_b128 v[102:105], v250 offset:3072
	ds_read_b128 v[106:109], v231
	ds_read_b128 v[118:121], v231 offset:1024
	ds_read_b128 v[130:133], v231 offset:2048
	ds_read_b128 v[142:145], v231 offset:3072
	ds_read_b128 v[154:157], v231 offset:4096
	ds_read_b128 v[158:161], v231 offset:5120
	ds_read_b128 v[170:173], v231 offset:6144
	ds_read_b128 v[174:177], v231 offset:7168
	s_waitcnt lgkmcnt(8)
	s_barrier
	s_waitcnt lgkmcnt(0)
	v_mfma_f32_16x16x32_bf16 v[166:169], v[34:37], v[106:109], v[166:169]
	v_mfma_f32_16x16x32_bf16 v[162:165], v[98:101], v[106:109], v[162:165]
	v_mfma_f32_16x16x32_bf16 v[150:153], v[34:37], v[130:133], v[150:153]
	v_mfma_f32_16x16x32_bf16 v[146:149], v[98:101], v[130:133], v[146:149]
	v_mfma_f32_16x16x32_bf16 v[138:141], v[34:37], v[154:157], v[138:141]
	v_mfma_f32_16x16x32_bf16 v[134:137], v[98:101], v[154:157], v[134:137]
	v_mfma_f32_16x16x32_bf16 v[126:129], v[34:37], v[170:173], v[126:129]
	v_mfma_f32_16x16x32_bf16 v[122:125], v[98:101], v[170:173], v[122:125]
	v_mfma_f32_16x16x32_bf16 v[166:169], v[38:41], v[118:121], v[166:169]
	v_mfma_f32_16x16x32_bf16 v[162:165], v[102:105], v[118:121], v[162:165]
	v_mfma_f32_16x16x32_bf16 v[150:153], v[38:41], v[142:145], v[150:153]
	v_mfma_f32_16x16x32_bf16 v[146:149], v[102:105], v[142:145], v[146:149]
	v_mfma_f32_16x16x32_bf16 v[138:141], v[38:41], v[158:161], v[138:141]
	v_mfma_f32_16x16x32_bf16 v[134:137], v[102:105], v[158:161], v[134:137]
	v_mfma_f32_16x16x32_bf16 v[126:129], v[38:41], v[174:177], v[126:129]
	v_mfma_f32_16x16x32_bf16 v[122:125], v[102:105], v[174:177], v[122:125]
	s_barrier
	s_add_i32 s61, 0, 0x14000
	s_add_i32 s0, s60, s19
	s_add_u32 s100, s4, s6
	s_addc_u32 s101, s5, s7
	s_mov_b32 m0, s0
	s_nop 0
	global_load_lds_dwordx4 v0, s[4:5]
	s_add_i32 m0, s0, 0x2000
	s_nop 0
	global_load_lds_dwordx4 v188, s[4:5]
	ds_read_b128 v[198:201], v250 offset:16384
	ds_read_b128 v[202:205], v250 offset:17408
	ds_read_b128 v[206:209], v250 offset:18432
	ds_read_b128 v[210:213], v250 offset:19456
	s_barrier
	s_waitcnt lgkmcnt(0)
	v_mfma_f32_16x16x32_bf16 v[70:73], v[198:201], v[106:109], v[70:73]
	v_mfma_f32_16x16x32_bf16 v[66:69], v[206:209], v[106:109], v[66:69]
	v_mfma_f32_16x16x32_bf16 v[62:65], v[198:201], v[130:133], v[62:65]
	v_mfma_f32_16x16x32_bf16 v[58:61], v[206:209], v[130:133], v[58:61]
	v_mfma_f32_16x16x32_bf16 v[54:57], v[198:201], v[154:157], v[54:57]
	v_mfma_f32_16x16x32_bf16 v[50:53], v[206:209], v[154:157], v[50:53]
	v_mfma_f32_16x16x32_bf16 v[46:49], v[198:201], v[170:173], v[46:49]
	v_mfma_f32_16x16x32_bf16 v[42:45], v[206:209], v[170:173], v[42:45]
	v_mfma_f32_16x16x32_bf16 v[70:73], v[202:205], v[118:121], v[70:73]
	v_mfma_f32_16x16x32_bf16 v[66:69], v[210:213], v[118:121], v[66:69]
	v_mfma_f32_16x16x32_bf16 v[62:65], v[202:205], v[142:145], v[62:65]
	v_mfma_f32_16x16x32_bf16 v[58:61], v[210:213], v[142:145], v[58:61]
	v_mfma_f32_16x16x32_bf16 v[54:57], v[202:205], v[158:161], v[54:57]
	v_mfma_f32_16x16x32_bf16 v[50:53], v[210:213], v[158:161], v[50:53]
	v_mfma_f32_16x16x32_bf16 v[46:49], v[202:205], v[174:177], v[46:49]
	v_mfma_f32_16x16x32_bf16 v[42:45], v[210:213], v[174:177], v[42:45]
	s_mov_b32 m0, s20
	s_add_u32 vcc_lo, s10, s6
	s_addc_u32 vcc_hi, s11, s7
	s_barrier
	global_load_lds_dwordx4 v192, s[10:11]
	s_mov_b32 m0, s21
	s_nop 0
	global_load_lds_dwordx4 v190, s[10:11]
	ds_read_b128 v[106:109], v231 offset:16384
	ds_read_b128 v[118:121], v231 offset:17408
	ds_read_b128 v[130:133], v231 offset:18432
	ds_read_b128 v[142:145], v231 offset:19456
	ds_read_b128 v[154:157], v231 offset:20480
	ds_read_b128 v[158:161], v231 offset:21504
	ds_read_b128 v[170:173], v231 offset:22528
	ds_read_b128 v[174:177], v231 offset:23552
	s_barrier
	s_waitcnt lgkmcnt(0)
	v_mfma_f32_16x16x32_bf16 v[114:117], v[34:37], v[106:109], v[114:117]
	v_mfma_f32_16x16x32_bf16 v[110:113], v[98:101], v[106:109], v[110:113]
	v_mfma_f32_16x16x32_bf16 v[94:97], v[34:37], v[130:133], v[94:97]
	v_mfma_f32_16x16x32_bf16 v[90:93], v[98:101], v[130:133], v[90:93]
	v_mfma_f32_16x16x32_bf16 v[86:89], v[34:37], v[154:157], v[86:89]
	v_mfma_f32_16x16x32_bf16 v[82:85], v[98:101], v[154:157], v[82:85]
	v_mfma_f32_16x16x32_bf16 v[34:37], v[34:37], v[170:173], v[78:81]
	v_mfma_f32_16x16x32_bf16 v[114:117], v[38:41], v[118:121], v[114:117]
	v_mfma_f32_16x16x32_bf16 v[110:113], v[102:105], v[118:121], v[110:113]
	v_mfma_f32_16x16x32_bf16 v[94:97], v[38:41], v[142:145], v[94:97]
	v_mfma_f32_16x16x32_bf16 v[90:93], v[102:105], v[142:145], v[90:93]
	v_mfma_f32_16x16x32_bf16 v[86:89], v[38:41], v[158:161], v[86:89]
	v_mfma_f32_16x16x32_bf16 v[82:85], v[102:105], v[158:161], v[82:85]
	v_mfma_f32_16x16x32_bf16 v[34:37], v[38:41], v[174:177], v[34:37]
	v_mfma_f32_16x16x32_bf16 v[38:41], v[98:101], v[170:173], v[74:77]
	v_mfma_f32_16x16x32_bf16 v[38:41], v[102:105], v[174:177], v[38:41]
	s_barrier
	s_add_u32 s0, s4, 0x40000
	s_addc_u32 s1, s5, 0
	s_add_i32 s60, s61, s19
	s_mov_b32 m0, s60
	s_nop 0
	global_load_lds_dwordx4 v0, s[0:1]
	s_add_i32 m0, s60, 0x2000
	s_nop 0
	global_load_lds_dwordx4 v188, s[0:1]
	s_waitcnt vmcnt(6)
	s_barrier
; #define PG8_STAGE(bufoff, gbase, voff) do { _Pragma("unroll") for (int _i = 0; _i < 2; ++_i) \
;         __builtin_amdgcn_global_load_lds((const unsigned*)((const char*)(gbase) + (voff)[_i]), (LAS unsigned*)(lds + (bufoff) + ldsw + _i * 8192), 16, 0, 0); } while (0)
; #define PG8_LDA(dst, b, h) do { _Pragma("unroll") for (int m = 0; m < 4; ++m) _Pragma("unroll") for (int k = 0; k < 2; ++k) dst[m][k] = *(const LAS bf16x8*)(lds + PG8_SA(b, h) + aoff + m * 2048 + k * 1024); } while (0)
; #define PG8_LDB(dst, b, h) do { _Pragma("unroll") for (int n = 0; n < 2; ++n) _Pragma("unroll") for (int k = 0; k < 2; ++k) dst[n][k] = *(const LAS bf16x8*)(lds + PG8_SB(b, h) + boff + n * 2048 + k * 1024); } while (0)
; #define PG8_MMA(ai, bj, At, Bt) do { __builtin_amdgcn_s_setprio(1); _Pragma("unroll") for (int m = 0; m < 4; ++m) _Pragma("unroll") for (int n = 0; n < 2; ++n) _Pragma("unroll") for (int k = 0; k < 2; ++k) \
;         acc[ai][bj][m][n] = __builtin_amdgcn_mfma_f32_16x16x32_bf16(Bt[n][k], At[m][k], acc[ai][bj][m][n], 0, 0, 0); __builtin_amdgcn_s_setprio(0); } while (0)
; #define PG8_WAIT_V(n) asm volatile("s_waitcnt vmcnt(" #n ")" ::: "memory")
; #define PG8_WAIT_L(n) asm volatile("s_waitcnt lgkmcnt(" #n ")" ::: "memory")
; #define PG8_BAR __builtin_amdgcn_s_barrier()
; #define PG8_SCHED __builtin_amdgcn_sched_barrier(0)
; template <class Epi>
; __device__ __forceinline__ void gemm_phase(LAS unsigned char* lds, const Gemm g, const StaticOrder& S, const Epi& E) {
;     ...
;             PG8_WAIT_V(6); PG8_BAR; PG8_MMA(1, 1, At, B1); PG8_BAR;
;             PG8_LDB(B0, 1, 0); PG8_SCHED; PG8_LDA(At, 1, 0); PG8_STAGE(PG8_SA(0, 1), a2 + hstepA, voffA);
;             PG8_WAIT_L(8); PG8_BAR; PG8_WAIT_L(0); PG8_MMA(0, 0, At, B0); PG8_BAR; PG8_SCHED;
;             PG8_LDB(B1, 1, 1); PG8_STAGE(PG8_SB(1, 0), b3, voffB);
;             PG8_BAR; PG8_WAIT_L(0); PG8_MMA(0, 1, At, B1); PG8_BAR;
;             PG8_LDA(At, 1, 1); PG8_STAGE(PG8_SA(1, 0), a3, voffA);
;             PG8_BAR; PG8_WAIT_L(0); PG8_MMA(1, 0, At, B0); PG8_BAR; PG8_SCHED;
	v_mfma_f32_16x16x32_bf16 v[30:33], v[198:201], v[106:109], v[30:33]
	v_mfma_f32_16x16x32_bf16 v[26:29], v[206:209], v[106:109], v[26:29]
	v_mfma_f32_16x16x32_bf16 v[22:25], v[198:201], v[130:133], v[22:25]
	v_mfma_f32_16x16x32_bf16 v[18:21], v[206:209], v[130:133], v[18:21]
	v_mfma_f32_16x16x32_bf16 v[14:17], v[198:201], v[154:157], v[14:17]
	v_mfma_f32_16x16x32_bf16 v[10:13], v[206:209], v[154:157], v[10:13]
	v_mfma_f32_16x16x32_bf16 v[6:9], v[198:201], v[170:173], v[6:9]
	v_mfma_f32_16x16x32_bf16 v[2:5], v[206:209], v[170:173], v[2:5]
	v_mfma_f32_16x16x32_bf16 v[30:33], v[202:205], v[118:121], v[30:33]
	v_mfma_f32_16x16x32_bf16 v[26:29], v[210:213], v[118:121], v[26:29]
	v_mfma_f32_16x16x32_bf16 v[22:25], v[202:205], v[142:145], v[22:25]
	v_mfma_f32_16x16x32_bf16 v[18:21], v[210:213], v[142:145], v[18:21]
	v_mfma_f32_16x16x32_bf16 v[14:17], v[202:205], v[158:161], v[14:17]
	v_mfma_f32_16x16x32_bf16 v[10:13], v[210:213], v[158:161], v[10:13]
	v_mfma_f32_16x16x32_bf16 v[6:9], v[202:205], v[174:177], v[6:9]
	v_mfma_f32_16x16x32_bf16 v[2:5], v[210:213], v[174:177], v[2:5]
	s_add_i32 s60, 0, 0x18000
	s_barrier
	s_add_u32 s0, s10, 0x100000
	s_addc_u32 s1, s11, 0
	s_mov_b32 m0, s22
	s_nop 0
	global_load_lds_dwordx4 v192, s[0:1]
	s_mov_b32 m0, s23
	s_nop 0
	global_load_lds_dwordx4 v190, s[0:1]
	ds_read_b128 v[74:77], v250 offset:32768
	ds_read_b128 v[78:81], v250 offset:33792
	ds_read_b128 v[98:101], v250 offset:34816
	ds_read_b128 v[102:105], v250 offset:35840
	ds_read_b128 v[106:109], v231 offset:32768
	ds_read_b128 v[118:121], v231 offset:33792
	ds_read_b128 v[130:133], v231 offset:34816
	ds_read_b128 v[142:145], v231 offset:35840
	ds_read_b128 v[154:157], v231 offset:36864
	ds_read_b128 v[158:161], v231 offset:37888
	ds_read_b128 v[170:173], v231 offset:38912
	ds_read_b128 v[174:177], v231 offset:39936
	s_waitcnt lgkmcnt(8)
	s_barrier
	s_waitcnt lgkmcnt(0)
	v_mfma_f32_16x16x32_bf16 v[166:169], v[74:77], v[106:109], v[166:169]
	v_mfma_f32_16x16x32_bf16 v[162:165], v[98:101], v[106:109], v[162:165]
	v_mfma_f32_16x16x32_bf16 v[150:153], v[74:77], v[130:133], v[150:153]
	v_mfma_f32_16x16x32_bf16 v[146:149], v[98:101], v[130:133], v[146:149]
	v_mfma_f32_16x16x32_bf16 v[138:141], v[74:77], v[154:157], v[138:141]
	v_mfma_f32_16x16x32_bf16 v[134:137], v[98:101], v[154:157], v[134:137]
	v_mfma_f32_16x16x32_bf16 v[126:129], v[74:77], v[170:173], v[126:129]
	v_mfma_f32_16x16x32_bf16 v[122:125], v[98:101], v[170:173], v[122:125]
	v_mfma_f32_16x16x32_bf16 v[166:169], v[78:81], v[118:121], v[166:169]
	v_mfma_f32_16x16x32_bf16 v[162:165], v[102:105], v[118:121], v[162:165]
	v_mfma_f32_16x16x32_bf16 v[150:153], v[78:81], v[142:145], v[150:153]
	v_mfma_f32_16x16x32_bf16 v[146:149], v[102:105], v[142:145], v[146:149]
	v_mfma_f32_16x16x32_bf16 v[138:141], v[78:81], v[158:161], v[138:141]
	v_mfma_f32_16x16x32_bf16 v[134:137], v[102:105], v[158:161], v[134:137]
	v_mfma_f32_16x16x32_bf16 v[126:129], v[78:81], v[174:177], v[126:129]
	v_mfma_f32_16x16x32_bf16 v[122:125], v[102:105], v[174:177], v[122:125]
	s_barrier
	s_add_i32 s10, 0, 0x1c000
	s_add_i32 s0, s60, s19
	s_mov_b32 m0, s0
	s_nop 0
	global_load_lds_dwordx4 v0, s[100:101]
	s_add_i32 m0, s0, 0x2000
	s_nop 0
	global_load_lds_dwordx4 v188, s[100:101]
	ds_read_b128 v[198:201], v250 offset:49152
	ds_read_b128 v[202:205], v250 offset:50176
	ds_read_b128 v[206:209], v250 offset:51200
	ds_read_b128 v[210:213], v250 offset:52224
	s_barrier
	s_waitcnt lgkmcnt(0)
	v_mfma_f32_16x16x32_bf16 v[70:73], v[198:201], v[106:109], v[70:73]
	v_mfma_f32_16x16x32_bf16 v[66:69], v[206:209], v[106:109], v[66:69]
	v_mfma_f32_16x16x32_bf16 v[62:65], v[198:201], v[130:133], v[62:65]
	v_mfma_f32_16x16x32_bf16 v[58:61], v[206:209], v[130:133], v[58:61]
	v_mfma_f32_16x16x32_bf16 v[54:57], v[198:201], v[154:157], v[54:57]
	v_mfma_f32_16x16x32_bf16 v[50:53], v[206:209], v[154:157], v[50:53]
	v_mfma_f32_16x16x32_bf16 v[46:49], v[198:201], v[170:173], v[46:49]
	v_mfma_f32_16x16x32_bf16 v[42:45], v[206:209], v[170:173], v[42:45]
	v_mfma_f32_16x16x32_bf16 v[70:73], v[202:205], v[118:121], v[70:73]
	v_mfma_f32_16x16x32_bf16 v[66:69], v[210:213], v[118:121], v[66:69]
	v_mfma_f32_16x16x32_bf16 v[62:65], v[202:205], v[142:145], v[62:65]
	v_mfma_f32_16x16x32_bf16 v[58:61], v[210:213], v[142:145], v[58:61]
	v_mfma_f32_16x16x32_bf16 v[54:57], v[202:205], v[158:161], v[54:57]
	v_mfma_f32_16x16x32_bf16 v[50:53], v[210:213], v[158:161], v[50:53]
	v_mfma_f32_16x16x32_bf16 v[46:49], v[202:205], v[174:177], v[46:49]
	v_mfma_f32_16x16x32_bf16 v[42:45], v[210:213], v[174:177], v[42:45]
	s_mov_b32 m0, s24
	s_barrier
	global_load_lds_dwordx4 v192, vcc
	s_mov_b32 m0, s25
	s_nop 0
	global_load_lds_dwordx4 v190, vcc
	ds_read_b128 v[106:109], v231 offset:49152
	ds_read_b128 v[118:121], v231 offset:50176
	ds_read_b128 v[130:133], v231 offset:51200
	ds_read_b128 v[142:145], v231 offset:52224
	ds_read_b128 v[154:157], v231 offset:53248
	ds_read_b128 v[158:161], v231 offset:54272
	ds_read_b128 v[170:173], v231 offset:55296
	ds_read_b128 v[174:177], v231 offset:56320
	s_barrier
	s_waitcnt lgkmcnt(0)
	v_mfma_f32_16x16x32_bf16 v[114:117], v[74:77], v[106:109], v[114:117]
	v_mfma_f32_16x16x32_bf16 v[94:97], v[74:77], v[130:133], v[94:97]
	v_mfma_f32_16x16x32_bf16 v[86:89], v[74:77], v[154:157], v[86:89]
	v_mfma_f32_16x16x32_bf16 v[34:37], v[74:77], v[170:173], v[34:37]
	v_mfma_f32_16x16x32_bf16 v[114:117], v[78:81], v[118:121], v[114:117]
	v_mfma_f32_16x16x32_bf16 v[110:113], v[98:101], v[106:109], v[110:113]
	v_mfma_f32_16x16x32_bf16 v[94:97], v[78:81], v[142:145], v[94:97]
	v_mfma_f32_16x16x32_bf16 v[90:93], v[98:101], v[130:133], v[90:93]
	v_mfma_f32_16x16x32_bf16 v[86:89], v[78:81], v[158:161], v[86:89]
	v_mfma_f32_16x16x32_bf16 v[82:85], v[98:101], v[154:157], v[82:85]
	v_mfma_f32_16x16x32_bf16 v[78:81], v[78:81], v[174:177], v[34:37]
	v_mfma_f32_16x16x32_bf16 v[34:37], v[98:101], v[170:173], v[38:41]
	v_mfma_f32_16x16x32_bf16 v[110:113], v[102:105], v[118:121], v[110:113]
	v_mfma_f32_16x16x32_bf16 v[90:93], v[102:105], v[142:145], v[90:93]
	v_mfma_f32_16x16x32_bf16 v[82:85], v[102:105], v[158:161], v[82:85]
	v_mfma_f32_16x16x32_bf16 v[74:77], v[102:105], v[174:177], v[34:37]
	s_barrier
; __device__ __forceinline__ unsigned cvt_pk_bf16(float lo, float hi) { unsigned r; asm volatile("v_cvt_pk_bf16_f32 %0, %1, %2" : "=v"(r) : "v"(lo), "v"(hi)); return r; }
; __device__ __forceinline__ float bf_lo(unsigned w) { return __uint_as_float(w << 16); }
; __device__ __forceinline__ float bf_hi(unsigned w) { return __uint_as_float(w & 0xffff0000u); }
; __device__ __forceinline__ float silu_f(float z) { return z * fast_rcp(1.0f + __builtin_amdgcn_exp2f(z * -1.44269504f)); }
; template <class Epi>
; __device__ __forceinline__ void gemm_phase(LAS unsigned char* lds, const Gemm g, const StaticOrder& S, const Epi& E) {
;     ...
;             PG8_STAGE(PG8_SB(1, 1), b3 + hstepB, voffB);
;             PG8_WAIT_V(6); PG8_BAR; PG8_MMA(1, 1, At, B1); PG8_BAR;
;         }
;         if constexpr (!Epi::AFTER_DRAIN) E(acc, cur, wr, wc, fr, fq, pre);
;     __device__ __forceinline__ void operator()(const f32x4 (&acc)[2][2][4][2], const Unit& u, int wr, int wc, int fr, int fq, const Pre&) const {
;         const int row0 = u.pm * BM + wr * 64 + fr, col0 = u.pn * BM + wc * 32 + 8 * fq;
;         f32x4 sc[2][2];
; #pragma unroll
;         for (int bj = 0; bj < 2; ++bj) { sc[bj][0] = *(const f32x4*)(scale + col0 + bj * HALF); sc[bj][1] = *(const f32x4*)(scale + col0 + bj * HALF + 4); }
; #pragma unroll
;         for (int bj = 0; bj < 2; ++bj) { const int c = col0 + bj * HALF;
;             u32x4 zv[8];
; #pragma unroll
;             for (int g8 = 0; g8 < 8; ++g8) zv[g8] = *(const u32x4*)(Z + (size_t)(row0 + (g8 >> 2) * HALF + (g8 & 3) * 16) * DE2 + c);
; #pragma unroll
;             for (int ai = 0; ai < 2; ++ai)
; #pragma unroll
;                 for (int m = 0; m < 4; ++m) { const int r = row0 + ai * HALF + m * 16;
;                     const u32x4 zw = zv[ai * 4 + m];
;                     const f32x4 a0 = acc[ai][bj][m][0] * sc[bj][0], a1 = acc[ai][bj][m][1] * sc[bj][1];
;                     u32x4 w;
;                     w.x = cvt_pk_bf16(a0[0] * silu_f(bf_lo(zw.x)), a0[1] * silu_f(bf_hi(zw.x)));
;                     w.y = cvt_pk_bf16(a0[2] * silu_f(bf_lo(zw.y)), a0[3] * silu_f(bf_hi(zw.y)));
;                     w.z = cvt_pk_bf16(a1[0] * silu_f(bf_lo(zw.z)), a1[1] * silu_f(bf_hi(zw.z)));
;                     w.w = cvt_pk_bf16(a1[2] * silu_f(bf_lo(zw.w)), a1[3] * silu_f(bf_hi(zw.w)));
;                     *(u32x4*)(O + (size_t)r * DE + c) = w; } }
	s_add_u32 s0, s4, 0x40080
	s_addc_u32 s1, s5, 0
	s_add_i32 s4, s10, s19
	s_mov_b32 m0, s4
	s_nop 0
	global_load_lds_dwordx4 v0, s[0:1]
	s_add_i32 m0, s4, 0x2000
	s_nop 0
	global_load_lds_dwordx4 v188, s[0:1]
	s_waitcnt vmcnt(6)
	s_barrier
	v_mfma_f32_16x16x32_bf16 v[30:33], v[198:201], v[106:109], v[30:33]
	v_mfma_f32_16x16x32_bf16 v[26:29], v[206:209], v[106:109], v[26:29]
	v_mfma_f32_16x16x32_bf16 v[22:25], v[198:201], v[130:133], v[22:25]
	v_mfma_f32_16x16x32_bf16 v[18:21], v[206:209], v[130:133], v[18:21]
	v_mfma_f32_16x16x32_bf16 v[14:17], v[198:201], v[154:157], v[14:17]
	v_mfma_f32_16x16x32_bf16 v[10:13], v[206:209], v[154:157], v[10:13]
	v_mfma_f32_16x16x32_bf16 v[6:9], v[198:201], v[170:173], v[6:9]
	v_mfma_f32_16x16x32_bf16 v[2:5], v[206:209], v[170:173], v[2:5]
	v_mfma_f32_16x16x32_bf16 v[30:33], v[202:205], v[118:121], v[30:33]
	v_mfma_f32_16x16x32_bf16 v[26:29], v[210:213], v[118:121], v[26:29]
	v_mfma_f32_16x16x32_bf16 v[22:25], v[202:205], v[142:145], v[22:25]
	v_mfma_f32_16x16x32_bf16 v[18:21], v[210:213], v[142:145], v[18:21]
	v_mfma_f32_16x16x32_bf16 v[14:17], v[202:205], v[158:161], v[14:17]
	v_mfma_f32_16x16x32_bf16 v[10:13], v[210:213], v[158:161], v[10:13]
	v_mfma_f32_16x16x32_bf16 v[6:9], v[202:205], v[174:177], v[6:9]
	v_mfma_f32_16x16x32_bf16 v[2:5], v[210:213], v[174:177], v[2:5]
	s_add_i32 s59, s59, 2
	s_add_u32 s53, s53, 0x100
	s_addc_u32 s58, s58, 0
	s_cmp_gt_u32 s59, 13
	s_mov_b64 s[0:1], s[8:9]
	s_barrier
	s_cbranch_scc0 .LBB0_603
	v_lshl_or_b32 v200, s34, 8, v230
	v_ashrrev_i32_e32 v201, 31, v200
	v_lshl_add_u32 v226, s27, 8, v228
	v_lshlrev_b64 v[216:217], 1, v[200:201]
	v_ashrrev_i32_e32 v227, 31, v226
	v_lshl_add_u64 v[106:107], s[46:47], 0, v[216:217]
	v_lshlrev_b64 v[204:205], 14, v[226:227]
	v_lshl_add_u64 v[38:39], v[200:201], 2, s[48:49]
	v_lshl_add_u64 v[108:109], v[106:107], 0, v[204:205]
	global_load_dwordx4 v[98:101], v[38:39], off offset:16
	global_load_dwordx4 v[102:105], v[38:39], off
	global_load_dwordx4 v[34:37], v[38:39], off offset:528
	s_nop 0
	global_load_dwordx4 v[38:41], v[38:39], off offset:512
	v_or_b32_e32 v224, 16, v226
	global_load_dwordx4 v[174:177], v[108:109], off
	v_ashrrev_i32_e32 v225, 31, v224
	v_or_b32_e32 v222, 32, v226
	v_lshlrev_b64 v[198:199], 14, v[224:225]
	v_ashrrev_i32_e32 v223, 31, v222
	v_or_b32_e32 v220, 48, v226
	v_lshl_add_u64 v[108:109], v[106:107], 0, v[198:199]
	v_lshlrev_b64 v[202:203], 14, v[222:223]
	v_ashrrev_i32_e32 v221, 31, v220
	v_add_u32_e32 v218, 0x80, v226
	global_load_dwordx4 v[170:173], v[108:109], off
	v_lshl_add_u64 v[108:109], v[106:107], 0, v[202:203]
	v_lshlrev_b64 v[206:207], 14, v[220:221]
	v_ashrrev_i32_e32 v219, 31, v218
	global_load_dwordx4 v[158:161], v[108:109], off
	v_lshl_add_u64 v[108:109], v[106:107], 0, v[206:207]
	v_lshlrev_b64 v[208:209], 14, v[218:219]
	global_load_dwordx4 v[154:157], v[108:109], off
	v_lshl_add_u64 v[108:109], v[106:107], 0, v[208:209]
	global_load_dwordx4 v[142:145], v[108:109], off
	v_add_u32_e32 v108, 0x90, v226
	v_ashrrev_i32_e32 v109, 31, v108
	v_lshlrev_b64 v[210:211], 14, v[108:109]
	v_lshl_add_u64 v[108:109], v[106:107], 0, v[210:211]
	global_load_dwordx4 v[130:133], v[108:109], off
	v_add_u32_e32 v108, 0xa0, v226
	v_ashrrev_i32_e32 v109, 31, v108
	v_lshlrev_b64 v[212:213], 14, v[108:109]
	v_lshl_add_u64 v[108:109], v[106:107], 0, v[212:213]
	global_load_dwordx4 v[118:121], v[108:109], off
	v_add_u32_e32 v108, 0xb0, v226
	v_ashrrev_i32_e32 v109, 31, v108
	v_lshlrev_b64 v[214:215], 14, v[108:109]
	v_lshl_add_u64 v[106:107], v[106:107], 0, v[214:215]
	global_load_dwordx4 v[106:109], v[106:107], off
	s_mov_b64 s[0:1], 0x120000
	s_mov_b32 s27, s52
	s_mov_b32 s34, s50
	s_mov_b64 s[8:9], s[56:57]
	s_waitcnt vmcnt(0)
	v_pk_mul_f32 v[146:147], v[146:147], v[98:99]
	v_pk_mul_f32 v[184:185], v[166:167], v[102:103]
	v_pk_mul_f32 v[166:167], v[164:165], v[100:101]
	v_pk_mul_f32 v[164:165], v[162:163], v[98:99]
	v_pk_mul_f32 v[168:169], v[168:169], v[104:105]
	v_lshlrev_b32_e32 v162, 16, v174
	v_mul_f32_e32 v163, 0xbfb8aa3b, v162
	v_exp_f32_e32 v163, v163
	v_pk_mul_f32 v[150:151], v[150:151], v[102:103]
	v_pk_mul_f32 v[152:153], v[152:153], v[104:105]
	v_pk_mul_f32 v[148:149], v[148:149], v[100:101]
	v_add_f32_e32 v163, 1.0, v163
	v_rcp_f32_e32 v163, v163
	v_pk_mul_f32 v[138:139], v[138:139], v[102:103]
	v_pk_mul_f32 v[140:141], v[140:141], v[104:105]
	v_pk_mul_f32 v[134:135], v[134:135], v[98:99]
	v_mul_f32_e32 v162, v163, v162
	v_and_b32_e32 v163, 0xffff0000, v174
	v_mul_f32_e32 v174, 0xbfb8aa3b, v163
	v_exp_f32_e32 v174, v174
	v_mul_f32_e32 v162, v184, v162
	v_pk_mul_f32 v[136:137], v[136:137], v[100:101]
	v_pk_mul_f32 v[126:127], v[126:127], v[102:103]
	v_add_f32_e32 v174, 1.0, v174
	v_rcp_f32_e32 v174, v174
	v_pk_mul_f32 v[128:129], v[128:129], v[104:105]
	v_pk_mul_f32 v[122:123], v[122:123], v[98:99]
	v_pk_mul_f32 v[124:125], v[124:125], v[100:101]
	v_mul_f32_e32 v163, v174, v163
	v_mul_f32_e32 v163, v185, v163
	v_cvt_pk_bf16_f32 v162, v162, v163
	v_lshlrev_b32_e32 v163, 16, v175
	v_mul_f32_e32 v174, 0xbfb8aa3b, v163
	v_exp_f32_e32 v174, v174
	v_pk_mul_f32 v[114:115], v[114:115], v[102:103]
	v_pk_mul_f32 v[116:117], v[116:117], v[104:105]
	v_pk_mul_f32 v[110:111], v[110:111], v[98:99]
	v_add_f32_e32 v174, 1.0, v174
	v_rcp_f32_e32 v174, v174
	v_pk_mul_f32 v[112:113], v[112:113], v[100:101]
	v_pk_mul_f32 v[94:95], v[94:95], v[102:103]
	v_pk_mul_f32 v[96:97], v[96:97], v[104:105]
	v_mul_f32_e32 v163, v174, v163
	v_mul_f32_e32 v163, v168, v163
	v_and_b32_e32 v168, 0xffff0000, v175
	v_mul_f32_e32 v174, 0xbfb8aa3b, v168
	v_exp_f32_e32 v174, v174
	v_pk_mul_f32 v[90:91], v[90:91], v[98:99]
; __device__ __forceinline__ unsigned cvt_pk_bf16(float lo, float hi) { unsigned r; asm volatile("v_cvt_pk_bf16_f32 %0, %1, %2" : "=v"(r) : "v"(lo), "v"(hi)); return r; }
; __device__ __forceinline__ float bf_lo(unsigned w) { return __uint_as_float(w << 16); }
; __device__ __forceinline__ float bf_hi(unsigned w) { return __uint_as_float(w & 0xffff0000u); }
; __device__ __forceinline__ float silu_f(float z) { return z * fast_rcp(1.0f + __builtin_amdgcn_exp2f(z * -1.44269504f)); }
;     __device__ __forceinline__ void operator()(const f32x4 (&acc)[2][2][4][2], const Unit& u, int wr, int wc, int fr, int fq, const Pre&) const {
;     ...
;         for (int bj = 0; bj < 2; ++bj) { const int c = col0 + bj * HALF;
;             u32x4 zv[8];
; #pragma unroll
;             for (int g8 = 0; g8 < 8; ++g8) zv[g8] = *(const u32x4*)(Z + (size_t)(row0 + (g8 >> 2) * HALF + (g8 & 3) * 16) * DE2 + c);
; #pragma unroll
;             for (int ai = 0; ai < 2; ++ai)
; #pragma unroll
;                 for (int m = 0; m < 4; ++m) { const int r = row0 + ai * HALF + m * 16;
;                     const u32x4 zw = zv[ai * 4 + m];
;                     const f32x4 a0 = acc[ai][bj][m][0] * sc[bj][0], a1 = acc[ai][bj][m][1] * sc[bj][1];
;                     u32x4 w;
;                     w.x = cvt_pk_bf16(a0[0] * silu_f(bf_lo(zw.x)), a0[1] * silu_f(bf_hi(zw.x)));
;                     w.y = cvt_pk_bf16(a0[2] * silu_f(bf_lo(zw.y)), a0[3] * silu_f(bf_hi(zw.y)));
;                     w.z = cvt_pk_bf16(a1[0] * silu_f(bf_lo(zw.z)), a1[1] * silu_f(bf_hi(zw.z)));
;                     w.w = cvt_pk_bf16(a1[2] * silu_f(bf_lo(zw.w)), a1[3] * silu_f(bf_hi(zw.w)));
;                     *(u32x4*)(O + (size_t)r * DE + c) = w; } }
	v_pk_mul_f32 v[92:93], v[92:93], v[100:101]
	v_pk_mul_f32 v[86:87], v[86:87], v[102:103]
	v_add_f32_e32 v174, 1.0, v174
	v_rcp_f32_e32 v174, v174
	v_pk_mul_f32 v[88:89], v[88:89], v[104:105]
	v_pk_mul_f32 v[82:83], v[82:83], v[98:99]
	v_pk_mul_f32 v[84:85], v[84:85], v[100:101]
	v_mul_f32_e32 v168, v174, v168
	v_mul_f32_e32 v168, v169, v168
	v_cvt_pk_bf16_f32 v163, v163, v168
	v_lshlrev_b32_e32 v168, 16, v176
	v_mul_f32_e32 v169, 0xbfb8aa3b, v168
	v_exp_f32_e32 v169, v169
	v_pk_mul_f32 v[78:79], v[78:79], v[102:103]
	v_pk_mul_f32 v[80:81], v[80:81], v[104:105]
	v_pk_mul_f32 v[74:75], v[74:75], v[98:99]
	v_add_f32_e32 v169, 1.0, v169
	v_rcp_f32_e32 v169, v169
	v_pk_mul_f32 v[76:77], v[76:77], v[100:101]
	v_pk_mul_f32 v[70:71], v[70:71], v[38:39]
	v_pk_mul_f32 v[72:73], v[72:73], v[40:41]
	v_mul_f32_e32 v168, v169, v168
	v_mul_f32_e32 v164, v164, v168
	v_and_b32_e32 v168, 0xffff0000, v176
	v_mul_f32_e32 v169, 0xbfb8aa3b, v168
	v_exp_f32_e32 v169, v169
	v_pk_mul_f32 v[66:67], v[66:67], v[34:35]
	v_pk_mul_f32 v[68:69], v[68:69], v[36:37]
	v_pk_mul_f32 v[62:63], v[62:63], v[38:39]
	v_add_f32_e32 v169, 1.0, v169
	v_rcp_f32_e32 v169, v169
	v_pk_mul_f32 v[64:65], v[64:65], v[40:41]
	v_pk_mul_f32 v[58:59], v[58:59], v[34:35]
	v_pk_mul_f32 v[60:61], v[60:61], v[36:37]
	v_mul_f32_e32 v168, v169, v168
	v_mul_f32_e32 v165, v165, v168
	v_cvt_pk_bf16_f32 v164, v164, v165
	v_lshlrev_b32_e32 v165, 16, v177
	v_mul_f32_e32 v168, 0xbfb8aa3b, v165
	v_exp_f32_e32 v168, v168
	v_pk_mul_f32 v[54:55], v[54:55], v[38:39]
	v_pk_mul_f32 v[56:57], v[56:57], v[40:41]
	v_pk_mul_f32 v[50:51], v[50:51], v[34:35]
	v_add_f32_e32 v168, 1.0, v168
	v_rcp_f32_e32 v168, v168
	v_pk_mul_f32 v[52:53], v[52:53], v[36:37]
	v_pk_mul_f32 v[46:47], v[46:47], v[38:39]
	v_pk_mul_f32 v[48:49], v[48:49], v[40:41]
	v_mul_f32_e32 v165, v168, v165
	v_mul_f32_e32 v165, v166, v165
	v_and_b32_e32 v166, 0xffff0000, v177
	v_mul_f32_e32 v168, 0xbfb8aa3b, v166
	v_exp_f32_e32 v168, v168
	v_pk_mul_f32 v[42:43], v[42:43], v[34:35]
	v_pk_mul_f32 v[44:45], v[44:45], v[36:37]
	v_pk_mul_f32 v[30:31], v[30:31], v[38:39]
	v_add_f32_e32 v168, 1.0, v168
	v_rcp_f32_e32 v168, v168
	v_pk_mul_f32 v[32:33], v[32:33], v[40:41]
	v_pk_mul_f32 v[26:27], v[26:27], v[34:35]
	v_pk_mul_f32 v[28:29], v[28:29], v[36:37]
	v_mul_f32_e32 v166, v168, v166
	v_mul_f32_e32 v166, v167, v166
	v_cvt_pk_bf16_f32 v165, v165, v166
	v_lshlrev_b64 v[166:167], 13, v[226:227]
	v_lshl_add_u64 v[166:167], s[44:45], 0, v[166:167]
	v_lshl_add_u64 v[166:167], v[166:167], 0, v[216:217]
	global_store_dwordx4 v[166:167], v[162:165], off
	v_pk_mul_f32 v[22:23], v[22:23], v[38:39]
	v_pk_mul_f32 v[24:25], v[24:25], v[40:41]
	v_lshlrev_b32_e32 v162, 16, v170
	v_mul_f32_e32 v163, 0xbfb8aa3b, v162
	v_exp_f32_e32 v163, v163
	v_pk_mul_f32 v[18:19], v[18:19], v[34:35]
	v_pk_mul_f32 v[20:21], v[20:21], v[36:37]
	v_pk_mul_f32 v[14:15], v[14:15], v[38:39]
	v_add_f32_e32 v163, 1.0, v163
	v_rcp_f32_e32 v163, v163
	v_pk_mul_f32 v[16:17], v[16:17], v[40:41]
	v_pk_mul_f32 v[10:11], v[10:11], v[34:35]
	v_pk_mul_f32 v[12:13], v[12:13], v[36:37]
	v_mul_f32_e32 v162, v163, v162
	v_mul_f32_e32 v150, v150, v162
	v_and_b32_e32 v162, 0xffff0000, v170
	v_mul_f32_e32 v163, 0xbfb8aa3b, v162
	v_exp_f32_e32 v163, v163
	v_pk_mul_f32 v[6:7], v[6:7], v[38:39]
	v_pk_mul_f32 v[8:9], v[8:9], v[40:41]
	v_pk_mul_f32 v[2:3], v[2:3], v[34:35]
	v_add_f32_e32 v163, 1.0, v163
	v_rcp_f32_e32 v163, v163
	v_pk_mul_f32 v[4:5], v[4:5], v[36:37]
	v_mul_f32_e32 v162, v163, v162
	v_mul_f32_e32 v151, v151, v162
	v_cvt_pk_bf16_f32 v150, v150, v151
	v_lshlrev_b32_e32 v151, 16, v171
	v_mul_f32_e32 v162, 0xbfb8aa3b, v151
	v_exp_f32_e32 v162, v162
	s_nop 0
	v_add_f32_e32 v162, 1.0, v162
	v_rcp_f32_e32 v162, v162
	s_nop 0
	v_mul_f32_e32 v151, v162, v151
	v_mul_f32_e32 v151, v152, v151
	v_and_b32_e32 v152, 0xffff0000, v171
	v_mul_f32_e32 v162, 0xbfb8aa3b, v152
	v_exp_f32_e32 v162, v162
	s_nop 0
	v_add_f32_e32 v162, 1.0, v162
	v_rcp_f32_e32 v162, v162
	s_nop 0
	v_mul_f32_e32 v152, v162, v152
	v_mul_f32_e32 v152, v153, v152
	v_cvt_pk_bf16_f32 v151, v151, v152
	v_lshlrev_b32_e32 v152, 16, v172
	v_mul_f32_e32 v153, 0xbfb8aa3b, v152
	v_exp_f32_e32 v153, v153
	s_nop 0
	v_add_f32_e32 v153, 1.0, v153
	v_rcp_f32_e32 v153, v153
	s_nop 0
	v_mul_f32_e32 v152, v153, v152
	v_mul_f32_e32 v146, v146, v152
	v_and_b32_e32 v152, 0xffff0000, v172
	v_mul_f32_e32 v153, 0xbfb8aa3b, v152
	v_exp_f32_e32 v153, v153
	s_nop 0
	v_add_f32_e32 v153, 1.0, v153
	v_rcp_f32_e32 v153, v153
	s_nop 0
	v_mul_f32_e32 v152, v153, v152
	v_mul_f32_e32 v147, v147, v152
	v_cvt_pk_bf16_f32 v152, v146, v147
	v_lshlrev_b32_e32 v146, 16, v173
	v_mul_f32_e32 v147, 0xbfb8aa3b, v146
	v_exp_f32_e32 v147, v147
	s_nop 0
	v_add_f32_e32 v147, 1.0, v147
	v_rcp_f32_e32 v147, v147
	s_nop 0
	v_mul_f32_e32 v146, v147, v146
	v_and_b32_e32 v147, 0xffff0000, v173
	v_mul_f32_e32 v146, v148, v146
	v_mul_f32_e32 v148, 0xbfb8aa3b, v147
	v_exp_f32_e32 v148, v148
	s_nop 0
	v_add_f32_e32 v148, 1.0, v148
	v_rcp_f32_e32 v148, v148
	s_nop 0
	v_mul_f32_e32 v147, v148, v147
	v_lshlrev_b32_e32 v148, 16, v158
	v_mul_f32_e32 v147, v149, v147
	v_mul_f32_e32 v149, 0xbfb8aa3b, v148
	v_exp_f32_e32 v149, v149
	v_cvt_pk_bf16_f32 v153, v146, v147
	v_lshlrev_b64 v[146:147], 13, v[224:225]
	v_lshl_add_u64 v[146:147], s[44:45], 0, v[146:147]
	v_add_f32_e32 v149, 1.0, v149
	v_rcp_f32_e32 v149, v149
	v_lshl_add_u64 v[146:147], v[146:147], 0, v[216:217]
	global_store_dwordx4 v[146:147], v[150:153], off
	v_mul_f32_e32 v148, v149, v148
	v_mul_f32_e32 v138, v138, v148
	v_and_b32_e32 v148, 0xffff0000, v158
	v_mul_f32_e32 v149, 0xbfb8aa3b, v148
	v_exp_f32_e32 v149, v149
	s_nop 0
	v_add_f32_e32 v149, 1.0, v149
; __device__ __forceinline__ unsigned cvt_pk_bf16(float lo, float hi) { unsigned r; asm volatile("v_cvt_pk_bf16_f32 %0, %1, %2" : "=v"(r) : "v"(lo), "v"(hi)); return r; }
; __device__ __forceinline__ float bf_lo(unsigned w) { return __uint_as_float(w << 16); }
; __device__ __forceinline__ float bf_hi(unsigned w) { return __uint_as_float(w & 0xffff0000u); }
; __device__ __forceinline__ float silu_f(float z) { return z * fast_rcp(1.0f + __builtin_amdgcn_exp2f(z * -1.44269504f)); }
;     __device__ __forceinline__ void operator()(const f32x4 (&acc)[2][2][4][2], const Unit& u, int wr, int wc, int fr, int fq, const Pre&) const {
;     ...
;         for (int bj = 0; bj < 2; ++bj) { const int c = col0 + bj * HALF;
;             u32x4 zv[8];
; #pragma unroll
;             for (int g8 = 0; g8 < 8; ++g8) zv[g8] = *(const u32x4*)(Z + (size_t)(row0 + (g8 >> 2) * HALF + (g8 & 3) * 16) * DE2 + c);
; #pragma unroll
;             for (int ai = 0; ai < 2; ++ai)
; #pragma unroll
;                 for (int m = 0; m < 4; ++m) { const int r = row0 + ai * HALF + m * 16;
;                     const u32x4 zw = zv[ai * 4 + m];
;                     const f32x4 a0 = acc[ai][bj][m][0] * sc[bj][0], a1 = acc[ai][bj][m][1] * sc[bj][1];
;                     u32x4 w;
;                     w.x = cvt_pk_bf16(a0[0] * silu_f(bf_lo(zw.x)), a0[1] * silu_f(bf_hi(zw.x)));
;                     w.y = cvt_pk_bf16(a0[2] * silu_f(bf_lo(zw.y)), a0[3] * silu_f(bf_hi(zw.y)));
;                     w.z = cvt_pk_bf16(a1[0] * silu_f(bf_lo(zw.z)), a1[1] * silu_f(bf_hi(zw.z)));
;                     w.w = cvt_pk_bf16(a1[2] * silu_f(bf_lo(zw.w)), a1[3] * silu_f(bf_hi(zw.w)));
;                     *(u32x4*)(O + (size_t)r * DE + c) = w; } }
	v_rcp_f32_e32 v149, v149
	s_nop 0
	v_mul_f32_e32 v148, v149, v148
	v_mul_f32_e32 v139, v139, v148
	v_cvt_pk_bf16_f32 v138, v138, v139
	v_lshlrev_b32_e32 v139, 16, v159
	v_mul_f32_e32 v148, 0xbfb8aa3b, v139
	v_exp_f32_e32 v148, v148
	s_nop 0
	v_add_f32_e32 v148, 1.0, v148
	v_rcp_f32_e32 v148, v148
	s_nop 0
	v_mul_f32_e32 v139, v148, v139
	v_mul_f32_e32 v139, v140, v139
	v_and_b32_e32 v140, 0xffff0000, v159
	v_mul_f32_e32 v148, 0xbfb8aa3b, v140
	v_exp_f32_e32 v148, v148
	s_nop 0
	v_add_f32_e32 v148, 1.0, v148
	v_rcp_f32_e32 v148, v148
	s_nop 0
	v_mul_f32_e32 v140, v148, v140
	v_mul_f32_e32 v140, v141, v140
	v_cvt_pk_bf16_f32 v139, v139, v140
	v_lshlrev_b32_e32 v140, 16, v160
	v_mul_f32_e32 v141, 0xbfb8aa3b, v140
	v_exp_f32_e32 v141, v141
	s_nop 0
	v_add_f32_e32 v141, 1.0, v141
	v_rcp_f32_e32 v141, v141
	s_nop 0
	v_mul_f32_e32 v140, v141, v140
	v_mul_f32_e32 v134, v134, v140
	v_and_b32_e32 v140, 0xffff0000, v160
	v_mul_f32_e32 v141, 0xbfb8aa3b, v140
	v_exp_f32_e32 v141, v141
	s_nop 0
	v_add_f32_e32 v141, 1.0, v141
	v_rcp_f32_e32 v141, v141
	s_nop 0
	v_mul_f32_e32 v140, v141, v140
	v_mul_f32_e32 v135, v135, v140
	v_cvt_pk_bf16_f32 v140, v134, v135
	v_lshlrev_b32_e32 v134, 16, v161
	v_mul_f32_e32 v135, 0xbfb8aa3b, v134
	v_exp_f32_e32 v135, v135
	s_nop 0
	v_add_f32_e32 v135, 1.0, v135
	v_rcp_f32_e32 v135, v135
	s_nop 0
	v_mul_f32_e32 v134, v135, v134
	v_and_b32_e32 v135, 0xffff0000, v161
	v_mul_f32_e32 v134, v136, v134
	v_mul_f32_e32 v136, 0xbfb8aa3b, v135
	v_exp_f32_e32 v136, v136
	s_nop 0
	v_add_f32_e32 v136, 1.0, v136
	v_rcp_f32_e32 v136, v136
	s_nop 0
	v_mul_f32_e32 v135, v136, v135
	v_lshlrev_b32_e32 v136, 16, v154
	v_mul_f32_e32 v135, v137, v135
	v_mul_f32_e32 v137, 0xbfb8aa3b, v136
	v_exp_f32_e32 v137, v137
	v_cvt_pk_bf16_f32 v141, v134, v135
	v_lshlrev_b64 v[134:135], 13, v[222:223]
	v_lshl_add_u64 v[134:135], s[44:45], 0, v[134:135]
	v_add_f32_e32 v137, 1.0, v137
	v_rcp_f32_e32 v137, v137
	v_lshl_add_u64 v[134:135], v[134:135], 0, v[216:217]
	global_store_dwordx4 v[134:135], v[138:141], off
	v_mul_f32_e32 v136, v137, v136
	v_mul_f32_e32 v126, v126, v136
	v_and_b32_e32 v136, 0xffff0000, v154
	v_mul_f32_e32 v137, 0xbfb8aa3b, v136
	v_exp_f32_e32 v137, v137
	s_nop 0
	v_add_f32_e32 v137, 1.0, v137
	v_rcp_f32_e32 v137, v137
	s_nop 0
	v_mul_f32_e32 v136, v137, v136
	v_mul_f32_e32 v127, v127, v136
	v_cvt_pk_bf16_f32 v126, v126, v127
	v_lshlrev_b32_e32 v127, 16, v155
	v_mul_f32_e32 v136, 0xbfb8aa3b, v127
	v_exp_f32_e32 v136, v136
	s_nop 0
	v_add_f32_e32 v136, 1.0, v136
	v_rcp_f32_e32 v136, v136
	s_nop 0
	v_mul_f32_e32 v127, v136, v127
	v_mul_f32_e32 v127, v128, v127
	v_and_b32_e32 v128, 0xffff0000, v155
	v_mul_f32_e32 v136, 0xbfb8aa3b, v128
	v_exp_f32_e32 v136, v136
	s_nop 0
	v_add_f32_e32 v136, 1.0, v136
	v_rcp_f32_e32 v136, v136
	s_nop 0
	v_mul_f32_e32 v128, v136, v128
	v_mul_f32_e32 v128, v129, v128
	v_cvt_pk_bf16_f32 v127, v127, v128
	v_lshlrev_b32_e32 v128, 16, v156
	v_mul_f32_e32 v129, 0xbfb8aa3b, v128
	v_exp_f32_e32 v129, v129
	s_nop 0
	v_add_f32_e32 v129, 1.0, v129
	v_rcp_f32_e32 v129, v129
	s_nop 0
	v_mul_f32_e32 v128, v129, v128
	v_mul_f32_e32 v122, v122, v128
	v_and_b32_e32 v128, 0xffff0000, v156
	v_mul_f32_e32 v129, 0xbfb8aa3b, v128
	v_exp_f32_e32 v129, v129
	s_nop 0
	v_add_f32_e32 v129, 1.0, v129
	v_rcp_f32_e32 v129, v129
	s_nop 0
	v_mul_f32_e32 v128, v129, v128
	v_mul_f32_e32 v123, v123, v128
	v_cvt_pk_bf16_f32 v128, v122, v123
	v_lshlrev_b32_e32 v122, 16, v157
	v_mul_f32_e32 v123, 0xbfb8aa3b, v122
	v_exp_f32_e32 v123, v123
	s_nop 0
	v_add_f32_e32 v123, 1.0, v123
	v_rcp_f32_e32 v123, v123
	s_nop 0
	v_mul_f32_e32 v122, v123, v122
	v_and_b32_e32 v123, 0xffff0000, v157
	v_mul_f32_e32 v122, v124, v122
	v_mul_f32_e32 v124, 0xbfb8aa3b, v123
	v_exp_f32_e32 v124, v124
	s_nop 0
	v_add_f32_e32 v124, 1.0, v124
	v_rcp_f32_e32 v124, v124
	s_nop 0
	v_mul_f32_e32 v123, v124, v123
	v_lshlrev_b32_e32 v124, 16, v142
	v_mul_f32_e32 v123, v125, v123
	v_mul_f32_e32 v125, 0xbfb8aa3b, v124
	v_exp_f32_e32 v125, v125
	v_cvt_pk_bf16_f32 v129, v122, v123
	v_lshlrev_b64 v[122:123], 13, v[220:221]
	v_lshl_add_u64 v[122:123], s[44:45], 0, v[122:123]
	v_add_f32_e32 v125, 1.0, v125
	v_rcp_f32_e32 v125, v125
	v_lshl_add_u64 v[122:123], v[122:123], 0, v[216:217]
	global_store_dwordx4 v[122:123], v[126:129], off
	v_mul_f32_e32 v124, v125, v124
	v_mul_f32_e32 v114, v114, v124
	v_and_b32_e32 v124, 0xffff0000, v142
	v_mul_f32_e32 v125, 0xbfb8aa3b, v124
	v_exp_f32_e32 v125, v125
	s_nop 0
	v_add_f32_e32 v125, 1.0, v125
	v_rcp_f32_e32 v125, v125
	s_nop 0
	v_mul_f32_e32 v124, v125, v124
	v_mul_f32_e32 v115, v115, v124
	v_cvt_pk_bf16_f32 v114, v114, v115
	v_lshlrev_b32_e32 v115, 16, v143
	v_mul_f32_e32 v124, 0xbfb8aa3b, v115
	v_exp_f32_e32 v124, v124
	s_nop 0
	v_add_f32_e32 v124, 1.0, v124
	v_rcp_f32_e32 v124, v124
	s_nop 0
	v_mul_f32_e32 v115, v124, v115
	v_mul_f32_e32 v115, v116, v115
	v_and_b32_e32 v116, 0xffff0000, v143
	v_mul_f32_e32 v124, 0xbfb8aa3b, v116
	v_exp_f32_e32 v124, v124
	s_nop 0
	v_add_f32_e32 v124, 1.0, v124
	v_rcp_f32_e32 v124, v124
	s_nop 0
	v_mul_f32_e32 v116, v124, v116
	v_mul_f32_e32 v116, v117, v116
	v_cvt_pk_bf16_f32 v115, v115, v116
	v_lshlrev_b32_e32 v116, 16, v144
	v_mul_f32_e32 v117, 0xbfb8aa3b, v116
	v_exp_f32_e32 v117, v117
	s_nop 0
	v_add_f32_e32 v117, 1.0, v117
	v_rcp_f32_e32 v117, v117
	s_nop 0
	v_mul_f32_e32 v116, v117, v116
	v_mul_f32_e32 v110, v110, v116
	v_and_b32_e32 v116, 0xffff0000, v144
	v_mul_f32_e32 v117, 0xbfb8aa3b, v116
	v_exp_f32_e32 v117, v117
	s_nop 0
	v_add_f32_e32 v117, 1.0, v117
	v_rcp_f32_e32 v117, v117
	s_nop 0
	v_mul_f32_e32 v116, v117, v116
	v_mul_f32_e32 v111, v111, v116
	v_cvt_pk_bf16_f32 v116, v110, v111
; __device__ __forceinline__ unsigned cvt_pk_bf16(float lo, float hi) { unsigned r; asm volatile("v_cvt_pk_bf16_f32 %0, %1, %2" : "=v"(r) : "v"(lo), "v"(hi)); return r; }
; __device__ __forceinline__ float bf_lo(unsigned w) { return __uint_as_float(w << 16); }
; __device__ __forceinline__ float bf_hi(unsigned w) { return __uint_as_float(w & 0xffff0000u); }
; __device__ __forceinline__ float silu_f(float z) { return z * fast_rcp(1.0f + __builtin_amdgcn_exp2f(z * -1.44269504f)); }
;     __device__ __forceinline__ void operator()(const f32x4 (&acc)[2][2][4][2], const Unit& u, int wr, int wc, int fr, int fq, const Pre&) const {
;     ...
;         for (int bj = 0; bj < 2; ++bj) { const int c = col0 + bj * HALF;
;             u32x4 zv[8];
; #pragma unroll
;             for (int g8 = 0; g8 < 8; ++g8) zv[g8] = *(const u32x4*)(Z + (size_t)(row0 + (g8 >> 2) * HALF + (g8 & 3) * 16) * DE2 + c);
; #pragma unroll
;             for (int ai = 0; ai < 2; ++ai)
; #pragma unroll
;                 for (int m = 0; m < 4; ++m) { const int r = row0 + ai * HALF + m * 16;
;                     const u32x4 zw = zv[ai * 4 + m];
;                     const f32x4 a0 = acc[ai][bj][m][0] * sc[bj][0], a1 = acc[ai][bj][m][1] * sc[bj][1];
;                     u32x4 w;
;                     w.x = cvt_pk_bf16(a0[0] * silu_f(bf_lo(zw.x)), a0[1] * silu_f(bf_hi(zw.x)));
;                     w.y = cvt_pk_bf16(a0[2] * silu_f(bf_lo(zw.y)), a0[3] * silu_f(bf_hi(zw.y)));
;                     w.z = cvt_pk_bf16(a1[0] * silu_f(bf_lo(zw.z)), a1[1] * silu_f(bf_hi(zw.z)));
;                     w.w = cvt_pk_bf16(a1[2] * silu_f(bf_lo(zw.w)), a1[3] * silu_f(bf_hi(zw.w)));
;                     *(u32x4*)(O + (size_t)r * DE + c) = w; } }
	v_lshlrev_b32_e32 v110, 16, v145
	v_mul_f32_e32 v111, 0xbfb8aa3b, v110
	v_exp_f32_e32 v111, v111
	s_nop 0
	v_add_f32_e32 v111, 1.0, v111
	v_rcp_f32_e32 v111, v111
	s_nop 0
	v_mul_f32_e32 v110, v111, v110
	v_and_b32_e32 v111, 0xffff0000, v145
	v_mul_f32_e32 v110, v112, v110
	v_mul_f32_e32 v112, 0xbfb8aa3b, v111
	v_exp_f32_e32 v112, v112
	s_nop 0
	v_add_f32_e32 v112, 1.0, v112
	v_rcp_f32_e32 v112, v112
	s_nop 0
	v_mul_f32_e32 v111, v112, v111
	v_mul_f32_e32 v111, v113, v111
	v_cvt_pk_bf16_f32 v117, v110, v111
	v_lshlrev_b64 v[110:111], 13, v[218:219]
	v_lshl_add_u64 v[110:111], s[44:45], 0, v[110:111]
	v_lshl_add_u64 v[112:113], v[110:111], 0, v[216:217]
	v_lshlrev_b32_e32 v110, 16, v130
	v_mul_f32_e32 v111, 0xbfb8aa3b, v110
	v_exp_f32_e32 v111, v111
	global_store_dwordx4 v[112:113], v[114:117], off
	v_add_f32_e32 v111, 1.0, v111
	v_rcp_f32_e32 v111, v111
	s_nop 0
	v_mul_f32_e32 v110, v111, v110
	v_mul_f32_e32 v94, v94, v110
	v_and_b32_e32 v110, 0xffff0000, v130
	v_mul_f32_e32 v111, 0xbfb8aa3b, v110
	v_exp_f32_e32 v111, v111
	s_nop 0
	v_add_f32_e32 v111, 1.0, v111
	v_rcp_f32_e32 v111, v111
	s_nop 0
	v_mul_f32_e32 v110, v111, v110
	v_mul_f32_e32 v95, v95, v110
	v_cvt_pk_bf16_f32 v94, v94, v95
	v_lshlrev_b32_e32 v95, 16, v131
	v_mul_f32_e32 v110, 0xbfb8aa3b, v95
	v_exp_f32_e32 v110, v110
	s_nop 0
	v_add_f32_e32 v110, 1.0, v110
	v_rcp_f32_e32 v110, v110
	s_nop 0
	v_mul_f32_e32 v95, v110, v95
	v_mul_f32_e32 v95, v96, v95
	v_and_b32_e32 v96, 0xffff0000, v131
	v_mul_f32_e32 v110, 0xbfb8aa3b, v96
	v_exp_f32_e32 v110, v110
	s_nop 0
	v_add_f32_e32 v110, 1.0, v110
	v_rcp_f32_e32 v110, v110
	s_nop 0
	v_mul_f32_e32 v96, v110, v96
	v_mul_f32_e32 v96, v97, v96
	v_cvt_pk_bf16_f32 v95, v95, v96
	v_lshlrev_b32_e32 v96, 16, v132
	v_mul_f32_e32 v97, 0xbfb8aa3b, v96
	v_exp_f32_e32 v97, v97
	v_lshl_add_u64 v[110:111], v[166:167], 0, s[0:1]
	s_mov_b64 s[0:1], 0x140000
	v_lshl_add_u64 v[114:115], v[166:167], 0, s[0:1]
	v_add_f32_e32 v97, 1.0, v97
	v_rcp_f32_e32 v97, v97
	s_mov_b64 s[0:1], 0x160000
	v_mul_f32_e32 v96, v97, v96
	v_mul_f32_e32 v90, v90, v96
	v_and_b32_e32 v96, 0xffff0000, v132
	v_mul_f32_e32 v97, 0xbfb8aa3b, v96
	v_exp_f32_e32 v97, v97
	s_nop 0
	v_add_f32_e32 v97, 1.0, v97
	v_rcp_f32_e32 v97, v97
	s_nop 0
	v_mul_f32_e32 v96, v97, v96
	v_mul_f32_e32 v91, v91, v96
	v_cvt_pk_bf16_f32 v96, v90, v91
	v_lshlrev_b32_e32 v90, 16, v133
	v_mul_f32_e32 v91, 0xbfb8aa3b, v90
	v_exp_f32_e32 v91, v91
	s_nop 0
	v_add_f32_e32 v91, 1.0, v91
	v_rcp_f32_e32 v91, v91
	s_nop 0
	v_mul_f32_e32 v90, v91, v90
	v_and_b32_e32 v91, 0xffff0000, v133
	v_mul_f32_e32 v90, v92, v90
	v_mul_f32_e32 v92, 0xbfb8aa3b, v91
	v_exp_f32_e32 v92, v92
	s_nop 0
	v_add_f32_e32 v92, 1.0, v92
	v_rcp_f32_e32 v92, v92
	s_nop 0
	v_mul_f32_e32 v91, v92, v91
	v_mul_f32_e32 v91, v93, v91
	v_cvt_pk_bf16_f32 v97, v90, v91
	v_add_co_u32_e32 v90, vcc, s41, v166
	s_nop 1
	v_addc_co_u32_e32 v91, vcc, 0, v167, vcc
	global_store_dwordx4 v[90:91], v[94:97], off
	v_lshlrev_b32_e32 v90, 16, v118
	v_mul_f32_e32 v91, 0xbfb8aa3b, v90
	v_exp_f32_e32 v91, v91
	s_nop 0
	v_add_f32_e32 v91, 1.0, v91
	v_rcp_f32_e32 v91, v91
	s_nop 0
	v_mul_f32_e32 v90, v91, v90
	v_mul_f32_e32 v86, v86, v90
	v_and_b32_e32 v90, 0xffff0000, v118
	v_mul_f32_e32 v91, 0xbfb8aa3b, v90
	v_exp_f32_e32 v91, v91
	s_nop 0
	v_add_f32_e32 v91, 1.0, v91
	v_rcp_f32_e32 v91, v91
	s_nop 0
	v_mul_f32_e32 v90, v91, v90
	v_mul_f32_e32 v87, v87, v90
	v_cvt_pk_bf16_f32 v86, v86, v87
	v_lshlrev_b32_e32 v87, 16, v119
	v_mul_f32_e32 v90, 0xbfb8aa3b, v87
	v_exp_f32_e32 v90, v90
	s_nop 0
	v_add_f32_e32 v90, 1.0, v90
	v_rcp_f32_e32 v90, v90
	s_nop 0
	v_mul_f32_e32 v87, v90, v87
	v_mul_f32_e32 v87, v88, v87
	v_and_b32_e32 v88, 0xffff0000, v119
	v_mul_f32_e32 v90, 0xbfb8aa3b, v88
	v_exp_f32_e32 v90, v90
	s_nop 0
	v_add_f32_e32 v90, 1.0, v90
	v_rcp_f32_e32 v90, v90
	s_nop 0
	v_mul_f32_e32 v88, v90, v88
	v_mul_f32_e32 v88, v89, v88
	v_cvt_pk_bf16_f32 v87, v87, v88
	v_lshlrev_b32_e32 v88, 16, v120
	v_mul_f32_e32 v89, 0xbfb8aa3b, v88
	v_exp_f32_e32 v89, v89
	s_nop 0
	v_add_f32_e32 v89, 1.0, v89
	v_rcp_f32_e32 v89, v89
	s_nop 0
	v_mul_f32_e32 v88, v89, v88
	v_mul_f32_e32 v82, v82, v88
	v_and_b32_e32 v88, 0xffff0000, v120
	v_mul_f32_e32 v89, 0xbfb8aa3b, v88
	v_exp_f32_e32 v89, v89
	s_nop 0
	v_add_f32_e32 v89, 1.0, v89
	v_rcp_f32_e32 v89, v89
	s_nop 0
	v_mul_f32_e32 v88, v89, v88
	v_mul_f32_e32 v83, v83, v88
	v_cvt_pk_bf16_f32 v88, v82, v83
	v_lshlrev_b32_e32 v82, 16, v121
	v_mul_f32_e32 v83, 0xbfb8aa3b, v82
	v_exp_f32_e32 v83, v83
	s_nop 0
	v_add_f32_e32 v83, 1.0, v83
	v_rcp_f32_e32 v83, v83
	s_nop 0
	v_mul_f32_e32 v82, v83, v82
	v_and_b32_e32 v83, 0xffff0000, v121
	v_mul_f32_e32 v82, v84, v82
	v_mul_f32_e32 v84, 0xbfb8aa3b, v83
	v_exp_f32_e32 v84, v84
	s_nop 0
	v_add_f32_e32 v84, 1.0, v84
	v_rcp_f32_e32 v84, v84
	s_nop 0
	v_mul_f32_e32 v83, v84, v83
	v_mul_f32_e32 v83, v85, v83
	v_cvt_pk_bf16_f32 v89, v82, v83
	v_add_co_u32_e32 v82, vcc, s65, v166
	s_nop 1
	v_addc_co_u32_e32 v83, vcc, 0, v167, vcc
	global_store_dwordx4 v[82:83], v[86:89], off
	v_lshlrev_b32_e32 v82, 16, v106
	v_mul_f32_e32 v83, 0xbfb8aa3b, v82
	v_exp_f32_e32 v83, v83
	s_nop 0
	v_add_f32_e32 v83, 1.0, v83
	v_rcp_f32_e32 v83, v83
	s_nop 0
	v_mul_f32_e32 v82, v83, v82
	v_mul_f32_e32 v78, v78, v82
	v_and_b32_e32 v82, 0xffff0000, v106
	v_mul_f32_e32 v83, 0xbfb8aa3b, v82
	v_exp_f32_e32 v83, v83
	s_nop 0
	v_add_f32_e32 v83, 1.0, v83
	v_rcp_f32_e32 v83, v83
	s_nop 0
	v_mul_f32_e32 v82, v83, v82
	v_mul_f32_e32 v79, v79, v82
	v_cvt_pk_bf16_f32 v78, v78, v79
	v_lshlrev_b32_e32 v79, 16, v107
	v_mul_f32_e32 v82, 0xbfb8aa3b, v79
	v_exp_f32_e32 v82, v82
	s_nop 0
	v_add_f32_e32 v82, 1.0, v82
	v_rcp_f32_e32 v82, v82
; __device__ __forceinline__ unsigned cvt_pk_bf16(float lo, float hi) { unsigned r; asm volatile("v_cvt_pk_bf16_f32 %0, %1, %2" : "=v"(r) : "v"(lo), "v"(hi)); return r; }
; __device__ __forceinline__ float bf_lo(unsigned w) { return __uint_as_float(w << 16); }
; __device__ __forceinline__ float bf_hi(unsigned w) { return __uint_as_float(w & 0xffff0000u); }
; __device__ __forceinline__ float silu_f(float z) { return z * fast_rcp(1.0f + __builtin_amdgcn_exp2f(z * -1.44269504f)); }
;     __device__ __forceinline__ void operator()(const f32x4 (&acc)[2][2][4][2], const Unit& u, int wr, int wc, int fr, int fq, const Pre&) const {
;     ...
;         for (int bj = 0; bj < 2; ++bj) { const int c = col0 + bj * HALF;
;             u32x4 zv[8];
; #pragma unroll
;             for (int g8 = 0; g8 < 8; ++g8) zv[g8] = *(const u32x4*)(Z + (size_t)(row0 + (g8 >> 2) * HALF + (g8 & 3) * 16) * DE2 + c);
; #pragma unroll
;             for (int ai = 0; ai < 2; ++ai)
; #pragma unroll
;                 for (int m = 0; m < 4; ++m) { const int r = row0 + ai * HALF + m * 16;
;                     const u32x4 zw = zv[ai * 4 + m];
;                     const f32x4 a0 = acc[ai][bj][m][0] * sc[bj][0], a1 = acc[ai][bj][m][1] * sc[bj][1];
;                     u32x4 w;
;                     w.x = cvt_pk_bf16(a0[0] * silu_f(bf_lo(zw.x)), a0[1] * silu_f(bf_hi(zw.x)));
;                     w.y = cvt_pk_bf16(a0[2] * silu_f(bf_lo(zw.y)), a0[3] * silu_f(bf_hi(zw.y)));
;                     w.z = cvt_pk_bf16(a1[0] * silu_f(bf_lo(zw.z)), a1[1] * silu_f(bf_hi(zw.z)));
;                     w.w = cvt_pk_bf16(a1[2] * silu_f(bf_lo(zw.w)), a1[3] * silu_f(bf_hi(zw.w)));
;                     *(u32x4*)(O + (size_t)r * DE + c) = w; } }
	s_nop 0
	v_mul_f32_e32 v79, v82, v79
	v_mul_f32_e32 v79, v80, v79
	v_and_b32_e32 v80, 0xffff0000, v107
	v_mul_f32_e32 v82, 0xbfb8aa3b, v80
	v_exp_f32_e32 v82, v82
	v_lshl_add_u64 v[106:107], v[166:167], 0, s[0:1]
	s_mov_b64 s[0:1], s[54:55]
	v_add_f32_e32 v82, 1.0, v82
	v_rcp_f32_e32 v82, v82
	s_nop 0
	v_mul_f32_e32 v80, v82, v80
	v_mul_f32_e32 v80, v81, v80
	v_cvt_pk_bf16_f32 v79, v79, v80
	v_lshlrev_b32_e32 v80, 16, v108
	v_mul_f32_e32 v81, 0xbfb8aa3b, v80
	v_exp_f32_e32 v81, v81
	s_nop 0
	v_add_f32_e32 v81, 1.0, v81
	v_rcp_f32_e32 v81, v81
	s_nop 0
	v_mul_f32_e32 v80, v81, v80
	v_mul_f32_e32 v74, v74, v80
	v_and_b32_e32 v80, 0xffff0000, v108
	v_mul_f32_e32 v81, 0xbfb8aa3b, v80
	v_exp_f32_e32 v81, v81
	s_nop 0
	v_add_f32_e32 v81, 1.0, v81
	v_rcp_f32_e32 v81, v81
	s_nop 0
	v_mul_f32_e32 v80, v81, v80
	v_mul_f32_e32 v75, v75, v80
	v_cvt_pk_bf16_f32 v80, v74, v75
	v_lshlrev_b32_e32 v74, 16, v109
	v_mul_f32_e32 v75, 0xbfb8aa3b, v74
	v_exp_f32_e32 v75, v75
	s_nop 0
	v_add_f32_e32 v75, 1.0, v75
	v_rcp_f32_e32 v75, v75
	s_nop 0
	v_mul_f32_e32 v74, v75, v74
	v_and_b32_e32 v75, 0xffff0000, v109
	v_mul_f32_e32 v74, v76, v74
	v_mul_f32_e32 v76, 0xbfb8aa3b, v75
	v_exp_f32_e32 v76, v76
	s_nop 0
	v_add_f32_e32 v76, 1.0, v76
	v_rcp_f32_e32 v76, v76
	s_nop 0
	v_mul_f32_e32 v75, v76, v75
	v_mul_f32_e32 v75, v77, v75
	v_cvt_pk_bf16_f32 v81, v74, v75
	v_add_co_u32_e32 v74, vcc, s70, v166
	v_lshl_add_u64 v[76:77], s[46:47], 0, v[204:205]
	s_nop 0
	v_addc_co_u32_e32 v75, vcc, 0, v167, vcc
	global_store_dwordx4 v[74:75], v[78:81], off
	v_or_b32_e32 v74, 0x80, v200
	v_ashrrev_i32_e32 v75, 31, v74
	v_lshlrev_b64 v[74:75], 1, v[74:75]
	v_lshl_add_u64 v[76:77], v[76:77], 0, v[74:75]
	global_load_dwordx4 v[102:105], v[76:77], off
	v_lshl_add_u64 v[76:77], s[46:47], 0, v[198:199]
	v_lshl_add_u64 v[76:77], v[76:77], 0, v[74:75]
	global_load_dwordx4 v[98:101], v[76:77], off
	v_lshl_add_u64 v[76:77], s[46:47], 0, v[202:203]
	v_lshl_add_u64 v[76:77], v[76:77], 0, v[74:75]
	global_load_dwordx4 v[94:97], v[76:77], off
	v_lshl_add_u64 v[76:77], s[46:47], 0, v[206:207]
	v_lshl_add_u64 v[76:77], v[76:77], 0, v[74:75]
	global_load_dwordx4 v[90:93], v[76:77], off
	v_lshl_add_u64 v[76:77], s[46:47], 0, v[208:209]
	v_lshl_add_u64 v[76:77], v[76:77], 0, v[74:75]
	global_load_dwordx4 v[86:89], v[76:77], off
	v_lshl_add_u64 v[76:77], s[46:47], 0, v[210:211]
	v_lshl_add_u64 v[76:77], v[76:77], 0, v[74:75]
	global_load_dwordx4 v[82:85], v[76:77], off
	v_lshl_add_u64 v[76:77], s[46:47], 0, v[212:213]
	v_lshl_add_u64 v[76:77], v[76:77], 0, v[74:75]
	global_load_dwordx4 v[78:81], v[76:77], off
	v_lshl_add_u64 v[76:77], s[46:47], 0, v[214:215]
	v_lshl_add_u64 v[74:75], v[76:77], 0, v[74:75]
	global_load_dwordx4 v[74:77], v[74:75], off
	s_and_b64 vcc, exec, s[42:43]
	s_waitcnt vmcnt(0)
	v_lshlrev_b32_e32 v108, 16, v102
	v_mul_f32_e32 v109, 0xbfb8aa3b, v108
	v_exp_f32_e32 v109, v109
	v_and_b32_e32 v102, 0xffff0000, v102
	v_add_f32_e32 v109, 1.0, v109
	v_rcp_f32_e32 v109, v109
	s_nop 0
	v_mul_f32_e32 v108, v109, v108
	v_mul_f32_e32 v70, v70, v108
	v_mul_f32_e32 v108, 0xbfb8aa3b, v102
	v_exp_f32_e32 v108, v108
	s_nop 0
	v_add_f32_e32 v108, 1.0, v108
	v_rcp_f32_e32 v108, v108
	s_nop 0
	v_mul_f32_e32 v102, v108, v102
	v_mul_f32_e32 v71, v71, v102
	v_cvt_pk_bf16_f32 v70, v70, v71
	v_lshlrev_b32_e32 v71, 16, v103
	v_mul_f32_e32 v102, 0xbfb8aa3b, v71
	v_exp_f32_e32 v102, v102
	s_nop 0
	v_add_f32_e32 v102, 1.0, v102
	v_rcp_f32_e32 v102, v102
	s_nop 0
	v_mul_f32_e32 v71, v102, v71
	v_mul_f32_e32 v71, v72, v71
	v_and_b32_e32 v72, 0xffff0000, v103
	v_mul_f32_e32 v102, 0xbfb8aa3b, v72
	v_exp_f32_e32 v102, v102
	s_nop 0
	v_add_f32_e32 v102, 1.0, v102
	v_rcp_f32_e32 v102, v102
	s_nop 0
	v_mul_f32_e32 v72, v102, v72
	v_mul_f32_e32 v72, v73, v72
	v_cvt_pk_bf16_f32 v71, v71, v72
	v_lshlrev_b32_e32 v72, 16, v104
	v_mul_f32_e32 v73, 0xbfb8aa3b, v72
	v_exp_f32_e32 v73, v73
	s_nop 0
	v_add_f32_e32 v73, 1.0, v73
	v_rcp_f32_e32 v73, v73
	s_nop 0
	v_mul_f32_e32 v72, v73, v72
	v_mul_f32_e32 v66, v66, v72
	v_and_b32_e32 v72, 0xffff0000, v104
	v_mul_f32_e32 v73, 0xbfb8aa3b, v72
	v_exp_f32_e32 v73, v73
	s_nop 0
	v_add_f32_e32 v73, 1.0, v73
	v_rcp_f32_e32 v73, v73
	s_nop 0
	v_mul_f32_e32 v72, v73, v72
	v_mul_f32_e32 v67, v67, v72
	v_cvt_pk_bf16_f32 v72, v66, v67
	v_lshlrev_b32_e32 v66, 16, v105
	v_mul_f32_e32 v67, 0xbfb8aa3b, v66
	v_exp_f32_e32 v67, v67
	s_nop 0
	v_add_f32_e32 v67, 1.0, v67
	v_rcp_f32_e32 v67, v67
	s_nop 0
	v_mul_f32_e32 v66, v67, v66
	v_and_b32_e32 v67, 0xffff0000, v105
	v_mul_f32_e32 v66, v68, v66
	v_mul_f32_e32 v68, 0xbfb8aa3b, v67
	v_exp_f32_e32 v68, v68
	s_nop 0
	v_add_f32_e32 v68, 1.0, v68
	v_rcp_f32_e32 v68, v68
	s_nop 0
	v_mul_f32_e32 v67, v68, v67
	v_mul_f32_e32 v67, v69, v67
	v_cvt_pk_bf16_f32 v73, v66, v67
	v_lshlrev_b32_e32 v66, 16, v98
	v_mul_f32_e32 v67, 0xbfb8aa3b, v66
	v_exp_f32_e32 v67, v67
	global_store_dwordx4 v[166:167], v[70:73], off offset:256
	v_add_f32_e32 v67, 1.0, v67
	v_rcp_f32_e32 v67, v67
	s_nop 0
	v_mul_f32_e32 v66, v67, v66
	v_mul_f32_e32 v62, v62, v66
	v_and_b32_e32 v66, 0xffff0000, v98
	v_mul_f32_e32 v67, 0xbfb8aa3b, v66
	v_exp_f32_e32 v67, v67
	s_nop 0
	v_add_f32_e32 v67, 1.0, v67
	v_rcp_f32_e32 v67, v67
	s_nop 0
	v_mul_f32_e32 v66, v67, v66
	v_mul_f32_e32 v63, v63, v66
	v_cvt_pk_bf16_f32 v62, v62, v63
	v_lshlrev_b32_e32 v63, 16, v99
	v_mul_f32_e32 v66, 0xbfb8aa3b, v63
	v_exp_f32_e32 v66, v66
	s_nop 0
	v_add_f32_e32 v66, 1.0, v66
	v_rcp_f32_e32 v66, v66
	s_nop 0
	v_mul_f32_e32 v63, v66, v63
	v_mul_f32_e32 v63, v64, v63
	v_and_b32_e32 v64, 0xffff0000, v99
	v_mul_f32_e32 v66, 0xbfb8aa3b, v64
	v_exp_f32_e32 v66, v66
	s_nop 0
	v_add_f32_e32 v66, 1.0, v66
; __device__ __forceinline__ unsigned cvt_pk_bf16(float lo, float hi) { unsigned r; asm volatile("v_cvt_pk_bf16_f32 %0, %1, %2" : "=v"(r) : "v"(lo), "v"(hi)); return r; }
; __device__ __forceinline__ float bf_lo(unsigned w) { return __uint_as_float(w << 16); }
; __device__ __forceinline__ float bf_hi(unsigned w) { return __uint_as_float(w & 0xffff0000u); }
; __device__ __forceinline__ float silu_f(float z) { return z * fast_rcp(1.0f + __builtin_amdgcn_exp2f(z * -1.44269504f)); }
;     __device__ __forceinline__ void operator()(const f32x4 (&acc)[2][2][4][2], const Unit& u, int wr, int wc, int fr, int fq, const Pre&) const {
;     ...
; #pragma unroll
;             for (int ai = 0; ai < 2; ++ai)
; #pragma unroll
;                 for (int m = 0; m < 4; ++m) { const int r = row0 + ai * HALF + m * 16;
;                     const u32x4 zw = zv[ai * 4 + m];
;                     const f32x4 a0 = acc[ai][bj][m][0] * sc[bj][0], a1 = acc[ai][bj][m][1] * sc[bj][1];
;                     u32x4 w;
;                     w.x = cvt_pk_bf16(a0[0] * silu_f(bf_lo(zw.x)), a0[1] * silu_f(bf_hi(zw.x)));
;                     w.y = cvt_pk_bf16(a0[2] * silu_f(bf_lo(zw.y)), a0[3] * silu_f(bf_hi(zw.y)));
;                     w.z = cvt_pk_bf16(a1[0] * silu_f(bf_lo(zw.z)), a1[1] * silu_f(bf_hi(zw.z)));
;                     w.w = cvt_pk_bf16(a1[2] * silu_f(bf_lo(zw.w)), a1[3] * silu_f(bf_hi(zw.w)));
;                     *(u32x4*)(O + (size_t)r * DE + c) = w; } }
	v_rcp_f32_e32 v66, v66
	s_nop 0
	v_mul_f32_e32 v64, v66, v64
	v_mul_f32_e32 v64, v65, v64
	v_cvt_pk_bf16_f32 v63, v63, v64
	v_lshlrev_b32_e32 v64, 16, v100
	v_mul_f32_e32 v65, 0xbfb8aa3b, v64
	v_exp_f32_e32 v65, v65
	s_nop 0
	v_add_f32_e32 v65, 1.0, v65
	v_rcp_f32_e32 v65, v65
	s_nop 0
	v_mul_f32_e32 v64, v65, v64
	v_mul_f32_e32 v58, v58, v64
	v_and_b32_e32 v64, 0xffff0000, v100
	v_mul_f32_e32 v65, 0xbfb8aa3b, v64
	v_exp_f32_e32 v65, v65
	s_nop 0
	v_add_f32_e32 v65, 1.0, v65
	v_rcp_f32_e32 v65, v65
	s_nop 0
	v_mul_f32_e32 v64, v65, v64
	v_mul_f32_e32 v59, v59, v64
	v_cvt_pk_bf16_f32 v64, v58, v59
	v_lshlrev_b32_e32 v58, 16, v101
	v_mul_f32_e32 v59, 0xbfb8aa3b, v58
	v_exp_f32_e32 v59, v59
	s_nop 0
	v_add_f32_e32 v59, 1.0, v59
	v_rcp_f32_e32 v59, v59
	s_nop 0
	v_mul_f32_e32 v58, v59, v58
	v_and_b32_e32 v59, 0xffff0000, v101
	v_mul_f32_e32 v58, v60, v58
	v_mul_f32_e32 v60, 0xbfb8aa3b, v59
	v_exp_f32_e32 v60, v60
	s_nop 0
	v_add_f32_e32 v60, 1.0, v60
	v_rcp_f32_e32 v60, v60
	s_nop 0
	v_mul_f32_e32 v59, v60, v59
	v_mul_f32_e32 v59, v61, v59
	v_cvt_pk_bf16_f32 v65, v58, v59
	v_lshlrev_b32_e32 v58, 16, v94
	v_mul_f32_e32 v59, 0xbfb8aa3b, v58
	v_exp_f32_e32 v59, v59
	global_store_dwordx4 v[146:147], v[62:65], off offset:256
	v_add_f32_e32 v59, 1.0, v59
	v_rcp_f32_e32 v59, v59
	s_nop 0
	v_mul_f32_e32 v58, v59, v58
	v_mul_f32_e32 v54, v54, v58
	v_and_b32_e32 v58, 0xffff0000, v94
	v_mul_f32_e32 v59, 0xbfb8aa3b, v58
	v_exp_f32_e32 v59, v59
	s_nop 0
	v_add_f32_e32 v59, 1.0, v59
	v_rcp_f32_e32 v59, v59
	s_nop 0
	v_mul_f32_e32 v58, v59, v58
	v_mul_f32_e32 v55, v55, v58
	v_cvt_pk_bf16_f32 v54, v54, v55
	v_lshlrev_b32_e32 v55, 16, v95
	v_mul_f32_e32 v58, 0xbfb8aa3b, v55
	v_exp_f32_e32 v58, v58
	s_nop 0
	v_add_f32_e32 v58, 1.0, v58
	v_rcp_f32_e32 v58, v58
	s_nop 0
	v_mul_f32_e32 v55, v58, v55
	v_mul_f32_e32 v55, v56, v55
	v_and_b32_e32 v56, 0xffff0000, v95
	v_mul_f32_e32 v58, 0xbfb8aa3b, v56
	v_exp_f32_e32 v58, v58
	s_nop 0
	v_add_f32_e32 v58, 1.0, v58
	v_rcp_f32_e32 v58, v58
	s_nop 0
	v_mul_f32_e32 v56, v58, v56
	v_mul_f32_e32 v56, v57, v56
	v_cvt_pk_bf16_f32 v55, v55, v56
	v_lshlrev_b32_e32 v56, 16, v96
	v_mul_f32_e32 v57, 0xbfb8aa3b, v56
	v_exp_f32_e32 v57, v57
	s_nop 0
	v_add_f32_e32 v57, 1.0, v57
	v_rcp_f32_e32 v57, v57
	s_nop 0
	v_mul_f32_e32 v56, v57, v56
	v_mul_f32_e32 v50, v50, v56
	v_and_b32_e32 v56, 0xffff0000, v96
	v_mul_f32_e32 v57, 0xbfb8aa3b, v56
	v_exp_f32_e32 v57, v57
	s_nop 0
	v_add_f32_e32 v57, 1.0, v57
	v_rcp_f32_e32 v57, v57
	s_nop 0
	v_mul_f32_e32 v56, v57, v56
	v_mul_f32_e32 v51, v51, v56
	v_cvt_pk_bf16_f32 v56, v50, v51
	v_lshlrev_b32_e32 v50, 16, v97
	v_mul_f32_e32 v51, 0xbfb8aa3b, v50
	v_exp_f32_e32 v51, v51
	s_nop 0
	v_add_f32_e32 v51, 1.0, v51
	v_rcp_f32_e32 v51, v51
	s_nop 0
	v_mul_f32_e32 v50, v51, v50
	v_and_b32_e32 v51, 0xffff0000, v97
	v_mul_f32_e32 v50, v52, v50
	v_mul_f32_e32 v52, 0xbfb8aa3b, v51
	v_exp_f32_e32 v52, v52
	s_nop 0
	v_add_f32_e32 v52, 1.0, v52
	v_rcp_f32_e32 v52, v52
	s_nop 0
	v_mul_f32_e32 v51, v52, v51
	v_mul_f32_e32 v51, v53, v51
	v_cvt_pk_bf16_f32 v57, v50, v51
	v_lshlrev_b32_e32 v50, 16, v90
	v_mul_f32_e32 v51, 0xbfb8aa3b, v50
	v_exp_f32_e32 v51, v51
	global_store_dwordx4 v[134:135], v[54:57], off offset:256
	v_add_f32_e32 v51, 1.0, v51
	v_rcp_f32_e32 v51, v51
	s_nop 0
	v_mul_f32_e32 v50, v51, v50
	v_mul_f32_e32 v46, v46, v50
	v_and_b32_e32 v50, 0xffff0000, v90
	v_mul_f32_e32 v51, 0xbfb8aa3b, v50
	v_exp_f32_e32 v51, v51
	s_nop 0
	v_add_f32_e32 v51, 1.0, v51
	v_rcp_f32_e32 v51, v51
	s_nop 0
	v_mul_f32_e32 v50, v51, v50
	v_mul_f32_e32 v47, v47, v50
	v_cvt_pk_bf16_f32 v46, v46, v47
	v_lshlrev_b32_e32 v47, 16, v91
	v_mul_f32_e32 v50, 0xbfb8aa3b, v47
	v_exp_f32_e32 v50, v50
	s_nop 0
	v_add_f32_e32 v50, 1.0, v50
	v_rcp_f32_e32 v50, v50
	s_nop 0
	v_mul_f32_e32 v47, v50, v47
	v_mul_f32_e32 v47, v48, v47
	v_and_b32_e32 v48, 0xffff0000, v91
	v_mul_f32_e32 v50, 0xbfb8aa3b, v48
	v_exp_f32_e32 v50, v50
	s_nop 0
	v_add_f32_e32 v50, 1.0, v50
	v_rcp_f32_e32 v50, v50
	s_nop 0
	v_mul_f32_e32 v48, v50, v48
	v_mul_f32_e32 v48, v49, v48
	v_cvt_pk_bf16_f32 v47, v47, v48
	v_lshlrev_b32_e32 v48, 16, v92
	v_mul_f32_e32 v49, 0xbfb8aa3b, v48
	v_exp_f32_e32 v49, v49
	s_nop 0
	v_add_f32_e32 v49, 1.0, v49
	v_rcp_f32_e32 v49, v49
	s_nop 0
	v_mul_f32_e32 v48, v49, v48
	v_mul_f32_e32 v42, v42, v48
	v_and_b32_e32 v48, 0xffff0000, v92
	v_mul_f32_e32 v49, 0xbfb8aa3b, v48
	v_exp_f32_e32 v49, v49
	s_nop 0
	v_add_f32_e32 v49, 1.0, v49
	v_rcp_f32_e32 v49, v49
	s_nop 0
	v_mul_f32_e32 v48, v49, v48
	v_mul_f32_e32 v43, v43, v48
	v_cvt_pk_bf16_f32 v48, v42, v43
	v_lshlrev_b32_e32 v42, 16, v93
	v_mul_f32_e32 v43, 0xbfb8aa3b, v42
	v_exp_f32_e32 v43, v43
	s_nop 0
	v_add_f32_e32 v43, 1.0, v43
	v_rcp_f32_e32 v43, v43
	s_nop 0
	v_mul_f32_e32 v42, v43, v42
	v_and_b32_e32 v43, 0xffff0000, v93
	v_mul_f32_e32 v42, v44, v42
	v_mul_f32_e32 v44, 0xbfb8aa3b, v43
	v_exp_f32_e32 v44, v44
	s_nop 0
	v_add_f32_e32 v44, 1.0, v44
	v_rcp_f32_e32 v44, v44
	s_nop 0
	v_mul_f32_e32 v43, v44, v43
	v_mul_f32_e32 v43, v45, v43
	v_cvt_pk_bf16_f32 v49, v42, v43
	v_lshlrev_b32_e32 v42, 16, v86
	v_mul_f32_e32 v43, 0xbfb8aa3b, v42
	v_exp_f32_e32 v43, v43
	global_store_dwordx4 v[122:123], v[46:49], off offset:256
	v_add_f32_e32 v43, 1.0, v43
	v_rcp_f32_e32 v43, v43
	s_nop 0
	v_mul_f32_e32 v42, v43, v42
	v_mul_f32_e32 v30, v30, v42
	v_and_b32_e32 v42, 0xffff0000, v86
	v_mul_f32_e32 v43, 0xbfb8aa3b, v42
	v_exp_f32_e32 v43, v43
	s_nop 0
	v_add_f32_e32 v43, 1.0, v43
	v_rcp_f32_e32 v43, v43
	s_nop 0
	v_mul_f32_e32 v42, v43, v42
	v_mul_f32_e32 v31, v31, v42
	v_cvt_pk_bf16_f32 v30, v30, v31
	v_lshlrev_b32_e32 v31, 16, v87
	v_mul_f32_e32 v42, 0xbfb8aa3b, v31
	v_exp_f32_e32 v42, v42
; __device__ __forceinline__ unsigned cvt_pk_bf16(float lo, float hi) { unsigned r; asm volatile("v_cvt_pk_bf16_f32 %0, %1, %2" : "=v"(r) : "v"(lo), "v"(hi)); return r; }
; __device__ __forceinline__ float bf_lo(unsigned w) { return __uint_as_float(w << 16); }
; __device__ __forceinline__ float bf_hi(unsigned w) { return __uint_as_float(w & 0xffff0000u); }
; __device__ __forceinline__ float silu_f(float z) { return z * fast_rcp(1.0f + __builtin_amdgcn_exp2f(z * -1.44269504f)); }
;     __device__ __forceinline__ void operator()(const f32x4 (&acc)[2][2][4][2], const Unit& u, int wr, int wc, int fr, int fq, const Pre&) const {
;     ...
; #pragma unroll
;             for (int ai = 0; ai < 2; ++ai)
; #pragma unroll
;                 for (int m = 0; m < 4; ++m) { const int r = row0 + ai * HALF + m * 16;
;                     const u32x4 zw = zv[ai * 4 + m];
;                     const f32x4 a0 = acc[ai][bj][m][0] * sc[bj][0], a1 = acc[ai][bj][m][1] * sc[bj][1];
;                     u32x4 w;
;                     w.x = cvt_pk_bf16(a0[0] * silu_f(bf_lo(zw.x)), a0[1] * silu_f(bf_hi(zw.x)));
;                     w.y = cvt_pk_bf16(a0[2] * silu_f(bf_lo(zw.y)), a0[3] * silu_f(bf_hi(zw.y)));
;                     w.z = cvt_pk_bf16(a1[0] * silu_f(bf_lo(zw.z)), a1[1] * silu_f(bf_hi(zw.z)));
;                     w.w = cvt_pk_bf16(a1[2] * silu_f(bf_lo(zw.w)), a1[3] * silu_f(bf_hi(zw.w)));
;                     *(u32x4*)(O + (size_t)r * DE + c) = w; } }
	s_nop 0
	v_add_f32_e32 v42, 1.0, v42
	v_rcp_f32_e32 v42, v42
	s_nop 0
	v_mul_f32_e32 v31, v42, v31
	v_mul_f32_e32 v31, v32, v31
	v_and_b32_e32 v32, 0xffff0000, v87
	v_mul_f32_e32 v42, 0xbfb8aa3b, v32
	v_exp_f32_e32 v42, v42
	s_nop 0
	v_add_f32_e32 v42, 1.0, v42
	v_rcp_f32_e32 v42, v42
	s_nop 0
	v_mul_f32_e32 v32, v42, v32
	v_mul_f32_e32 v32, v33, v32
	v_cvt_pk_bf16_f32 v31, v31, v32
	v_lshlrev_b32_e32 v32, 16, v88
	v_mul_f32_e32 v33, 0xbfb8aa3b, v32
	v_exp_f32_e32 v33, v33
	s_nop 0
	v_add_f32_e32 v33, 1.0, v33
	v_rcp_f32_e32 v33, v33
	s_nop 0
	v_mul_f32_e32 v32, v33, v32
	v_mul_f32_e32 v26, v26, v32
	v_and_b32_e32 v32, 0xffff0000, v88
	v_mul_f32_e32 v33, 0xbfb8aa3b, v32
	v_exp_f32_e32 v33, v33
	s_nop 0
	v_add_f32_e32 v33, 1.0, v33
	v_rcp_f32_e32 v33, v33
	s_nop 0
	v_mul_f32_e32 v32, v33, v32
	v_mul_f32_e32 v27, v27, v32
	v_cvt_pk_bf16_f32 v32, v26, v27
	v_lshlrev_b32_e32 v26, 16, v89
	v_mul_f32_e32 v27, 0xbfb8aa3b, v26
	v_exp_f32_e32 v27, v27
	s_nop 0
	v_add_f32_e32 v27, 1.0, v27
	v_rcp_f32_e32 v27, v27
	s_nop 0
	v_mul_f32_e32 v26, v27, v26
	v_and_b32_e32 v27, 0xffff0000, v89
	v_mul_f32_e32 v26, v28, v26
	v_mul_f32_e32 v28, 0xbfb8aa3b, v27
	v_exp_f32_e32 v28, v28
	s_nop 0
	v_add_f32_e32 v28, 1.0, v28
	v_rcp_f32_e32 v28, v28
	s_nop 0
	v_mul_f32_e32 v27, v28, v27
	v_mul_f32_e32 v27, v29, v27
	v_cvt_pk_bf16_f32 v33, v26, v27
	v_lshlrev_b32_e32 v26, 16, v82
	v_mul_f32_e32 v27, 0xbfb8aa3b, v26
	v_exp_f32_e32 v27, v27
	global_store_dwordx4 v[112:113], v[30:33], off offset:256
	v_add_f32_e32 v27, 1.0, v27
	v_rcp_f32_e32 v27, v27
	s_nop 0
	v_mul_f32_e32 v26, v27, v26
	v_mul_f32_e32 v22, v22, v26
	v_and_b32_e32 v26, 0xffff0000, v82
	v_mul_f32_e32 v27, 0xbfb8aa3b, v26
	v_exp_f32_e32 v27, v27
	s_nop 0
	v_add_f32_e32 v27, 1.0, v27
	v_rcp_f32_e32 v27, v27
	s_nop 0
	v_mul_f32_e32 v26, v27, v26
	v_mul_f32_e32 v23, v23, v26
	v_cvt_pk_bf16_f32 v22, v22, v23
	v_lshlrev_b32_e32 v23, 16, v83
	v_mul_f32_e32 v26, 0xbfb8aa3b, v23
	v_exp_f32_e32 v26, v26
	s_nop 0
	v_add_f32_e32 v26, 1.0, v26
	v_rcp_f32_e32 v26, v26
	s_nop 0
	v_mul_f32_e32 v23, v26, v23
	v_mul_f32_e32 v23, v24, v23
	v_and_b32_e32 v24, 0xffff0000, v83
	v_mul_f32_e32 v26, 0xbfb8aa3b, v24
	v_exp_f32_e32 v26, v26
	s_nop 0
	v_add_f32_e32 v26, 1.0, v26
	v_rcp_f32_e32 v26, v26
	s_nop 0
	v_mul_f32_e32 v24, v26, v24
	v_mul_f32_e32 v24, v25, v24
	v_cvt_pk_bf16_f32 v23, v23, v24
	v_lshlrev_b32_e32 v24, 16, v84
	v_mul_f32_e32 v25, 0xbfb8aa3b, v24
	v_exp_f32_e32 v25, v25
	s_nop 0
	v_add_f32_e32 v25, 1.0, v25
	v_rcp_f32_e32 v25, v25
	s_nop 0
	v_mul_f32_e32 v24, v25, v24
	v_mul_f32_e32 v18, v18, v24
	v_and_b32_e32 v24, 0xffff0000, v84
	v_mul_f32_e32 v25, 0xbfb8aa3b, v24
	v_exp_f32_e32 v25, v25
	s_nop 0
	v_add_f32_e32 v25, 1.0, v25
	v_rcp_f32_e32 v25, v25
	s_nop 0
	v_mul_f32_e32 v24, v25, v24
	v_mul_f32_e32 v19, v19, v24
	v_cvt_pk_bf16_f32 v24, v18, v19
	v_lshlrev_b32_e32 v18, 16, v85
	v_mul_f32_e32 v19, 0xbfb8aa3b, v18
	v_exp_f32_e32 v19, v19
	s_nop 0
	v_add_f32_e32 v19, 1.0, v19
	v_rcp_f32_e32 v19, v19
	s_nop 0
	v_mul_f32_e32 v18, v19, v18
	v_and_b32_e32 v19, 0xffff0000, v85
	v_mul_f32_e32 v18, v20, v18
	v_mul_f32_e32 v20, 0xbfb8aa3b, v19
	v_exp_f32_e32 v20, v20
	s_nop 0
	v_add_f32_e32 v20, 1.0, v20
	v_rcp_f32_e32 v20, v20
	s_nop 0
	v_mul_f32_e32 v19, v20, v19
	v_mul_f32_e32 v19, v21, v19
	v_cvt_pk_bf16_f32 v25, v18, v19
	v_lshlrev_b32_e32 v18, 16, v78
	v_mul_f32_e32 v19, 0xbfb8aa3b, v18
	v_exp_f32_e32 v19, v19
	global_store_dwordx4 v[110:111], v[22:25], off offset:256
	v_add_f32_e32 v19, 1.0, v19
	v_rcp_f32_e32 v19, v19
	s_nop 0
	v_mul_f32_e32 v18, v19, v18
	v_mul_f32_e32 v14, v14, v18
	v_and_b32_e32 v18, 0xffff0000, v78
	v_mul_f32_e32 v19, 0xbfb8aa3b, v18
	v_exp_f32_e32 v19, v19
; __device__ __forceinline__ unsigned cvt_pk_bf16(float lo, float hi) { unsigned r; asm volatile("v_cvt_pk_bf16_f32 %0, %1, %2" : "=v"(r) : "v"(lo), "v"(hi)); return r; }
; __device__ __forceinline__ float bf_lo(unsigned w) { return __uint_as_float(w << 16); }
; __device__ __forceinline__ float bf_hi(unsigned w) { return __uint_as_float(w & 0xffff0000u); }
; __device__ __forceinline__ float silu_f(float z) { return z * fast_rcp(1.0f + __builtin_amdgcn_exp2f(z * -1.44269504f)); }
;     __device__ __forceinline__ void operator()(const f32x4 (&acc)[2][2][4][2], const Unit& u, int wr, int wc, int fr, int fq, const Pre&) const {
;     ...
; #pragma unroll
;             for (int ai = 0; ai < 2; ++ai)
; #pragma unroll
;                 for (int m = 0; m < 4; ++m) { const int r = row0 + ai * HALF + m * 16;
;                     const u32x4 zw = zv[ai * 4 + m];
;                     const f32x4 a0 = acc[ai][bj][m][0] * sc[bj][0], a1 = acc[ai][bj][m][1] * sc[bj][1];
;                     u32x4 w;
;                     w.x = cvt_pk_bf16(a0[0] * silu_f(bf_lo(zw.x)), a0[1] * silu_f(bf_hi(zw.x)));
;                     w.y = cvt_pk_bf16(a0[2] * silu_f(bf_lo(zw.y)), a0[3] * silu_f(bf_hi(zw.y)));
;                     w.z = cvt_pk_bf16(a1[0] * silu_f(bf_lo(zw.z)), a1[1] * silu_f(bf_hi(zw.z)));
;                     w.w = cvt_pk_bf16(a1[2] * silu_f(bf_lo(zw.w)), a1[3] * silu_f(bf_hi(zw.w)));
;                     *(u32x4*)(O + (size_t)r * DE + c) = w; } }
	s_nop 0
	v_add_f32_e32 v19, 1.0, v19
	v_rcp_f32_e32 v19, v19
	s_nop 0
	v_mul_f32_e32 v18, v19, v18
	v_mul_f32_e32 v15, v15, v18
	v_cvt_pk_bf16_f32 v14, v14, v15
	v_lshlrev_b32_e32 v15, 16, v79
	v_mul_f32_e32 v18, 0xbfb8aa3b, v15
	v_exp_f32_e32 v18, v18
	s_nop 0
	v_add_f32_e32 v18, 1.0, v18
	v_rcp_f32_e32 v18, v18
	s_nop 0
	v_mul_f32_e32 v15, v18, v15
	v_mul_f32_e32 v15, v16, v15
	v_and_b32_e32 v16, 0xffff0000, v79
	v_mul_f32_e32 v18, 0xbfb8aa3b, v16
	v_exp_f32_e32 v18, v18
	s_nop 0
	v_add_f32_e32 v18, 1.0, v18
	v_rcp_f32_e32 v18, v18
	s_nop 0
	v_mul_f32_e32 v16, v18, v16
	v_mul_f32_e32 v16, v17, v16
	v_cvt_pk_bf16_f32 v15, v15, v16
	v_lshlrev_b32_e32 v16, 16, v80
	v_mul_f32_e32 v17, 0xbfb8aa3b, v16
	v_exp_f32_e32 v17, v17
	s_nop 0
	v_add_f32_e32 v17, 1.0, v17
	v_rcp_f32_e32 v17, v17
	s_nop 0
	v_mul_f32_e32 v16, v17, v16
	v_mul_f32_e32 v10, v10, v16
	v_and_b32_e32 v16, 0xffff0000, v80
	v_mul_f32_e32 v17, 0xbfb8aa3b, v16
	v_exp_f32_e32 v17, v17
	s_nop 0
	v_add_f32_e32 v17, 1.0, v17
	v_rcp_f32_e32 v17, v17
	s_nop 0
	v_mul_f32_e32 v16, v17, v16
	v_mul_f32_e32 v11, v11, v16
	v_cvt_pk_bf16_f32 v16, v10, v11
	v_lshlrev_b32_e32 v10, 16, v81
	v_mul_f32_e32 v11, 0xbfb8aa3b, v10
	v_exp_f32_e32 v11, v11
	s_nop 0
	v_add_f32_e32 v11, 1.0, v11
	v_rcp_f32_e32 v11, v11
	s_nop 0
	v_mul_f32_e32 v10, v11, v10
	v_and_b32_e32 v11, 0xffff0000, v81
	v_mul_f32_e32 v10, v12, v10
	v_mul_f32_e32 v12, 0xbfb8aa3b, v11
	v_exp_f32_e32 v12, v12
	s_nop 0
	v_add_f32_e32 v12, 1.0, v12
	v_rcp_f32_e32 v12, v12
	s_nop 0
	v_mul_f32_e32 v11, v12, v11
	v_mul_f32_e32 v11, v13, v11
	v_cvt_pk_bf16_f32 v17, v10, v11
	v_lshlrev_b32_e32 v10, 16, v74
	v_mul_f32_e32 v11, 0xbfb8aa3b, v10
	v_exp_f32_e32 v11, v11
	global_store_dwordx4 v[114:115], v[14:17], off offset:256
	v_add_f32_e32 v11, 1.0, v11
	v_rcp_f32_e32 v11, v11
	s_nop 0
	v_mul_f32_e32 v10, v11, v10
	v_mul_f32_e32 v6, v6, v10
	v_and_b32_e32 v10, 0xffff0000, v74
	v_mul_f32_e32 v11, 0xbfb8aa3b, v10
	v_exp_f32_e32 v11, v11
	s_nop 0
	v_add_f32_e32 v11, 1.0, v11
	v_rcp_f32_e32 v11, v11
	s_nop 0
	v_mul_f32_e32 v10, v11, v10
	v_mul_f32_e32 v7, v7, v10
	v_cvt_pk_bf16_f32 v6, v6, v7
	v_lshlrev_b32_e32 v7, 16, v75
	v_mul_f32_e32 v10, 0xbfb8aa3b, v7
	v_exp_f32_e32 v10, v10
	s_nop 0
	v_add_f32_e32 v10, 1.0, v10
	v_rcp_f32_e32 v10, v10
	s_nop 0
	v_mul_f32_e32 v7, v10, v7
	v_mul_f32_e32 v7, v8, v7
	v_and_b32_e32 v8, 0xffff0000, v75
	v_mul_f32_e32 v10, 0xbfb8aa3b, v8
	v_exp_f32_e32 v10, v10
	s_nop 0
	v_add_f32_e32 v10, 1.0, v10
	v_rcp_f32_e32 v10, v10
	s_nop 0
	v_mul_f32_e32 v8, v10, v8
	v_mul_f32_e32 v8, v9, v8
	v_cvt_pk_bf16_f32 v7, v7, v8
	v_lshlrev_b32_e32 v8, 16, v76
	v_mul_f32_e32 v9, 0xbfb8aa3b, v8
	v_exp_f32_e32 v9, v9
	s_nop 0
	v_add_f32_e32 v9, 1.0, v9
	v_rcp_f32_e32 v9, v9
	s_nop 0
	v_mul_f32_e32 v8, v9, v8
	v_mul_f32_e32 v2, v2, v8
	v_and_b32_e32 v8, 0xffff0000, v76
	v_mul_f32_e32 v9, 0xbfb8aa3b, v8
	v_exp_f32_e32 v9, v9
	s_nop 0
	v_add_f32_e32 v9, 1.0, v9
	v_rcp_f32_e32 v9, v9
	s_nop 0
	v_mul_f32_e32 v8, v9, v8
	v_mul_f32_e32 v3, v3, v8
	v_cvt_pk_bf16_f32 v8, v2, v3
	v_lshlrev_b32_e32 v2, 16, v77
	v_mul_f32_e32 v3, 0xbfb8aa3b, v2
	v_exp_f32_e32 v3, v3
	s_nop 0
	v_add_f32_e32 v3, 1.0, v3
	v_rcp_f32_e32 v3, v3
	s_nop 0
	v_mul_f32_e32 v2, v3, v2
	v_and_b32_e32 v3, 0xffff0000, v77
	v_mul_f32_e32 v2, v4, v2
	v_mul_f32_e32 v4, 0xbfb8aa3b, v3
	v_exp_f32_e32 v4, v4
	s_nop 0
	v_add_f32_e32 v4, 1.0, v4
	v_rcp_f32_e32 v4, v4
	s_nop 0
	v_mul_f32_e32 v3, v4, v3
	v_mul_f32_e32 v3, v5, v3
	v_cvt_pk_bf16_f32 v9, v2, v3
	global_store_dwordx4 v[106:107], v[6:9], off offset:256
	s_cbranch_vccz .LBB0_596
	s_waitcnt vmcnt(0)
	s_cmpk_gt_u32 s14, 0xff
	s_mov_b64 s[36:37], s[96:97]
	s_cbranch_scc1 .LBB0_607
	s_barrier

; #define PG8_STAGE(bufoff, gbase, voff) do { _Pragma("unroll") for (int _i = 0; _i < 2; ++_i) \
;         __builtin_amdgcn_global_load_lds((const unsigned*)((const char*)(gbase) + (voff)[_i]), (LAS unsigned*)(lds + (bufoff) + ldsw + _i * 8192), 16, 0, 0); } while (0)
; #define PG8_LDA(dst, b, h) do { _Pragma("unroll") for (int m = 0; m < 4; ++m) _Pragma("unroll") for (int k = 0; k < 2; ++k) dst[m][k] = *(const LAS bf16x8*)(lds + PG8_SA(b, h) + aoff + m * 2048 + k * 1024); } while (0)
; #define PG8_LDB(dst, b, h) do { _Pragma("unroll") for (int n = 0; n < 2; ++n) _Pragma("unroll") for (int k = 0; k < 2; ++k) dst[n][k] = *(const LAS bf16x8*)(lds + PG8_SB(b, h) + boff + n * 2048 + k * 1024); } while (0)
; #define PG8_MMA(ai, bj, At, Bt) do { __builtin_amdgcn_s_setprio(1); _Pragma("unroll") for (int m = 0; m < 4; ++m) _Pragma("unroll") for (int n = 0; n < 2; ++n) _Pragma("unroll") for (int k = 0; k < 2; ++k) \
;         acc[ai][bj][m][n] = __builtin_amdgcn_mfma_f32_16x16x32_bf16(Bt[n][k], At[m][k], acc[ai][bj][m][n], 0, 0, 0); __builtin_amdgcn_s_setprio(0); } while (0)
; #define PG8_WAIT_V(n) asm volatile("s_waitcnt vmcnt(" #n ")" ::: "memory")
; #define PG8_WAIT_L(n) asm volatile("s_waitcnt lgkmcnt(" #n ")" ::: "memory")
; #define PG8_BAR __builtin_amdgcn_s_barrier()
; template <class Epi>
; __device__ __forceinline__ void gemm_phase(LAS unsigned char* lds, const Gemm g, const StaticOrder& S, const Epi& E) {
;     ...
;             const bool last = (t == nt - 2);
;             const char* a1 = cA + (size_t)(t + 1) * kstepA;
;             const char* a2 = last ? nA : cA + (size_t)(t + 2) * kstepA; const char* b2 = last ? nB : cB + (size_t)(t + 2) * kstep;
;             const char* a3 = a2 + kstepA; const char* b3 = b2 + kstep;
;             PG8_LDB(B0, 0, 0); PG8_SCHED; PG8_LDA(At, 0, 0); PG8_STAGE(PG8_SA(1, 1), a1 + hstepA, voffA);
;             PG8_WAIT_L(8); PG8_BAR; PG8_WAIT_L(0); PG8_MMA(0, 0, At, B0); PG8_BAR; PG8_SCHED;
;             PG8_LDB(B1, 0, 1); PG8_STAGE(PG8_SB(0, 0), b2, voffB);
;             PG8_BAR; PG8_WAIT_L(0); PG8_MMA(0, 1, At, B1); PG8_BAR;
;             PG8_LDA(At, 0, 1); PG8_STAGE(PG8_SA(0, 0), a2, voffA);
;             PG8_BAR; PG8_WAIT_L(0); PG8_MMA(1, 0, At, B0); PG8_BAR; PG8_SCHED;
;             PG8_STAGE(PG8_SB(0, 1), b2 + hstepB, voffB);
;             PG8_WAIT_V(6); PG8_BAR; PG8_MMA(1, 1, At, B1); PG8_BAR;
.LBB0_796:
	s_add_u32 s4, s8, 0x103400
	s_addc_u32 s5, s9, 0
	s_cmp_eq_u32 s57, 60
	s_cselect_b32 s16, s38, s4
	s_cselect_b32 s17, s37, s5
	s_cselect_b32 s4, s49, s51
	s_cselect_b32 s5, s39, s56
	s_add_u32 s14, s16, 0x104400
	s_addc_u32 s15, s17, 0
	s_add_i32 s58, 0, 0x10000
	s_add_i32 m0, s22, 0xc000
	s_nop 0
	global_load_lds_dwordx4 v196, s[8:9]
	s_add_i32 m0, s22, 0xe000
	s_nop 0
	global_load_lds_dwordx4 v198, s[8:9]
	ds_read_b128 v[26:29], v250
	ds_read_b128 v[30:33], v250 offset:1024
	ds_read_b128 v[98:101], v250 offset:2048
	ds_read_b128 v[102:105], v250 offset:3072
	ds_read_b128 v[130:133], v247
	ds_read_b128 v[142:145], v247 offset:1024
	ds_read_b128 v[146:149], v247 offset:2048
	ds_read_b128 v[150:153], v247 offset:3072
	ds_read_b128 v[154:157], v247 offset:4096
	ds_read_b128 v[166:169], v247 offset:5120
	ds_read_b128 v[170:173], v247 offset:6144
	ds_read_b128 v[174:177], v247 offset:7168
	s_waitcnt lgkmcnt(8)
	s_barrier
	s_waitcnt lgkmcnt(0)
	v_mfma_f32_16x16x32_bf16 v[162:165], v[26:29], v[130:133], v[162:165]
	v_mfma_f32_16x16x32_bf16 v[158:161], v[98:101], v[130:133], v[158:161]
	v_mfma_f32_16x16x32_bf16 v[138:141], v[26:29], v[146:149], v[138:141]
	v_mfma_f32_16x16x32_bf16 v[134:137], v[98:101], v[146:149], v[134:137]
	v_mfma_f32_16x16x32_bf16 v[126:129], v[26:29], v[154:157], v[126:129]
	v_mfma_f32_16x16x32_bf16 v[122:125], v[98:101], v[154:157], v[122:125]
	v_mfma_f32_16x16x32_bf16 v[118:121], v[26:29], v[170:173], v[118:121]
	v_mfma_f32_16x16x32_bf16 v[114:117], v[98:101], v[170:173], v[114:117]
	v_mfma_f32_16x16x32_bf16 v[162:165], v[30:33], v[142:145], v[162:165]
	v_mfma_f32_16x16x32_bf16 v[158:161], v[102:105], v[142:145], v[158:161]
	v_mfma_f32_16x16x32_bf16 v[138:141], v[30:33], v[150:153], v[138:141]
	v_mfma_f32_16x16x32_bf16 v[134:137], v[102:105], v[150:153], v[134:137]
	v_mfma_f32_16x16x32_bf16 v[126:129], v[30:33], v[166:169], v[126:129]
	v_mfma_f32_16x16x32_bf16 v[122:125], v[102:105], v[166:169], v[122:125]
	v_mfma_f32_16x16x32_bf16 v[118:121], v[30:33], v[174:177], v[118:121]
	v_mfma_f32_16x16x32_bf16 v[114:117], v[102:105], v[174:177], v[114:117]
	s_barrier
	s_add_i32 s60, 0, 0x14000
	s_add_i32 s58, s58, s21
	s_add_u32 s100, s4, s6
	s_addc_u32 s101, s5, s7
	s_mov_b32 m0, s58
	s_nop 0
	global_load_lds_dwordx4 v0, s[4:5]
	s_add_i32 m0, s58, 0x2000
	s_nop 0
	global_load_lds_dwordx4 v188, s[4:5]
	ds_read_b128 v[184:187], v250 offset:16384
	ds_read_b128 v[200:203], v250 offset:17408
	ds_read_b128 v[204:207], v250 offset:18432
	ds_read_b128 v[208:211], v250 offset:19456
	s_barrier
	s_waitcnt lgkmcnt(0)
	v_mfma_f32_16x16x32_bf16 v[70:73], v[184:187], v[130:133], v[70:73]
	v_mfma_f32_16x16x32_bf16 v[66:69], v[204:207], v[130:133], v[66:69]
	v_mfma_f32_16x16x32_bf16 v[62:65], v[184:187], v[146:149], v[62:65]
	v_mfma_f32_16x16x32_bf16 v[58:61], v[204:207], v[146:149], v[58:61]
	v_mfma_f32_16x16x32_bf16 v[54:57], v[184:187], v[154:157], v[54:57]
	v_mfma_f32_16x16x32_bf16 v[50:53], v[204:207], v[154:157], v[50:53]
	v_mfma_f32_16x16x32_bf16 v[46:49], v[184:187], v[170:173], v[46:49]
	v_mfma_f32_16x16x32_bf16 v[42:45], v[204:207], v[170:173], v[42:45]
	v_mfma_f32_16x16x32_bf16 v[70:73], v[200:203], v[142:145], v[70:73]
	v_mfma_f32_16x16x32_bf16 v[66:69], v[208:211], v[142:145], v[66:69]
	v_mfma_f32_16x16x32_bf16 v[62:65], v[200:203], v[150:153], v[62:65]
	v_mfma_f32_16x16x32_bf16 v[58:61], v[208:211], v[150:153], v[58:61]
	v_mfma_f32_16x16x32_bf16 v[54:57], v[200:203], v[166:169], v[54:57]
	v_mfma_f32_16x16x32_bf16 v[50:53], v[208:211], v[166:169], v[50:53]
	v_mfma_f32_16x16x32_bf16 v[46:49], v[200:203], v[174:177], v[46:49]
	v_mfma_f32_16x16x32_bf16 v[42:45], v[208:211], v[174:177], v[42:45]
	s_mov_b32 m0, s22
	s_barrier
	global_load_lds_dwordx4 v192, s[16:17]
	s_mov_b32 m0, s23
	s_nop 0
	global_load_lds_dwordx4 v190, s[16:17]
	ds_read_b128 v[130:133], v247 offset:16384
	ds_read_b128 v[142:145], v247 offset:17408
	ds_read_b128 v[146:149], v247 offset:18432
	ds_read_b128 v[150:153], v247 offset:19456
	ds_read_b128 v[154:157], v247 offset:20480
	ds_read_b128 v[166:169], v247 offset:21504
	ds_read_b128 v[170:173], v247 offset:22528
	ds_read_b128 v[174:177], v247 offset:23552
	s_barrier
	s_waitcnt lgkmcnt(0)
	v_mfma_f32_16x16x32_bf16 v[110:113], v[26:29], v[130:133], v[110:113]
	v_mfma_f32_16x16x32_bf16 v[106:109], v[98:101], v[130:133], v[106:109]
	v_mfma_f32_16x16x32_bf16 v[94:97], v[26:29], v[146:149], v[94:97]
	v_mfma_f32_16x16x32_bf16 v[90:93], v[98:101], v[146:149], v[90:93]
	v_mfma_f32_16x16x32_bf16 v[86:89], v[26:29], v[154:157], v[86:89]
	v_mfma_f32_16x16x32_bf16 v[82:85], v[98:101], v[154:157], v[82:85]
	v_mfma_f32_16x16x32_bf16 v[26:29], v[26:29], v[170:173], v[78:81]
	v_mfma_f32_16x16x32_bf16 v[110:113], v[30:33], v[142:145], v[110:113]
	v_mfma_f32_16x16x32_bf16 v[106:109], v[102:105], v[142:145], v[106:109]
	v_mfma_f32_16x16x32_bf16 v[94:97], v[30:33], v[150:153], v[94:97]
	v_mfma_f32_16x16x32_bf16 v[90:93], v[102:105], v[150:153], v[90:93]
	v_mfma_f32_16x16x32_bf16 v[86:89], v[30:33], v[166:169], v[86:89]
	v_mfma_f32_16x16x32_bf16 v[82:85], v[102:105], v[166:169], v[82:85]
	v_mfma_f32_16x16x32_bf16 v[26:29], v[30:33], v[174:177], v[26:29]
	v_mfma_f32_16x16x32_bf16 v[30:33], v[98:101], v[170:173], v[74:77]
	v_mfma_f32_16x16x32_bf16 v[30:33], v[102:105], v[174:177], v[30:33]
	s_barrier
	s_add_u32 s58, s4, 0x100000
	s_addc_u32 s59, s5, 0
	s_add_i32 s60, s60, s21
	s_mov_b32 m0, s60
	s_nop 0
	global_load_lds_dwordx4 v0, s[58:59]
	s_add_i32 m0, s60, 0x2000
	s_nop 0
	global_load_lds_dwordx4 v188, s[58:59]
	s_waitcnt vmcnt(6)
	s_barrier
; #define PG8_STAGE(bufoff, gbase, voff) do { _Pragma("unroll") for (int _i = 0; _i < 2; ++_i) \
;         __builtin_amdgcn_global_load_lds((const unsigned*)((const char*)(gbase) + (voff)[_i]), (LAS unsigned*)(lds + (bufoff) + ldsw + _i * 8192), 16, 0, 0); } while (0)
; #define PG8_LDA(dst, b, h) do { _Pragma("unroll") for (int m = 0; m < 4; ++m) _Pragma("unroll") for (int k = 0; k < 2; ++k) dst[m][k] = *(const LAS bf16x8*)(lds + PG8_SA(b, h) + aoff + m * 2048 + k * 1024); } while (0)
; #define PG8_LDB(dst, b, h) do { _Pragma("unroll") for (int n = 0; n < 2; ++n) _Pragma("unroll") for (int k = 0; k < 2; ++k) dst[n][k] = *(const LAS bf16x8*)(lds + PG8_SB(b, h) + boff + n * 2048 + k * 1024); } while (0)
; #define PG8_MMA(ai, bj, At, Bt) do { __builtin_amdgcn_s_setprio(1); _Pragma("unroll") for (int m = 0; m < 4; ++m) _Pragma("unroll") for (int n = 0; n < 2; ++n) _Pragma("unroll") for (int k = 0; k < 2; ++k) \
;         acc[ai][bj][m][n] = __builtin_amdgcn_mfma_f32_16x16x32_bf16(Bt[n][k], At[m][k], acc[ai][bj][m][n], 0, 0, 0); __builtin_amdgcn_s_setprio(0); } while (0)
; #define PG8_WAIT_V(n) asm volatile("s_waitcnt vmcnt(" #n ")" ::: "memory")
; #define PG8_WAIT_L(n) asm volatile("s_waitcnt lgkmcnt(" #n ")" ::: "memory")
; #define PG8_BAR __builtin_amdgcn_s_barrier()
; #define PG8_SCHED __builtin_amdgcn_sched_barrier(0)
; template <class Epi>
; __device__ __forceinline__ void gemm_phase(LAS unsigned char* lds, const Gemm g, const StaticOrder& S, const Epi& E) {
;     ...
;             PG8_WAIT_V(6); PG8_BAR; PG8_MMA(1, 1, At, B1); PG8_BAR;
;             PG8_LDB(B0, 1, 0); PG8_SCHED; PG8_LDA(At, 1, 0); PG8_STAGE(PG8_SA(0, 1), a2 + hstepA, voffA);
;             PG8_WAIT_L(8); PG8_BAR; PG8_WAIT_L(0); PG8_MMA(0, 0, At, B0); PG8_BAR; PG8_SCHED;
;             PG8_LDB(B1, 1, 1); PG8_STAGE(PG8_SB(1, 0), b3, voffB);
;             PG8_BAR; PG8_WAIT_L(0); PG8_MMA(0, 1, At, B1); PG8_BAR;
;             PG8_LDA(At, 1, 1); PG8_STAGE(PG8_SA(1, 0), a3, voffA);
;             PG8_BAR; PG8_WAIT_L(0); PG8_MMA(1, 0, At, B0); PG8_BAR; PG8_SCHED;
	v_mfma_f32_16x16x32_bf16 v[38:41], v[184:187], v[130:133], v[38:41]
	v_mfma_f32_16x16x32_bf16 v[34:37], v[204:207], v[130:133], v[34:37]
	v_mfma_f32_16x16x32_bf16 v[22:25], v[184:187], v[146:149], v[22:25]
	v_mfma_f32_16x16x32_bf16 v[18:21], v[204:207], v[146:149], v[18:21]
	v_mfma_f32_16x16x32_bf16 v[14:17], v[184:187], v[154:157], v[14:17]
	v_mfma_f32_16x16x32_bf16 v[10:13], v[204:207], v[154:157], v[10:13]
	v_mfma_f32_16x16x32_bf16 v[6:9], v[184:187], v[170:173], v[6:9]
	v_mfma_f32_16x16x32_bf16 v[2:5], v[204:207], v[170:173], v[2:5]
	v_mfma_f32_16x16x32_bf16 v[38:41], v[200:203], v[142:145], v[38:41]
	v_mfma_f32_16x16x32_bf16 v[34:37], v[208:211], v[142:145], v[34:37]
	v_mfma_f32_16x16x32_bf16 v[22:25], v[200:203], v[150:153], v[22:25]
	v_mfma_f32_16x16x32_bf16 v[18:21], v[208:211], v[150:153], v[18:21]
	v_mfma_f32_16x16x32_bf16 v[14:17], v[200:203], v[166:169], v[14:17]
	v_mfma_f32_16x16x32_bf16 v[10:13], v[208:211], v[166:169], v[10:13]
	v_mfma_f32_16x16x32_bf16 v[6:9], v[200:203], v[174:177], v[6:9]
	v_mfma_f32_16x16x32_bf16 v[2:5], v[208:211], v[174:177], v[2:5]
	s_add_i32 s58, 0, 0x18000
	s_barrier
	s_add_u32 s16, s16, 0x1000
	s_addc_u32 s17, s17, 0
	s_mov_b32 m0, s24
	s_nop 0
	global_load_lds_dwordx4 v192, s[16:17]
	s_mov_b32 m0, s25
	s_nop 0
	global_load_lds_dwordx4 v190, s[16:17]
	ds_read_b128 v[74:77], v250 offset:32768
	ds_read_b128 v[78:81], v250 offset:33792
	ds_read_b128 v[98:101], v250 offset:34816
	ds_read_b128 v[102:105], v250 offset:35840
	ds_read_b128 v[130:133], v247 offset:32768
	ds_read_b128 v[142:145], v247 offset:33792
	ds_read_b128 v[146:149], v247 offset:34816
	ds_read_b128 v[150:153], v247 offset:35840
	ds_read_b128 v[154:157], v247 offset:36864
	ds_read_b128 v[166:169], v247 offset:37888
	ds_read_b128 v[170:173], v247 offset:38912
	ds_read_b128 v[174:177], v247 offset:39936
	s_waitcnt lgkmcnt(8)
	s_barrier
	s_waitcnt lgkmcnt(0)
	v_mfma_f32_16x16x32_bf16 v[162:165], v[74:77], v[130:133], v[162:165]
	v_mfma_f32_16x16x32_bf16 v[158:161], v[98:101], v[130:133], v[158:161]
	v_mfma_f32_16x16x32_bf16 v[138:141], v[74:77], v[146:149], v[138:141]
	v_mfma_f32_16x16x32_bf16 v[134:137], v[98:101], v[146:149], v[134:137]
	v_mfma_f32_16x16x32_bf16 v[126:129], v[74:77], v[154:157], v[126:129]
	v_mfma_f32_16x16x32_bf16 v[122:125], v[98:101], v[154:157], v[122:125]
	v_mfma_f32_16x16x32_bf16 v[118:121], v[74:77], v[170:173], v[118:121]
	v_mfma_f32_16x16x32_bf16 v[114:117], v[98:101], v[170:173], v[114:117]
	v_mfma_f32_16x16x32_bf16 v[162:165], v[78:81], v[142:145], v[162:165]
	v_mfma_f32_16x16x32_bf16 v[158:161], v[102:105], v[142:145], v[158:161]
	v_mfma_f32_16x16x32_bf16 v[138:141], v[78:81], v[150:153], v[138:141]
	v_mfma_f32_16x16x32_bf16 v[134:137], v[102:105], v[150:153], v[134:137]
	v_mfma_f32_16x16x32_bf16 v[126:129], v[78:81], v[166:169], v[126:129]
	v_mfma_f32_16x16x32_bf16 v[122:125], v[102:105], v[166:169], v[122:125]
	v_mfma_f32_16x16x32_bf16 v[118:121], v[78:81], v[174:177], v[118:121]
	v_mfma_f32_16x16x32_bf16 v[114:117], v[102:105], v[174:177], v[114:117]
	s_barrier
	s_add_i32 s16, 0, 0x1c000
	s_add_i32 s17, s58, s21
	s_mov_b32 m0, s17
	s_nop 0
	global_load_lds_dwordx4 v0, s[100:101]
	s_add_i32 m0, s17, 0x2000
	s_nop 0
	global_load_lds_dwordx4 v188, s[100:101]
	ds_read_b128 v[184:187], v250 offset:49152
	ds_read_b128 v[200:203], v250 offset:50176
	ds_read_b128 v[204:207], v250 offset:51200
	ds_read_b128 v[208:211], v250 offset:52224
	s_barrier
	s_waitcnt lgkmcnt(0)
	v_mfma_f32_16x16x32_bf16 v[70:73], v[184:187], v[130:133], v[70:73]
	v_mfma_f32_16x16x32_bf16 v[66:69], v[204:207], v[130:133], v[66:69]
	v_mfma_f32_16x16x32_bf16 v[62:65], v[184:187], v[146:149], v[62:65]
	v_mfma_f32_16x16x32_bf16 v[58:61], v[204:207], v[146:149], v[58:61]
	v_mfma_f32_16x16x32_bf16 v[54:57], v[184:187], v[154:157], v[54:57]
	v_mfma_f32_16x16x32_bf16 v[50:53], v[204:207], v[154:157], v[50:53]
	v_mfma_f32_16x16x32_bf16 v[46:49], v[184:187], v[170:173], v[46:49]
	v_mfma_f32_16x16x32_bf16 v[42:45], v[204:207], v[170:173], v[42:45]
	v_mfma_f32_16x16x32_bf16 v[70:73], v[200:203], v[142:145], v[70:73]
	v_mfma_f32_16x16x32_bf16 v[66:69], v[208:211], v[142:145], v[66:69]
	v_mfma_f32_16x16x32_bf16 v[62:65], v[200:203], v[150:153], v[62:65]
	v_mfma_f32_16x16x32_bf16 v[58:61], v[208:211], v[150:153], v[58:61]
	v_mfma_f32_16x16x32_bf16 v[54:57], v[200:203], v[166:169], v[54:57]
	v_mfma_f32_16x16x32_bf16 v[50:53], v[208:211], v[166:169], v[50:53]
	v_mfma_f32_16x16x32_bf16 v[46:49], v[200:203], v[174:177], v[46:49]
	v_mfma_f32_16x16x32_bf16 v[42:45], v[208:211], v[174:177], v[42:45]
	s_mov_b32 m0, s26
	s_barrier
	global_load_lds_dwordx4 v192, s[14:15]
	s_mov_b32 m0, s27
	s_nop 0
	global_load_lds_dwordx4 v190, s[14:15]
	ds_read_b128 v[130:133], v247 offset:49152
	ds_read_b128 v[142:145], v247 offset:50176
	ds_read_b128 v[146:149], v247 offset:51200
	ds_read_b128 v[150:153], v247 offset:52224
	ds_read_b128 v[154:157], v247 offset:53248
	ds_read_b128 v[166:169], v247 offset:54272
	ds_read_b128 v[170:173], v247 offset:55296
	ds_read_b128 v[174:177], v247 offset:56320
	s_barrier
	s_waitcnt lgkmcnt(0)
	v_mfma_f32_16x16x32_bf16 v[110:113], v[74:77], v[130:133], v[110:113]
	v_mfma_f32_16x16x32_bf16 v[94:97], v[74:77], v[146:149], v[94:97]
	v_mfma_f32_16x16x32_bf16 v[86:89], v[74:77], v[154:157], v[86:89]
	v_mfma_f32_16x16x32_bf16 v[26:29], v[74:77], v[170:173], v[26:29]
	v_mfma_f32_16x16x32_bf16 v[110:113], v[78:81], v[142:145], v[110:113]
	v_mfma_f32_16x16x32_bf16 v[106:109], v[98:101], v[130:133], v[106:109]
	v_mfma_f32_16x16x32_bf16 v[94:97], v[78:81], v[150:153], v[94:97]
	v_mfma_f32_16x16x32_bf16 v[90:93], v[98:101], v[146:149], v[90:93]
	v_mfma_f32_16x16x32_bf16 v[86:89], v[78:81], v[166:169], v[86:89]
	v_mfma_f32_16x16x32_bf16 v[82:85], v[98:101], v[154:157], v[82:85]
	v_mfma_f32_16x16x32_bf16 v[78:81], v[78:81], v[174:177], v[26:29]
	v_mfma_f32_16x16x32_bf16 v[26:29], v[98:101], v[170:173], v[30:33]
	v_mfma_f32_16x16x32_bf16 v[106:109], v[102:105], v[142:145], v[106:109]
	v_mfma_f32_16x16x32_bf16 v[90:93], v[102:105], v[150:153], v[90:93]
	v_mfma_f32_16x16x32_bf16 v[82:85], v[102:105], v[166:169], v[82:85]
	v_mfma_f32_16x16x32_bf16 v[74:77], v[102:105], v[174:177], v[26:29]
	s_barrier
; __device__ __forceinline__ unsigned cvt_pk_bf16(float lo, float hi) { unsigned r; asm volatile("v_cvt_pk_bf16_f32 %0, %1, %2" : "=v"(r) : "v"(lo), "v"(hi)); return r; }
; __device__ __forceinline__ float bf_lo(unsigned w) { return __uint_as_float(w << 16); }
; template <class Epi>
; __device__ __forceinline__ void gemm_phase(LAS unsigned char* lds, const Gemm g, const StaticOrder& S, const Epi& E) {
;     ...
;             PG8_STAGE(PG8_SB(1, 1), b3 + hstepB, voffB);
;             PG8_WAIT_V(6); PG8_BAR; PG8_MMA(1, 1, At, B1); PG8_BAR;
;         }
;         if constexpr (!Epi::AFTER_DRAIN) E(acc, cur, wr, wc, fr, fq, pre);
;     __device__ __forceinline__ void operator()(const f32x4 (&acc)[2][2][4][2], const Unit& u, int wr, int wc, int fr, int fq, const Pre&) const {
;         const int row0 = u.pm * BM + wr * 64 + fr, col0 = u.pn * BM + wc * 32 + 8 * fq;
;         f32x4 bs[2][2];
; #pragma unroll
;         for (int bj = 0; bj < 2; ++bj) { bs[bj][0] = *(const f32x4*)(bias + col0 + bj * HALF); bs[bj][1] = *(const f32x4*)(bias + col0 + bj * HALF + 4); }
; #pragma unroll
;         for (int bj = 0; bj < 2; ++bj) { const int c = col0 + bj * HALF;
; #pragma unroll
;             for (int ai = 0; ai < 2; ++ai) { u32x4 zv[4], gv[4];
; #pragma unroll
;                 for (int m = 0; m < 4; ++m) { const int r = row0 + ai * HALF + m * 16; zv[m] = *(const u32x4*)(Z + (size_t)r * DE2 + c); gv[m] = *(const u32x4*)(Gm + (size_t)(c >> 4) * GSTR + r * 16 + (c & 15)); }
; #pragma unroll
;                 for (int m = 0; m < 4; ++m) { const int r = row0 + ai * HALF + m * 16;
;                     const u32x4 zw = zv[m], gw = gv[m];
;                     const f32x4 a0 = acc[ai][bj][m][0] + bs[bj][0], a1 = acc[ai][bj][m][1] + bs[bj][1];
;                     u32x4 w;
;                     w.x = cvt_pk_bf16(glu_gate_f(bf_lo(gw.x), a0[0], bf_lo(zw.x)), glu_gate_f(bf_hi(gw.x), a0[1], bf_hi(zw.x)));
;                     w.y = cvt_pk_bf16(glu_gate_f(bf_lo(gw.y), a0[2], bf_lo(zw.y)), glu_gate_f(bf_hi(gw.y), a0[3], bf_hi(zw.y)));
;                     w.z = cvt_pk_bf16(glu_gate_f(bf_lo(gw.z), a1[0], bf_lo(zw.z)), glu_gate_f(bf_hi(gw.z), a1[1], bf_hi(zw.z)));
;                     w.w = cvt_pk_bf16(glu_gate_f(bf_lo(gw.w), a1[2], bf_lo(zw.w)), glu_gate_f(bf_hi(gw.w), a1[3], bf_hi(zw.w)));
;                     *(u32x4*)(O + (size_t)r * DE + c) = w; } } }
	s_add_u32 s4, s4, 0x100080
	s_addc_u32 s5, s5, 0
	s_add_i32 s14, s16, s21
	s_mov_b32 m0, s14
	s_nop 0
	global_load_lds_dwordx4 v0, s[4:5]
	s_add_i32 m0, s14, 0x2000
	s_nop 0
	global_load_lds_dwordx4 v188, s[4:5]
	s_waitcnt vmcnt(6)
	s_barrier
	v_mfma_f32_16x16x32_bf16 v[26:29], v[184:187], v[130:133], v[38:41]
	v_mfma_f32_16x16x32_bf16 v[38:41], v[200:203], v[142:145], v[26:29]
	v_mfma_f32_16x16x32_bf16 v[26:29], v[204:207], v[130:133], v[34:37]
	v_mfma_f32_16x16x32_bf16 v[22:25], v[184:187], v[146:149], v[22:25]
	v_mfma_f32_16x16x32_bf16 v[18:21], v[204:207], v[146:149], v[18:21]
	v_mfma_f32_16x16x32_bf16 v[14:17], v[184:187], v[154:157], v[14:17]
	v_mfma_f32_16x16x32_bf16 v[10:13], v[204:207], v[154:157], v[10:13]
	v_mfma_f32_16x16x32_bf16 v[6:9], v[184:187], v[170:173], v[6:9]
	v_mfma_f32_16x16x32_bf16 v[2:5], v[204:207], v[170:173], v[2:5]
	v_mfma_f32_16x16x32_bf16 v[34:37], v[208:211], v[142:145], v[26:29]
	v_mfma_f32_16x16x32_bf16 v[22:25], v[200:203], v[150:153], v[22:25]
	v_mfma_f32_16x16x32_bf16 v[18:21], v[208:211], v[150:153], v[18:21]
	v_mfma_f32_16x16x32_bf16 v[14:17], v[200:203], v[166:169], v[14:17]
	v_mfma_f32_16x16x32_bf16 v[10:13], v[208:211], v[166:169], v[10:13]
	v_mfma_f32_16x16x32_bf16 v[6:9], v[200:203], v[174:177], v[6:9]
	v_mfma_f32_16x16x32_bf16 v[2:5], v[208:211], v[174:177], v[2:5]
	s_add_i32 s57, s57, 2
	s_add_u32 s51, s51, 0x100
	s_addc_u32 s56, s56, 0
	s_add_u32 s8, s8, 0x208800
	s_addc_u32 s9, s9, 0
	s_cmp_gt_u32 s57, 61
	s_barrier
	s_cbranch_scc0 .LBB0_796
	v_lshl_or_b32 v200, s36, 8, v246
	v_ashrrev_i32_e32 v201, 31, v200
	v_lshl_add_u32 v224, s35, 8, v244
	v_lshlrev_b64 v[204:205], 1, v[200:201]
	v_ashrrev_i32_e32 v225, 31, v224
	v_ashrrev_i32_e32 v130, 4, v200
	v_lshl_add_u64 v[222:223], s[46:47], 0, v[204:205]
	v_lshlrev_b64 v[202:203], 14, v[224:225]
	v_lshl_add_u64 v[30:31], v[200:201], 2, s[10:11]
	v_mad_i64_i32 v[220:221], s[4:5], v130, s94, v[194:195]
	v_lshl_add_u64 v[130:131], v[222:223], 0, v[202:203]
	global_load_dwordx4 v[98:101], v[30:31], off offset:16
	global_load_dwordx4 v[102:105], v[30:31], off
	global_load_dwordx4 v[26:29], v[30:31], off offset:528
	s_nop 0
	global_load_dwordx4 v[30:33], v[30:31], off offset:512
	v_or_b32_e32 v226, 48, v224
	global_load_dwordx4 v[170:173], v[130:131], off
	v_lshlrev_b32_e32 v142, 4, v226
	v_ashrrev_i32_e32 v143, 31, v142
	v_lshlrev_b64 v[218:219], 1, v[142:143]
	v_lshl_add_u64 v[142:143], v[220:221], 0, v[218:219]
	global_load_dwordx4 v[142:145], v[142:143], off
	v_lshlrev_b32_e32 v130, 4, v224
	v_ashrrev_i32_e32 v131, 31, v130
	v_lshlrev_b64 v[206:207], 1, v[130:131]
	v_lshl_add_u64 v[130:131], v[220:221], 0, v[206:207]
	global_load_dwordx4 v[174:177], v[130:131], off
	v_or_b32_e32 v230, 16, v224
	v_ashrrev_i32_e32 v231, 31, v230
	v_lshlrev_b64 v[210:211], 14, v[230:231]
	v_lshl_add_u64 v[130:131], v[222:223], 0, v[210:211]
	global_load_dwordx4 v[154:157], v[130:131], off
	v_lshlrev_b32_e32 v130, 4, v230
	v_ashrrev_i32_e32 v131, 31, v130
	v_or_b32_e32 v228, 32, v224
	v_lshlrev_b64 v[208:209], 1, v[130:131]
	v_ashrrev_i32_e32 v229, 31, v228
	v_lshl_add_u64 v[130:131], v[220:221], 0, v[208:209]
	v_lshlrev_b64 v[214:215], 14, v[228:229]
	global_load_dwordx4 v[166:169], v[130:131], off
	v_lshl_add_u64 v[130:131], v[222:223], 0, v[214:215]
	global_load_dwordx4 v[146:149], v[130:131], off
	v_lshlrev_b32_e32 v130, 4, v228
	v_ashrrev_i32_e32 v131, 31, v130
	v_lshlrev_b64 v[212:213], 1, v[130:131]
	v_ashrrev_i32_e32 v227, 31, v226
	v_lshl_add_u64 v[130:131], v[220:221], 0, v[212:213]
	v_lshlrev_b64 v[216:217], 14, v[226:227]
	global_load_dwordx4 v[150:153], v[130:131], off
	v_lshl_add_u64 v[130:131], v[222:223], 0, v[216:217]
	global_load_dwordx4 v[130:133], v[130:131], off
	s_and_b64 vcc, exec, s[40:41]
	s_mov_b32 s35, s50
	s_mov_b32 s36, s48
	s_mov_b64 s[8:9], s[54:55]
	s_mov_b64 s[14:15], s[52:53]
	s_waitcnt vmcnt(0)
	v_pk_add_f32 v[134:135], v[134:135], v[98:99]
	v_pk_add_f32 v[184:185], v[162:163], v[102:103]
	v_pk_add_f32 v[162:163], v[160:161], v[100:101]
	v_pk_add_f32 v[160:161], v[158:159], v[98:99]
	v_mul_f32_e32 v158, 0xbfb8aa3b, v184
	v_lshlrev_b32_e32 v186, 16, v170
	v_mul_f32_e32 v159, 0xbfb8aa3b, v186
	v_exp_f32_e32 v158, v158
	v_exp_f32_e32 v159, v159
	v_and_b32_e32 v170, 0xffff0000, v170
	v_pk_add_f32 v[164:165], v[164:165], v[104:105]
	v_mul_f32_e32 v160, 0xbfb8aa3b, v160
	v_pk_add_f32 v[158:159], v[158:159], 1.0 op_sel_hi:[1,0]
	v_mul_f32_e32 v164, 0xbfb8aa3b, v164
	v_mul_f32_e32 v158, v158, v159
	v_rcp_f32_e32 v158, v158
	v_lshlrev_b32_e32 v187, 16, v174
	v_mul_f32_e32 v184, v187, v186
	v_mul_f32_e32 v159, 0xbfb8aa3b, v170
	v_mul_f32_e32 v184, v184, v158
	v_mul_f32_e32 v158, 0xbfb8aa3b, v185
	v_exp_f32_e32 v158, v158
	v_exp_f32_e32 v159, v159
	v_and_b32_e32 v174, 0xffff0000, v174
	v_mul_f32_e32 v170, v174, v170
	v_mul_f32_e32 v162, 0xbfb8aa3b, v162
	v_pk_add_f32 v[158:159], v[158:159], 1.0 op_sel_hi:[1,0]
	v_pk_add_f32 v[138:139], v[138:139], v[102:103]
	v_mul_f32_e32 v158, v158, v159
	v_rcp_f32_e32 v158, v158
	v_lshlrev_b32_e32 v159, 16, v171
	v_and_b32_e32 v171, 0xffff0000, v171
	v_mul_f32_e32 v138, 0xbfb8aa3b, v138
	v_mul_f32_e32 v158, v170, v158
	v_cvt_pk_bf16_f32 v158, v184, v158
	v_exp_f32_e32 v184, v164
	v_mul_f32_e32 v164, 0xbfb8aa3b, v159
	v_exp_f32_e32 v185, v164
	v_lshlrev_b32_e32 v170, 16, v175
	v_mul_f32_e32 v159, v170, v159
	v_and_b32_e32 v170, 0xffff0000, v175
	v_pk_add_f32 v[184:185], v[184:185], 1.0 op_sel_hi:[1,0]
	v_mul_f32_e32 v170, v170, v171
	v_mul_f32_e32 v164, v184, v185
	v_rcp_f32_e32 v164, v164
	v_pk_add_f32 v[140:141], v[140:141], v[104:105]
	v_mul_f32_e32 v134, 0xbfb8aa3b, v134
	v_mul_f32_e32 v140, 0xbfb8aa3b, v140
; __device__ __forceinline__ unsigned cvt_pk_bf16(float lo, float hi) { unsigned r; asm volatile("v_cvt_pk_bf16_f32 %0, %1, %2" : "=v"(r) : "v"(lo), "v"(hi)); return r; }
; __device__ __forceinline__ float bf_lo(unsigned w) { return __uint_as_float(w << 16); }
; __device__ __forceinline__ float bf_hi(unsigned w) { return __uint_as_float(w & 0xffff0000u); }
; __device__ __forceinline__ float fast_rcp(float x) { return __builtin_amdgcn_rcpf(x); }
; __device__ __forceinline__ float glu_gate_f(float g, float v, float z) {
;     const float ev = __builtin_amdgcn_exp2f(v * -1.44269504f), ez = __builtin_amdgcn_exp2f(z * -1.44269504f);
;     return g * z * fast_rcp((1.0f + ev) * (1.0f + ez));
;     __device__ __forceinline__ void operator()(const f32x4 (&acc)[2][2][4][2], const Unit& u, int wr, int wc, int fr, int fq, const Pre&) const {
;     ...
;         for (int bj = 0; bj < 2; ++bj) { const int c = col0 + bj * HALF;
; #pragma unroll
;             for (int ai = 0; ai < 2; ++ai) { u32x4 zv[4], gv[4];
; #pragma unroll
;                 for (int m = 0; m < 4; ++m) { const int r = row0 + ai * HALF + m * 16; zv[m] = *(const u32x4*)(Z + (size_t)r * DE2 + c); gv[m] = *(const u32x4*)(Gm + (size_t)(c >> 4) * GSTR + r * 16 + (c & 15)); }
; #pragma unroll
;                 for (int m = 0; m < 4; ++m) { const int r = row0 + ai * HALF + m * 16;
;                     const u32x4 zw = zv[m], gw = gv[m];
;                     const f32x4 a0 = acc[ai][bj][m][0] + bs[bj][0], a1 = acc[ai][bj][m][1] + bs[bj][1];
;                     u32x4 w;
;                     w.x = cvt_pk_bf16(glu_gate_f(bf_lo(gw.x), a0[0], bf_lo(zw.x)), glu_gate_f(bf_hi(gw.x), a0[1], bf_hi(zw.x)));
;                     w.y = cvt_pk_bf16(glu_gate_f(bf_lo(gw.y), a0[2], bf_lo(zw.y)), glu_gate_f(bf_hi(gw.y), a0[3], bf_hi(zw.y)));
;                     w.z = cvt_pk_bf16(glu_gate_f(bf_lo(gw.z), a1[0], bf_lo(zw.z)), glu_gate_f(bf_hi(gw.z), a1[1], bf_hi(zw.z)));
;                     w.w = cvt_pk_bf16(glu_gate_f(bf_lo(gw.w), a1[2], bf_lo(zw.w)), glu_gate_f(bf_hi(gw.w), a1[3], bf_hi(zw.w)));
;                     *(u32x4*)(O + (size_t)r * DE + c) = w; } } }
	v_mul_f32_e32 v159, v159, v164
	v_mul_f32_e32 v164, 0xbfb8aa3b, v165
	v_mul_f32_e32 v165, 0xbfb8aa3b, v171
	v_exp_f32_e32 v164, v164
	v_exp_f32_e32 v165, v165
	v_lshlrev_b32_e32 v171, 16, v176
	v_pk_add_f32 v[136:137], v[136:137], v[100:101]
	v_pk_add_f32 v[126:127], v[126:127], v[102:103]
	v_pk_add_f32 v[164:165], v[164:165], 1.0 op_sel_hi:[1,0]
	v_mul_f32_e32 v126, 0xbfb8aa3b, v126
	v_mul_f32_e32 v164, v164, v165
	v_rcp_f32_e32 v164, v164
	v_pk_add_f32 v[128:129], v[128:129], v[104:105]
	v_pk_add_f32 v[122:123], v[122:123], v[98:99]
	v_mul_f32_e32 v128, 0xbfb8aa3b, v128
	v_mul_f32_e32 v164, v170, v164
	v_lshlrev_b32_e32 v170, 16, v172
	v_cvt_pk_bf16_f32 v159, v159, v164
	v_exp_f32_e32 v164, v160
	v_mul_f32_e32 v160, 0xbfb8aa3b, v170
	v_exp_f32_e32 v165, v160
	v_mul_f32_e32 v160, v171, v170
	v_and_b32_e32 v170, 0xffff0000, v172
	v_mul_f32_e32 v122, 0xbfb8aa3b, v122
	v_pk_add_f32 v[164:165], v[164:165], 1.0 op_sel_hi:[1,0]
	v_pk_add_f32 v[124:125], v[124:125], v[100:101]
	v_mul_f32_e32 v164, v164, v165
	v_rcp_f32_e32 v164, v164
	v_and_b32_e32 v165, 0xffff0000, v176
	v_mul_f32_e32 v165, v165, v170
	v_pk_add_f32 v[118:119], v[118:119], v[102:103]
	v_mul_f32_e32 v164, v160, v164
	v_mul_f32_e32 v160, 0xbfb8aa3b, v161
	v_mul_f32_e32 v161, 0xbfb8aa3b, v170
	v_exp_f32_e32 v160, v160
	v_exp_f32_e32 v161, v161
	v_lshlrev_b32_e32 v170, 16, v177
	v_mul_f32_e32 v118, 0xbfb8aa3b, v118
	v_pk_add_f32 v[120:121], v[120:121], v[104:105]
	v_pk_add_f32 v[160:161], v[160:161], 1.0 op_sel_hi:[1,0]
	v_mul_f32_e32 v120, 0xbfb8aa3b, v120
	v_mul_f32_e32 v160, v160, v161
	v_rcp_f32_e32 v160, v160
	v_lshlrev_b32_e32 v161, 16, v173
	v_pk_add_f32 v[114:115], v[114:115], v[98:99]
	v_pk_add_f32 v[116:117], v[116:117], v[100:101]
	v_mul_f32_e32 v160, v165, v160
	v_cvt_pk_bf16_f32 v160, v164, v160
	v_exp_f32_e32 v164, v162
	v_mul_f32_e32 v162, 0xbfb8aa3b, v161
	v_exp_f32_e32 v165, v162
	v_mul_f32_e32 v161, v170, v161
	v_mul_f32_e32 v114, 0xbfb8aa3b, v114
	v_add_u32_e32 v176, 0x80, v224
	v_pk_add_f32 v[164:165], v[164:165], 1.0 op_sel_hi:[1,0]
	v_add_u32_e32 v170, 0xb0, v224
	v_mul_f32_e32 v162, v164, v165
	v_rcp_f32_e32 v162, v162
	v_and_b32_e32 v165, 0xffff0000, v173
	v_and_b32_e32 v164, 0xffff0000, v177
	v_mul_f32_e32 v164, v164, v165
	v_mul_f32_e32 v161, v161, v162
	v_mul_f32_e32 v162, 0xbfb8aa3b, v163
	v_mul_f32_e32 v163, 0xbfb8aa3b, v165
	v_exp_f32_e32 v162, v162
	v_exp_f32_e32 v163, v163
	v_ashrrev_i32_e32 v177, 31, v176
	v_pk_add_f32 v[110:111], v[110:111], v[102:103]
	v_add_u32_e32 v174, 0x90, v224
	v_pk_add_f32 v[162:163], v[162:163], 1.0 op_sel_hi:[1,0]
	v_mul_f32_e32 v110, 0xbfb8aa3b, v110
	v_mul_f32_e32 v162, v162, v163
	v_rcp_f32_e32 v162, v162
	v_exp_f32_e32 v184, v110
	v_ashrrev_i32_e32 v175, 31, v174
	v_add_u32_e32 v172, 0xa0, v224
	v_mul_f32_e32 v162, v164, v162
	v_cvt_pk_bf16_f32 v161, v161, v162
	v_lshlrev_b64 v[162:163], 13, v[224:225]
	v_lshl_add_u64 v[162:163], s[44:45], 0, v[162:163]
	v_lshl_add_u64 v[162:163], v[162:163], 0, v[204:205]
	global_store_dwordx4 v[162:163], v[158:161], off
	v_ashrrev_i32_e32 v173, 31, v172
	v_ashrrev_i32_e32 v171, 31, v170
	v_lshlrev_b32_e32 v160, 16, v154
	v_exp_f32_e32 v158, v138
	v_mul_f32_e32 v138, 0xbfb8aa3b, v160
	v_exp_f32_e32 v159, v138
	v_lshlrev_b32_e32 v161, 16, v166
	v_mul_f32_e32 v138, v161, v160
	v_and_b32_e32 v154, 0xffff0000, v154
	v_pk_add_f32 v[158:159], v[158:159], 1.0 op_sel_hi:[1,0]
	v_lshlrev_b64 v[160:161], 14, v[172:173]
	v_mul_f32_e32 v158, v158, v159
	v_rcp_f32_e32 v158, v158
	v_and_b32_e32 v159, 0xffff0000, v166
	v_pk_add_f32 v[112:113], v[112:113], v[104:105]
	v_pk_add_f32 v[106:107], v[106:107], v[98:99]
	v_mul_f32_e32 v158, v138, v158
	v_mul_f32_e32 v138, 0xbfb8aa3b, v139
	v_mul_f32_e32 v139, 0xbfb8aa3b, v154
	v_exp_f32_e32 v138, v138
	v_exp_f32_e32 v139, v139
	v_mul_f32_e32 v154, v159, v154
	v_mul_f32_e32 v112, 0xbfb8aa3b, v112
	v_mul_f32_e32 v106, 0xbfb8aa3b, v106
	v_pk_add_f32 v[138:139], v[138:139], 1.0 op_sel_hi:[1,0]
	v_pk_add_f32 v[108:109], v[108:109], v[100:101]
	v_mul_f32_e32 v138, v138, v139
	v_rcp_f32_e32 v138, v138
	v_lshlrev_b32_e32 v139, 16, v155
	v_and_b32_e32 v155, 0xffff0000, v155
	v_pk_add_f32 v[94:95], v[94:95], v[102:103]
	v_mul_f32_e32 v138, v154, v138
	v_cvt_pk_bf16_f32 v138, v158, v138
	v_exp_f32_e32 v158, v140
	v_mul_f32_e32 v140, 0xbfb8aa3b, v139
	v_exp_f32_e32 v159, v140
	v_lshlrev_b32_e32 v154, 16, v167
	v_mul_f32_e32 v139, v154, v139
	v_and_b32_e32 v154, 0xffff0000, v167
	v_pk_add_f32 v[158:159], v[158:159], 1.0 op_sel_hi:[1,0]
	v_mul_f32_e32 v154, v154, v155
	v_mul_f32_e32 v140, v158, v159
	v_rcp_f32_e32 v140, v140
	v_lshlrev_b64 v[166:167], 14, v[170:171]
	v_mul_f32_e32 v94, 0xbfb8aa3b, v94
	v_pk_add_f32 v[96:97], v[96:97], v[104:105]
	v_mul_f32_e32 v139, v139, v140
	v_mul_f32_e32 v140, 0xbfb8aa3b, v141
	v_mul_f32_e32 v141, 0xbfb8aa3b, v155
	v_exp_f32_e32 v140, v140
	v_exp_f32_e32 v141, v141
	v_lshlrev_b32_e32 v155, 16, v168
	v_mul_f32_e32 v96, 0xbfb8aa3b, v96
	v_pk_add_f32 v[90:91], v[90:91], v[98:99]
	v_pk_add_f32 v[140:141], v[140:141], 1.0 op_sel_hi:[1,0]
	v_mul_f32_e32 v90, 0xbfb8aa3b, v90
	v_mul_f32_e32 v140, v140, v141
	v_rcp_f32_e32 v140, v140
	v_pk_add_f32 v[92:93], v[92:93], v[100:101]
	v_pk_add_f32 v[86:87], v[86:87], v[102:103]
	v_pk_add_f32 v[88:89], v[88:89], v[104:105]
	v_mul_f32_e32 v140, v154, v140
	v_lshlrev_b32_e32 v154, 16, v156
	v_cvt_pk_bf16_f32 v139, v139, v140
	v_exp_f32_e32 v140, v134
	v_mul_f32_e32 v134, 0xbfb8aa3b, v154
	v_exp_f32_e32 v141, v134
	v_mul_f32_e32 v134, v155, v154
	v_and_b32_e32 v154, 0xffff0000, v156
	v_mul_f32_e32 v86, 0xbfb8aa3b, v86
	v_pk_add_f32 v[140:141], v[140:141], 1.0 op_sel_hi:[1,0]
	v_mul_f32_e32 v88, 0xbfb8aa3b, v88
; __device__ __forceinline__ unsigned cvt_pk_bf16(float lo, float hi) { unsigned r; asm volatile("v_cvt_pk_bf16_f32 %0, %1, %2" : "=v"(r) : "v"(lo), "v"(hi)); return r; }
; __device__ __forceinline__ float bf_lo(unsigned w) { return __uint_as_float(w << 16); }
; __device__ __forceinline__ float bf_hi(unsigned w) { return __uint_as_float(w & 0xffff0000u); }
; __device__ __forceinline__ float fast_rcp(float x) { return __builtin_amdgcn_rcpf(x); }
; __device__ __forceinline__ float glu_gate_f(float g, float v, float z) {
;     const float ev = __builtin_amdgcn_exp2f(v * -1.44269504f), ez = __builtin_amdgcn_exp2f(z * -1.44269504f);
;     return g * z * fast_rcp((1.0f + ev) * (1.0f + ez));
;     __device__ __forceinline__ void operator()(const f32x4 (&acc)[2][2][4][2], const Unit& u, int wr, int wc, int fr, int fq, const Pre&) const {
;     ...
;         for (int bj = 0; bj < 2; ++bj) { const int c = col0 + bj * HALF;
; #pragma unroll
;             for (int ai = 0; ai < 2; ++ai) { u32x4 zv[4], gv[4];
; #pragma unroll
;                 for (int m = 0; m < 4; ++m) { const int r = row0 + ai * HALF + m * 16; zv[m] = *(const u32x4*)(Z + (size_t)r * DE2 + c); gv[m] = *(const u32x4*)(Gm + (size_t)(c >> 4) * GSTR + r * 16 + (c & 15)); }
; #pragma unroll
;                 for (int m = 0; m < 4; ++m) { const int r = row0 + ai * HALF + m * 16;
;                     const u32x4 zw = zv[m], gw = gv[m];
;                     const f32x4 a0 = acc[ai][bj][m][0] + bs[bj][0], a1 = acc[ai][bj][m][1] + bs[bj][1];
;                     u32x4 w;
;                     w.x = cvt_pk_bf16(glu_gate_f(bf_lo(gw.x), a0[0], bf_lo(zw.x)), glu_gate_f(bf_hi(gw.x), a0[1], bf_hi(zw.x)));
;                     w.y = cvt_pk_bf16(glu_gate_f(bf_lo(gw.y), a0[2], bf_lo(zw.y)), glu_gate_f(bf_hi(gw.y), a0[3], bf_hi(zw.y)));
;                     w.z = cvt_pk_bf16(glu_gate_f(bf_lo(gw.z), a1[0], bf_lo(zw.z)), glu_gate_f(bf_hi(gw.z), a1[1], bf_hi(zw.z)));
;                     w.w = cvt_pk_bf16(glu_gate_f(bf_lo(gw.w), a1[2], bf_lo(zw.w)), glu_gate_f(bf_hi(gw.w), a1[3], bf_hi(zw.w)));
;                     *(u32x4*)(O + (size_t)r * DE + c) = w; } } }
	v_mul_f32_e32 v140, v140, v141
	v_rcp_f32_e32 v140, v140
	v_and_b32_e32 v141, 0xffff0000, v168
	v_mul_f32_e32 v141, v141, v154
	v_pk_add_f32 v[82:83], v[82:83], v[98:99]
	v_mul_f32_e32 v140, v134, v140
	v_mul_f32_e32 v134, 0xbfb8aa3b, v135
	v_mul_f32_e32 v135, 0xbfb8aa3b, v154
	v_exp_f32_e32 v134, v134
	v_exp_f32_e32 v135, v135
	v_lshlrev_b32_e32 v154, 16, v169
	v_mul_f32_e32 v82, 0xbfb8aa3b, v82
	v_pk_add_f32 v[84:85], v[84:85], v[100:101]
	v_pk_add_f32 v[134:135], v[134:135], 1.0 op_sel_hi:[1,0]
	v_pk_add_f32 v[78:79], v[78:79], v[102:103]
	v_mul_f32_e32 v134, v134, v135
	v_rcp_f32_e32 v134, v134
	v_mul_f32_e32 v78, 0xbfb8aa3b, v78
	v_pk_add_f32 v[80:81], v[80:81], v[104:105]
	v_pk_add_f32 v[74:75], v[74:75], v[98:99]
	v_mul_f32_e32 v134, v141, v134
	v_lshlrev_b32_e32 v141, 16, v157
	v_cvt_pk_bf16_f32 v140, v140, v134
	v_mul_f32_e32 v134, 0xbfb8aa3b, v136
	v_mul_f32_e32 v135, 0xbfb8aa3b, v141
	v_exp_f32_e32 v134, v134
	v_exp_f32_e32 v135, v135
	v_mul_f32_e32 v136, v154, v141
	v_and_b32_e32 v154, 0xffff0000, v157
	v_and_b32_e32 v141, 0xffff0000, v169
	v_pk_add_f32 v[134:135], v[134:135], 1.0 op_sel_hi:[1,0]
	v_lshlrev_b64 v[156:157], 14, v[174:175]
	v_mul_f32_e32 v134, v134, v135
	v_rcp_f32_e32 v134, v134
	v_mul_f32_e32 v135, 0xbfb8aa3b, v154
	v_exp_f32_e32 v135, v135
	v_mul_f32_e32 v80, 0xbfb8aa3b, v80
	v_mul_f32_e32 v136, v136, v134
	v_mul_f32_e32 v134, 0xbfb8aa3b, v137
	v_exp_f32_e32 v134, v134
	v_mul_f32_e32 v137, v141, v154
	v_mul_f32_e32 v74, 0xbfb8aa3b, v74
	v_pk_add_f32 v[76:77], v[76:77], v[100:101]
	v_pk_add_f32 v[134:135], v[134:135], 1.0 op_sel_hi:[1,0]
	v_pk_add_f32 v[70:71], v[70:71], v[30:31]
	v_mul_f32_e32 v134, v134, v135
	v_rcp_f32_e32 v134, v134
	v_mul_f32_e32 v70, 0xbfb8aa3b, v70
	v_pk_add_f32 v[72:73], v[72:73], v[32:33]
	v_pk_add_f32 v[66:67], v[66:67], v[26:27]
	v_mul_f32_e32 v134, v137, v134
	v_cvt_pk_bf16_f32 v141, v136, v134
	v_lshlrev_b64 v[134:135], 13, v[230:231]
	v_lshl_add_u64 v[134:135], s[44:45], 0, v[134:135]
	v_lshlrev_b32_e32 v136, 16, v146
	v_lshl_add_u64 v[154:155], v[134:135], 0, v[204:205]
	v_exp_f32_e32 v134, v126
	v_mul_f32_e32 v126, 0xbfb8aa3b, v136
	v_exp_f32_e32 v135, v126
	v_lshlrev_b32_e32 v137, 16, v150
	v_mul_f32_e32 v126, v137, v136
	v_and_b32_e32 v136, 0xffff0000, v146
	v_pk_add_f32 v[134:135], v[134:135], 1.0 op_sel_hi:[1,0]
	global_store_dwordx4 v[154:155], v[138:141], off
	v_mul_f32_e32 v134, v134, v135
	v_rcp_f32_e32 v134, v134
	v_and_b32_e32 v135, 0xffff0000, v150
	v_mul_f32_e32 v135, v135, v136
	v_mul_f32_e32 v72, 0xbfb8aa3b, v72
	v_mul_f32_e32 v134, v126, v134
	v_mul_f32_e32 v126, 0xbfb8aa3b, v127
	v_mul_f32_e32 v127, 0xbfb8aa3b, v136
	v_exp_f32_e32 v126, v126
	v_exp_f32_e32 v127, v127
	v_lshlrev_b32_e32 v136, 16, v151
	v_mul_f32_e32 v66, 0xbfb8aa3b, v66
	v_pk_add_f32 v[68:69], v[68:69], v[28:29]
	v_pk_add_f32 v[126:127], v[126:127], 1.0 op_sel_hi:[1,0]
	v_pk_add_f32 v[62:63], v[62:63], v[30:31]
	v_mul_f32_e32 v126, v126, v127
	v_rcp_f32_e32 v126, v126
	v_lshlrev_b32_e32 v127, 16, v147
	v_mul_f32_e32 v62, 0xbfb8aa3b, v62
	v_pk_add_f32 v[64:65], v[64:65], v[32:33]
	v_mul_f32_e32 v126, v135, v126
	v_cvt_pk_bf16_f32 v126, v134, v126
	v_exp_f32_e32 v134, v128
	v_mul_f32_e32 v128, 0xbfb8aa3b, v127
	v_exp_f32_e32 v135, v128
	v_mul_f32_e32 v127, v136, v127
	v_mul_f32_e32 v64, 0xbfb8aa3b, v64
	v_pk_add_f32 v[58:59], v[58:59], v[26:27]
	v_pk_add_f32 v[134:135], v[134:135], 1.0 op_sel_hi:[1,0]
	v_mul_f32_e32 v58, 0xbfb8aa3b, v58
	v_mul_f32_e32 v128, v134, v135
	v_rcp_f32_e32 v128, v128
	v_and_b32_e32 v135, 0xffff0000, v147
	v_and_b32_e32 v134, 0xffff0000, v151
	v_mul_f32_e32 v134, v134, v135
	v_mul_f32_e32 v127, v127, v128
	v_mul_f32_e32 v128, 0xbfb8aa3b, v129
	v_mul_f32_e32 v129, 0xbfb8aa3b, v135
	v_exp_f32_e32 v128, v128
	v_exp_f32_e32 v129, v129
	v_lshlrev_b32_e32 v135, 16, v152
	v_lshlrev_b64 v[150:151], 14, v[176:177]
	v_pk_add_f32 v[60:61], v[60:61], v[28:29]
	v_pk_add_f32 v[128:129], v[128:129], 1.0 op_sel_hi:[1,0]
	v_pk_add_f32 v[54:55], v[54:55], v[30:31]
	v_mul_f32_e32 v128, v128, v129
	v_rcp_f32_e32 v128, v128
	v_mul_f32_e32 v54, 0xbfb8aa3b, v54
	v_pk_add_f32 v[56:57], v[56:57], v[32:33]
	v_pk_add_f32 v[50:51], v[50:51], v[26:27]
	v_mul_f32_e32 v128, v134, v128
	v_lshlrev_b32_e32 v134, 16, v148
	v_cvt_pk_bf16_f32 v127, v127, v128
	v_exp_f32_e32 v128, v122
	v_mul_f32_e32 v122, 0xbfb8aa3b, v134
	v_exp_f32_e32 v129, v122
	v_mul_f32_e32 v122, v135, v134
	v_and_b32_e32 v134, 0xffff0000, v148
	v_mul_f32_e32 v56, 0xbfb8aa3b, v56
	v_pk_add_f32 v[128:129], v[128:129], 1.0 op_sel_hi:[1,0]
	v_mul_f32_e32 v50, 0xbfb8aa3b, v50
	v_mul_f32_e32 v128, v128, v129
	v_rcp_f32_e32 v128, v128
	v_and_b32_e32 v129, 0xffff0000, v152
	v_mul_f32_e32 v129, v129, v134
	v_pk_add_f32 v[52:53], v[52:53], v[28:29]
	v_mul_f32_e32 v128, v122, v128
	v_mul_f32_e32 v122, 0xbfb8aa3b, v123
	v_mul_f32_e32 v123, 0xbfb8aa3b, v134
	v_exp_f32_e32 v122, v122
	v_exp_f32_e32 v123, v123
	v_lshlrev_b32_e32 v134, 16, v153
	v_pk_add_f32 v[46:47], v[46:47], v[30:31]
	v_pk_add_f32 v[48:49], v[48:49], v[32:33]
	v_pk_add_f32 v[122:123], v[122:123], 1.0 op_sel_hi:[1,0]
	v_mul_f32_e32 v46, 0xbfb8aa3b, v46
	v_mul_f32_e32 v122, v122, v123
	v_rcp_f32_e32 v122, v122
	v_mul_f32_e32 v48, 0xbfb8aa3b, v48
	v_pk_add_f32 v[42:43], v[42:43], v[26:27]
	v_pk_add_f32 v[44:45], v[44:45], v[28:29]
	v_mul_f32_e32 v122, v129, v122
	v_lshlrev_b32_e32 v129, 16, v149
	v_cvt_pk_bf16_f32 v128, v128, v122
	v_mul_f32_e32 v122, 0xbfb8aa3b, v124
	v_mul_f32_e32 v123, 0xbfb8aa3b, v129
	v_exp_f32_e32 v122, v122
	v_exp_f32_e32 v123, v123
	v_mul_f32_e32 v124, v134, v129
	v_and_b32_e32 v134, 0xffff0000, v149
	v_and_b32_e32 v129, 0xffff0000, v153
; __device__ __forceinline__ unsigned cvt_pk_bf16(float lo, float hi) { unsigned r; asm volatile("v_cvt_pk_bf16_f32 %0, %1, %2" : "=v"(r) : "v"(lo), "v"(hi)); return r; }
; __device__ __forceinline__ float bf_lo(unsigned w) { return __uint_as_float(w << 16); }
; __device__ __forceinline__ float bf_hi(unsigned w) { return __uint_as_float(w & 0xffff0000u); }
;     __device__ __forceinline__ void operator()(const f32x4 (&acc)[2][2][4][2], const Unit& u, int wr, int wc, int fr, int fq, const Pre&) const {
;     ...
;             for (int ai = 0; ai < 2; ++ai) { u32x4 zv[4], gv[4];
; #pragma unroll
;                 for (int m = 0; m < 4; ++m) { const int r = row0 + ai * HALF + m * 16; zv[m] = *(const u32x4*)(Z + (size_t)r * DE2 + c); gv[m] = *(const u32x4*)(Gm + (size_t)(c >> 4) * GSTR + r * 16 + (c & 15)); }
; #pragma unroll
;                 for (int m = 0; m < 4; ++m) { const int r = row0 + ai * HALF + m * 16;
;                     const u32x4 zw = zv[m], gw = gv[m];
;                     const f32x4 a0 = acc[ai][bj][m][0] + bs[bj][0], a1 = acc[ai][bj][m][1] + bs[bj][1];
;                     u32x4 w;
;                     w.x = cvt_pk_bf16(glu_gate_f(bf_lo(gw.x), a0[0], bf_lo(zw.x)), glu_gate_f(bf_hi(gw.x), a0[1], bf_hi(zw.x)));
;                     w.y = cvt_pk_bf16(glu_gate_f(bf_lo(gw.y), a0[2], bf_lo(zw.y)), glu_gate_f(bf_hi(gw.y), a0[3], bf_hi(zw.y)));
;                     w.z = cvt_pk_bf16(glu_gate_f(bf_lo(gw.z), a1[0], bf_lo(zw.z)), glu_gate_f(bf_hi(gw.z), a1[1], bf_hi(zw.z)));
;                     w.w = cvt_pk_bf16(glu_gate_f(bf_lo(gw.w), a1[2], bf_lo(zw.w)), glu_gate_f(bf_hi(gw.w), a1[3], bf_hi(zw.w)));
;                     *(u32x4*)(O + (size_t)r * DE + c) = w; } } }
	v_pk_add_f32 v[122:123], v[122:123], 1.0 op_sel_hi:[1,0]
	v_mul_f32_e32 v42, 0xbfb8aa3b, v42
	v_mul_f32_e32 v122, v122, v123
	v_rcp_f32_e32 v122, v122
	v_mul_f32_e32 v123, 0xbfb8aa3b, v134
	v_exp_f32_e32 v123, v123
	v_pk_add_f32 v[38:39], v[38:39], v[30:31]
	v_mul_f32_e32 v124, v124, v122
	v_mul_f32_e32 v122, 0xbfb8aa3b, v125
	v_exp_f32_e32 v122, v122
	v_mul_f32_e32 v125, v129, v134
	v_mul_f32_e32 v38, 0xbfb8aa3b, v38
	v_pk_add_f32 v[40:41], v[40:41], v[32:33]
	v_pk_add_f32 v[122:123], v[122:123], 1.0 op_sel_hi:[1,0]
	v_mul_f32_e32 v40, 0xbfb8aa3b, v40
	v_mul_f32_e32 v122, v122, v123
	v_rcp_f32_e32 v122, v122
	v_pk_add_f32 v[34:35], v[34:35], v[26:27]
	v_pk_add_f32 v[36:37], v[36:37], v[28:29]
	v_mul_f32_e32 v34, 0xbfb8aa3b, v34
	v_mul_f32_e32 v122, v125, v122
	v_cvt_pk_bf16_f32 v129, v124, v122
	v_lshlrev_b64 v[122:123], 13, v[228:229]
	v_lshl_add_u64 v[122:123], s[44:45], 0, v[122:123]
	v_lshlrev_b32_e32 v124, 16, v130
	v_lshl_add_u64 v[146:147], v[122:123], 0, v[204:205]
	v_exp_f32_e32 v122, v118
	v_mul_f32_e32 v118, 0xbfb8aa3b, v124
	v_exp_f32_e32 v123, v118
	v_lshlrev_b32_e32 v125, 16, v142
	v_mul_f32_e32 v118, v125, v124
	v_and_b32_e32 v124, 0xffff0000, v130
	v_pk_add_f32 v[122:123], v[122:123], 1.0 op_sel_hi:[1,0]
	global_store_dwordx4 v[146:147], v[126:129], off
	v_mul_f32_e32 v122, v122, v123
	v_rcp_f32_e32 v122, v122
	v_and_b32_e32 v123, 0xffff0000, v142
	v_mul_f32_e32 v123, v123, v124
	v_pk_add_f32 v[22:23], v[22:23], v[30:31]
	v_mul_f32_e32 v122, v118, v122
	v_mul_f32_e32 v118, 0xbfb8aa3b, v119
	v_mul_f32_e32 v119, 0xbfb8aa3b, v124
	v_exp_f32_e32 v118, v118
	v_exp_f32_e32 v119, v119
	v_lshlrev_b32_e32 v124, 16, v143
	v_mul_f32_e32 v22, 0xbfb8aa3b, v22
	v_pk_add_f32 v[24:25], v[24:25], v[32:33]
	v_pk_add_f32 v[118:119], v[118:119], 1.0 op_sel_hi:[1,0]
	v_mul_f32_e32 v24, 0xbfb8aa3b, v24
	v_mul_f32_e32 v118, v118, v119
	v_rcp_f32_e32 v118, v118
	v_lshlrev_b32_e32 v119, 16, v131
	v_pk_add_f32 v[18:19], v[18:19], v[26:27]
	v_pk_add_f32 v[20:21], v[20:21], v[28:29]
	v_mul_f32_e32 v118, v123, v118
	v_cvt_pk_bf16_f32 v118, v122, v118
	v_exp_f32_e32 v122, v120
	v_mul_f32_e32 v120, 0xbfb8aa3b, v119
	v_exp_f32_e32 v123, v120
	v_mul_f32_e32 v119, v124, v119
	v_mul_f32_e32 v18, 0xbfb8aa3b, v18
	v_pk_add_f32 v[14:15], v[14:15], v[30:31]
	v_pk_add_f32 v[122:123], v[122:123], 1.0 op_sel_hi:[1,0]
	v_mul_f32_e32 v14, 0xbfb8aa3b, v14
	v_mul_f32_e32 v120, v122, v123
	v_rcp_f32_e32 v120, v120
	v_and_b32_e32 v123, 0xffff0000, v131
	v_and_b32_e32 v122, 0xffff0000, v143
	v_mul_f32_e32 v122, v122, v123
	v_mul_f32_e32 v119, v119, v120
	v_mul_f32_e32 v120, 0xbfb8aa3b, v121
	v_mul_f32_e32 v121, 0xbfb8aa3b, v123
	v_exp_f32_e32 v120, v120
	v_exp_f32_e32 v121, v121
	v_lshlrev_b32_e32 v123, 16, v144
	v_pk_add_f32 v[16:17], v[16:17], v[32:33]
	v_pk_add_f32 v[10:11], v[10:11], v[26:27]
	v_pk_add_f32 v[120:121], v[120:121], 1.0 op_sel_hi:[1,0]
	v_mul_f32_e32 v16, 0xbfb8aa3b, v16
	v_mul_f32_e32 v120, v120, v121
	v_rcp_f32_e32 v120, v120
	v_mul_f32_e32 v10, 0xbfb8aa3b, v10
	v_pk_add_f32 v[12:13], v[12:13], v[28:29]
	v_pk_add_f32 v[6:7], v[6:7], v[30:31]
	v_mul_f32_e32 v120, v122, v120
	v_lshlrev_b32_e32 v122, 16, v132
	v_cvt_pk_bf16_f32 v119, v119, v120
	v_exp_f32_e32 v120, v114
	v_mul_f32_e32 v114, 0xbfb8aa3b, v122
	v_exp_f32_e32 v121, v114
	v_mul_f32_e32 v114, v123, v122
	v_and_b32_e32 v122, 0xffff0000, v132
	v_mul_f32_e32 v6, 0xbfb8aa3b, v6
	v_pk_add_f32 v[120:121], v[120:121], 1.0 op_sel_hi:[1,0]
	v_pk_add_f32 v[8:9], v[8:9], v[32:33]
	v_mul_f32_e32 v120, v120, v121
	v_rcp_f32_e32 v120, v120
	v_and_b32_e32 v121, 0xffff0000, v144
	v_mul_f32_e32 v121, v121, v122
	v_mul_f32_e32 v8, 0xbfb8aa3b, v8
	v_mul_f32_e32 v120, v114, v120
	v_mul_f32_e32 v114, 0xbfb8aa3b, v115
	v_mul_f32_e32 v115, 0xbfb8aa3b, v122
	v_exp_f32_e32 v114, v114
	v_exp_f32_e32 v115, v115
	v_lshlrev_b32_e32 v122, 16, v145
	v_pk_add_f32 v[2:3], v[2:3], v[26:27]
	v_pk_add_f32 v[4:5], v[4:5], v[28:29]
	v_pk_add_f32 v[114:115], v[114:115], 1.0 op_sel_hi:[1,0]
	v_mul_f32_e32 v2, 0xbfb8aa3b, v2
	v_mul_f32_e32 v114, v114, v115
	v_rcp_f32_e32 v114, v114
	s_nop 0
	v_mul_f32_e32 v114, v121, v114
	v_lshlrev_b32_e32 v121, 16, v133
	v_cvt_pk_bf16_f32 v120, v120, v114
	v_mul_f32_e32 v114, 0xbfb8aa3b, v116
	v_mul_f32_e32 v115, 0xbfb8aa3b, v121
	v_exp_f32_e32 v114, v114
	v_exp_f32_e32 v115, v115
	v_mul_f32_e32 v116, v122, v121
	v_and_b32_e32 v122, 0xffff0000, v133
	v_and_b32_e32 v121, 0xffff0000, v145
	v_pk_add_f32 v[114:115], v[114:115], 1.0 op_sel_hi:[1,0]
	s_nop 0
	v_mul_f32_e32 v114, v114, v115
	v_rcp_f32_e32 v114, v114
	v_mul_f32_e32 v115, 0xbfb8aa3b, v122
	v_exp_f32_e32 v115, v115
	v_mul_f32_e32 v116, v116, v114
	v_mul_f32_e32 v114, 0xbfb8aa3b, v117
	v_exp_f32_e32 v114, v114
	v_mul_f32_e32 v117, v121, v122
	v_pk_add_f32 v[114:115], v[114:115], 1.0 op_sel_hi:[1,0]
	s_nop 0
	v_mul_f32_e32 v114, v114, v115
	v_rcp_f32_e32 v114, v114
	s_nop 0
	v_mul_f32_e32 v114, v117, v114
	v_cvt_pk_bf16_f32 v121, v116, v114
	v_lshlrev_b64 v[114:115], 13, v[226:227]
	v_lshl_add_u64 v[114:115], s[44:45], 0, v[114:115]
	v_lshl_add_u64 v[148:149], v[114:115], 0, v[204:205]
	global_store_dwordx4 v[148:149], v[118:121], off
	v_lshl_add_u64 v[114:115], v[222:223], 0, v[150:151]
	global_load_dwordx4 v[138:141], v[114:115], off
	v_lshlrev_b32_e32 v118, 4, v170
	v_ashrrev_i32_e32 v119, 31, v118
	v_lshlrev_b64 v[168:169], 1, v[118:119]
	v_lshl_add_u64 v[118:119], v[220:221], 0, v[168:169]
	global_load_dwordx4 v[118:121], v[118:119], off
	v_lshlrev_b32_e32 v114, 4, v176
	v_ashrrev_i32_e32 v115, 31, v114
	v_lshlrev_b64 v[152:153], 1, v[114:115]
	v_lshl_add_u64 v[114:115], v[220:221], 0, v[152:153]
	global_load_dwordx4 v[142:145], v[114:115], off
	v_lshl_add_u64 v[114:115], v[222:223], 0, v[156:157]
	global_load_dwordx4 v[130:133], v[114:115], off
	v_lshlrev_b32_e32 v114, 4, v174
	v_ashrrev_i32_e32 v115, 31, v114
	v_lshlrev_b64 v[158:159], 1, v[114:115]
	v_lshl_add_u64 v[114:115], v[220:221], 0, v[158:159]
	global_load_dwordx4 v[134:137], v[114:115], off
	v_lshl_add_u64 v[114:115], v[222:223], 0, v[160:161]
	global_load_dwordx4 v[122:125], v[114:115], off
	v_lshlrev_b32_e32 v114, 4, v172
	v_ashrrev_i32_e32 v115, 31, v114
	v_lshlrev_b64 v[164:165], 1, v[114:115]
	v_lshl_add_u64 v[114:115], v[220:221], 0, v[164:165]
	global_load_dwordx4 v[126:129], v[114:115], off
	v_lshl_add_u64 v[114:115], v[222:223], 0, v[166:167]
	global_load_dwordx4 v[114:117], v[114:115], off
	s_waitcnt vmcnt(0)
; __device__ __forceinline__ unsigned cvt_pk_bf16(float lo, float hi) { unsigned r; asm volatile("v_cvt_pk_bf16_f32 %0, %1, %2" : "=v"(r) : "v"(lo), "v"(hi)); return r; }
; __device__ __forceinline__ float bf_lo(unsigned w) { return __uint_as_float(w << 16); }
; __device__ __forceinline__ float bf_hi(unsigned w) { return __uint_as_float(w & 0xffff0000u); }
; __device__ __forceinline__ float fast_rcp(float x) { return __builtin_amdgcn_rcpf(x); }
; __device__ __forceinline__ float glu_gate_f(float g, float v, float z) {
;     const float ev = __builtin_amdgcn_exp2f(v * -1.44269504f), ez = __builtin_amdgcn_exp2f(z * -1.44269504f);
;     return g * z * fast_rcp((1.0f + ev) * (1.0f + ez));
;     __device__ __forceinline__ void operator()(const f32x4 (&acc)[2][2][4][2], const Unit& u, int wr, int wc, int fr, int fq, const Pre&) const {
;     ...
;                 for (int m = 0; m < 4; ++m) { const int r = row0 + ai * HALF + m * 16;
;                     const u32x4 zw = zv[m], gw = gv[m];
;                     const f32x4 a0 = acc[ai][bj][m][0] + bs[bj][0], a1 = acc[ai][bj][m][1] + bs[bj][1];
;                     u32x4 w;
;                     w.x = cvt_pk_bf16(glu_gate_f(bf_lo(gw.x), a0[0], bf_lo(zw.x)), glu_gate_f(bf_hi(gw.x), a0[1], bf_hi(zw.x)));
;                     w.y = cvt_pk_bf16(glu_gate_f(bf_lo(gw.y), a0[2], bf_lo(zw.y)), glu_gate_f(bf_hi(gw.y), a0[3], bf_hi(zw.y)));
;                     w.z = cvt_pk_bf16(glu_gate_f(bf_lo(gw.z), a1[0], bf_lo(zw.z)), glu_gate_f(bf_hi(gw.z), a1[1], bf_hi(zw.z)));
;                     w.w = cvt_pk_bf16(glu_gate_f(bf_lo(gw.w), a1[2], bf_lo(zw.w)), glu_gate_f(bf_hi(gw.w), a1[3], bf_hi(zw.w)));
;                     *(u32x4*)(O + (size_t)r * DE + c) = w; } } }
	v_lshlrev_b32_e32 v186, 16, v138
	v_mul_f32_e32 v110, 0xbfb8aa3b, v186
	v_exp_f32_e32 v185, v110
	v_and_b32_e32 v138, 0xffff0000, v138
	v_pk_add_f32 v[184:185], v[184:185], 1.0 op_sel_hi:[1,0]
	s_nop 0
	v_mul_f32_e32 v184, v184, v185
	v_rcp_f32_e32 v184, v184
	v_lshlrev_b32_e32 v187, 16, v142
	v_mul_f32_e32 v110, v187, v186
	v_mul_f32_e32 v184, v110, v184
	v_mul_f32_e32 v110, 0xbfb8aa3b, v111
	v_mul_f32_e32 v111, 0xbfb8aa3b, v138
	v_exp_f32_e32 v110, v110
	v_exp_f32_e32 v111, v111
	v_and_b32_e32 v142, 0xffff0000, v142
	v_mul_f32_e32 v138, v142, v138
	v_pk_add_f32 v[110:111], v[110:111], 1.0 op_sel_hi:[1,0]
	s_nop 0
	v_mul_f32_e32 v110, v110, v111
	v_rcp_f32_e32 v110, v110
	v_lshlrev_b32_e32 v111, 16, v139
	v_and_b32_e32 v139, 0xffff0000, v139
	v_mul_f32_e32 v110, v138, v110
	v_cvt_pk_bf16_f32 v110, v184, v110
	v_exp_f32_e32 v184, v112
	v_mul_f32_e32 v112, 0xbfb8aa3b, v111
	v_exp_f32_e32 v185, v112
	v_lshlrev_b32_e32 v138, 16, v143
	v_mul_f32_e32 v111, v138, v111
	v_and_b32_e32 v138, 0xffff0000, v143
	v_pk_add_f32 v[184:185], v[184:185], 1.0 op_sel_hi:[1,0]
	v_mul_f32_e32 v138, v138, v139
	v_mul_f32_e32 v112, v184, v185
	v_rcp_f32_e32 v112, v112
	s_nop 0
	v_mul_f32_e32 v111, v111, v112
	v_mul_f32_e32 v112, 0xbfb8aa3b, v113
	v_mul_f32_e32 v113, 0xbfb8aa3b, v139
	v_exp_f32_e32 v112, v112
	v_exp_f32_e32 v113, v113
	v_lshlrev_b32_e32 v139, 16, v144
	v_pk_add_f32 v[112:113], v[112:113], 1.0 op_sel_hi:[1,0]
	s_nop 0
	v_mul_f32_e32 v112, v112, v113
	v_rcp_f32_e32 v112, v112
	s_nop 0
	v_mul_f32_e32 v112, v138, v112
	v_lshlrev_b32_e32 v138, 16, v140
	v_cvt_pk_bf16_f32 v111, v111, v112
	v_exp_f32_e32 v112, v106
	v_mul_f32_e32 v106, 0xbfb8aa3b, v138
	v_exp_f32_e32 v113, v106
	v_mul_f32_e32 v106, v139, v138
	v_and_b32_e32 v138, 0xffff0000, v140
	v_pk_add_f32 v[112:113], v[112:113], 1.0 op_sel_hi:[1,0]
	s_nop 0
	v_mul_f32_e32 v112, v112, v113
	v_rcp_f32_e32 v112, v112
	v_and_b32_e32 v113, 0xffff0000, v144
	v_mul_f32_e32 v113, v113, v138
	v_mul_f32_e32 v112, v106, v112
	v_mul_f32_e32 v106, 0xbfb8aa3b, v107
	v_mul_f32_e32 v107, 0xbfb8aa3b, v138
	v_exp_f32_e32 v106, v106
	v_exp_f32_e32 v107, v107
	v_lshlrev_b32_e32 v138, 16, v145
	v_pk_add_f32 v[106:107], v[106:107], 1.0 op_sel_hi:[1,0]
	s_nop 0
	v_mul_f32_e32 v106, v106, v107
	v_rcp_f32_e32 v106, v106
	s_nop 0
	v_mul_f32_e32 v106, v113, v106
	v_lshlrev_b32_e32 v113, 16, v141
	v_cvt_pk_bf16_f32 v112, v112, v106
	v_mul_f32_e32 v106, 0xbfb8aa3b, v108
	v_mul_f32_e32 v107, 0xbfb8aa3b, v113
	v_exp_f32_e32 v106, v106
	v_exp_f32_e32 v107, v107
	v_mul_f32_e32 v108, v138, v113
	v_and_b32_e32 v138, 0xffff0000, v141
	v_and_b32_e32 v113, 0xffff0000, v145
	v_pk_add_f32 v[106:107], v[106:107], 1.0 op_sel_hi:[1,0]
	s_nop 0
	v_mul_f32_e32 v106, v106, v107
	v_rcp_f32_e32 v106, v106
	v_mul_f32_e32 v107, 0xbfb8aa3b, v138
	v_exp_f32_e32 v107, v107
	v_mul_f32_e32 v108, v108, v106
	v_mul_f32_e32 v106, 0xbfb8aa3b, v109
	v_exp_f32_e32 v106, v106
	v_mul_f32_e32 v109, v113, v138
	v_pk_add_f32 v[106:107], v[106:107], 1.0 op_sel_hi:[1,0]
	s_nop 0
	v_mul_f32_e32 v106, v106, v107
	v_rcp_f32_e32 v106, v106
	s_nop 0
	v_mul_f32_e32 v106, v109, v106
	v_cvt_pk_bf16_f32 v113, v108, v106
	v_lshlrev_b64 v[106:107], 13, v[176:177]
	v_lshl_add_u64 v[106:107], s[44:45], 0, v[106:107]
	v_lshl_add_u64 v[106:107], v[106:107], 0, v[204:205]
	global_store_dwordx4 v[106:107], v[110:113], off
	v_exp_f32_e32 v108, v94
	s_nop 0
	v_lshlrev_b32_e32 v110, 16, v130
	v_mul_f32_e32 v94, 0xbfb8aa3b, v110
	v_exp_f32_e32 v109, v94
	v_lshlrev_b32_e32 v111, 16, v134
	v_mul_f32_e32 v94, v111, v110
	v_and_b32_e32 v110, 0xffff0000, v130
	v_pk_add_f32 v[108:109], v[108:109], 1.0 op_sel_hi:[1,0]
	s_nop 0
	v_mul_f32_e32 v108, v108, v109
	v_rcp_f32_e32 v108, v108
	v_and_b32_e32 v109, 0xffff0000, v134
	v_mul_f32_e32 v109, v109, v110
	v_mul_f32_e32 v108, v94, v108
	v_mul_f32_e32 v94, 0xbfb8aa3b, v95
	v_mul_f32_e32 v95, 0xbfb8aa3b, v110
	v_exp_f32_e32 v94, v94
	v_exp_f32_e32 v95, v95
	v_lshlrev_b32_e32 v110, 16, v135
	v_pk_add_f32 v[94:95], v[94:95], 1.0 op_sel_hi:[1,0]
	s_nop 0
	v_mul_f32_e32 v94, v94, v95
	v_rcp_f32_e32 v94, v94
	v_lshlrev_b32_e32 v95, 16, v131
	v_mul_f32_e32 v94, v109, v94
	v_cvt_pk_bf16_f32 v94, v108, v94
	v_exp_f32_e32 v108, v96
	v_mul_f32_e32 v96, 0xbfb8aa3b, v95
	v_exp_f32_e32 v109, v96
	v_mul_f32_e32 v95, v110, v95
	v_pk_add_f32 v[108:109], v[108:109], 1.0 op_sel_hi:[1,0]
	s_nop 0
	v_mul_f32_e32 v96, v108, v109
	v_rcp_f32_e32 v96, v96
	v_and_b32_e32 v109, 0xffff0000, v131
	v_and_b32_e32 v108, 0xffff0000, v135
	v_mul_f32_e32 v108, v108, v109
	v_mul_f32_e32 v95, v95, v96
	v_mul_f32_e32 v96, 0xbfb8aa3b, v97
	v_mul_f32_e32 v97, 0xbfb8aa3b, v109
	v_exp_f32_e32 v96, v96
	v_exp_f32_e32 v97, v97
	v_lshlrev_b32_e32 v109, 16, v136
	v_pk_add_f32 v[96:97], v[96:97], 1.0 op_sel_hi:[1,0]
	s_nop 0
	v_mul_f32_e32 v96, v96, v97
	v_rcp_f32_e32 v96, v96
	s_nop 0
	v_mul_f32_e32 v96, v108, v96
	v_lshlrev_b32_e32 v108, 16, v132
	v_cvt_pk_bf16_f32 v95, v95, v96
	v_exp_f32_e32 v96, v90
	v_mul_f32_e32 v90, 0xbfb8aa3b, v108
	v_exp_f32_e32 v97, v90
	v_mul_f32_e32 v90, v109, v108
	v_and_b32_e32 v108, 0xffff0000, v132
	v_pk_add_f32 v[96:97], v[96:97], 1.0 op_sel_hi:[1,0]
	s_nop 0
	v_mul_f32_e32 v96, v96, v97
	v_rcp_f32_e32 v96, v96
	v_and_b32_e32 v97, 0xffff0000, v136
	v_mul_f32_e32 v97, v97, v108
	v_mul_f32_e32 v96, v90, v96
	v_mul_f32_e32 v90, 0xbfb8aa3b, v91
	v_mul_f32_e32 v91, 0xbfb8aa3b, v108
	v_exp_f32_e32 v90, v90
	v_exp_f32_e32 v91, v91
	v_lshlrev_b32_e32 v108, 16, v137
	v_pk_add_f32 v[90:91], v[90:91], 1.0 op_sel_hi:[1,0]
	s_nop 0
	v_mul_f32_e32 v90, v90, v91
	v_rcp_f32_e32 v90, v90
	s_nop 0
	v_mul_f32_e32 v90, v97, v90
	v_lshlrev_b32_e32 v97, 16, v133
; __device__ __forceinline__ unsigned cvt_pk_bf16(float lo, float hi) { unsigned r; asm volatile("v_cvt_pk_bf16_f32 %0, %1, %2" : "=v"(r) : "v"(lo), "v"(hi)); return r; }
; __device__ __forceinline__ float bf_lo(unsigned w) { return __uint_as_float(w << 16); }
; __device__ __forceinline__ float bf_hi(unsigned w) { return __uint_as_float(w & 0xffff0000u); }
; __device__ __forceinline__ float fast_rcp(float x) { return __builtin_amdgcn_rcpf(x); }
; __device__ __forceinline__ float glu_gate_f(float g, float v, float z) {
;     const float ev = __builtin_amdgcn_exp2f(v * -1.44269504f), ez = __builtin_amdgcn_exp2f(z * -1.44269504f);
;     return g * z * fast_rcp((1.0f + ev) * (1.0f + ez));
;     __device__ __forceinline__ void operator()(const f32x4 (&acc)[2][2][4][2], const Unit& u, int wr, int wc, int fr, int fq, const Pre&) const {
;     ...
;                 for (int m = 0; m < 4; ++m) { const int r = row0 + ai * HALF + m * 16;
;                     const u32x4 zw = zv[m], gw = gv[m];
;                     const f32x4 a0 = acc[ai][bj][m][0] + bs[bj][0], a1 = acc[ai][bj][m][1] + bs[bj][1];
;                     u32x4 w;
;                     w.x = cvt_pk_bf16(glu_gate_f(bf_lo(gw.x), a0[0], bf_lo(zw.x)), glu_gate_f(bf_hi(gw.x), a0[1], bf_hi(zw.x)));
;                     w.y = cvt_pk_bf16(glu_gate_f(bf_lo(gw.y), a0[2], bf_lo(zw.y)), glu_gate_f(bf_hi(gw.y), a0[3], bf_hi(zw.y)));
;                     w.z = cvt_pk_bf16(glu_gate_f(bf_lo(gw.z), a1[0], bf_lo(zw.z)), glu_gate_f(bf_hi(gw.z), a1[1], bf_hi(zw.z)));
;                     w.w = cvt_pk_bf16(glu_gate_f(bf_lo(gw.w), a1[2], bf_lo(zw.w)), glu_gate_f(bf_hi(gw.w), a1[3], bf_hi(zw.w)));
;                     *(u32x4*)(O + (size_t)r * DE + c) = w; } } }
	v_cvt_pk_bf16_f32 v96, v96, v90
	v_mul_f32_e32 v90, 0xbfb8aa3b, v92
	v_mul_f32_e32 v91, 0xbfb8aa3b, v97
	v_exp_f32_e32 v90, v90
	v_exp_f32_e32 v91, v91
	v_mul_f32_e32 v92, v108, v97
	v_and_b32_e32 v108, 0xffff0000, v133
	v_and_b32_e32 v97, 0xffff0000, v137
	v_pk_add_f32 v[90:91], v[90:91], 1.0 op_sel_hi:[1,0]
	s_nop 0
	v_mul_f32_e32 v90, v90, v91
	v_rcp_f32_e32 v90, v90
	v_mul_f32_e32 v91, 0xbfb8aa3b, v108
	v_exp_f32_e32 v91, v91
	v_mul_f32_e32 v92, v92, v90
	v_mul_f32_e32 v90, 0xbfb8aa3b, v93
	v_exp_f32_e32 v90, v90
	v_mul_f32_e32 v93, v97, v108
	v_pk_add_f32 v[90:91], v[90:91], 1.0 op_sel_hi:[1,0]
	s_nop 0
	v_mul_f32_e32 v90, v90, v91
	v_rcp_f32_e32 v90, v90
	s_nop 0
	v_mul_f32_e32 v90, v93, v90
	v_cvt_pk_bf16_f32 v97, v92, v90
	v_lshlrev_b64 v[90:91], 13, v[174:175]
	v_lshl_add_u64 v[90:91], s[44:45], 0, v[90:91]
	v_lshlrev_b32_e32 v92, 16, v122
	v_lshl_add_u64 v[108:109], v[90:91], 0, v[204:205]
	v_exp_f32_e32 v90, v86
	v_mul_f32_e32 v86, 0xbfb8aa3b, v92
	v_exp_f32_e32 v91, v86
	v_lshlrev_b32_e32 v93, 16, v126
	v_mul_f32_e32 v86, v93, v92
	v_and_b32_e32 v92, 0xffff0000, v122
	v_pk_add_f32 v[90:91], v[90:91], 1.0 op_sel_hi:[1,0]
	global_store_dwordx4 v[108:109], v[94:97], off
	v_mul_f32_e32 v90, v90, v91
	v_rcp_f32_e32 v90, v90
	v_and_b32_e32 v91, 0xffff0000, v126
	v_mul_f32_e32 v91, v91, v92
	v_mul_f32_e32 v90, v86, v90
	v_mul_f32_e32 v86, 0xbfb8aa3b, v87
	v_mul_f32_e32 v87, 0xbfb8aa3b, v92
	v_exp_f32_e32 v86, v86
	v_exp_f32_e32 v87, v87
	v_lshlrev_b32_e32 v92, 16, v127
	v_pk_add_f32 v[86:87], v[86:87], 1.0 op_sel_hi:[1,0]
	s_nop 0
	v_mul_f32_e32 v86, v86, v87
	v_rcp_f32_e32 v86, v86
	v_lshlrev_b32_e32 v87, 16, v123
	v_mul_f32_e32 v86, v91, v86
	v_cvt_pk_bf16_f32 v86, v90, v86
	v_exp_f32_e32 v90, v88
	v_mul_f32_e32 v88, 0xbfb8aa3b, v87
	v_exp_f32_e32 v91, v88
	v_mul_f32_e32 v87, v92, v87
	v_pk_add_f32 v[90:91], v[90:91], 1.0 op_sel_hi:[1,0]
	s_nop 0
	v_mul_f32_e32 v88, v90, v91
	v_rcp_f32_e32 v88, v88
	v_and_b32_e32 v91, 0xffff0000, v123
	v_and_b32_e32 v90, 0xffff0000, v127
	v_mul_f32_e32 v90, v90, v91
	v_mul_f32_e32 v87, v87, v88
	v_mul_f32_e32 v88, 0xbfb8aa3b, v89
	v_mul_f32_e32 v89, 0xbfb8aa3b, v91
	v_exp_f32_e32 v88, v88
	v_exp_f32_e32 v89, v89
	v_lshlrev_b32_e32 v91, 16, v128
	v_pk_add_f32 v[88:89], v[88:89], 1.0 op_sel_hi:[1,0]
	s_nop 0
	v_mul_f32_e32 v88, v88, v89
	v_rcp_f32_e32 v88, v88
	s_nop 0
	v_mul_f32_e32 v88, v90, v88
	v_lshlrev_b32_e32 v90, 16, v124
	v_cvt_pk_bf16_f32 v87, v87, v88
	v_exp_f32_e32 v88, v82
	v_mul_f32_e32 v82, 0xbfb8aa3b, v90
	v_exp_f32_e32 v89, v82
	v_mul_f32_e32 v82, v91, v90
	v_and_b32_e32 v90, 0xffff0000, v124
	v_pk_add_f32 v[88:89], v[88:89], 1.0 op_sel_hi:[1,0]
	s_nop 0
	v_mul_f32_e32 v88, v88, v89
	v_rcp_f32_e32 v88, v88
	v_and_b32_e32 v89, 0xffff0000, v128
	v_mul_f32_e32 v89, v89, v90
	v_mul_f32_e32 v88, v82, v88
	v_mul_f32_e32 v82, 0xbfb8aa3b, v83
	v_mul_f32_e32 v83, 0xbfb8aa3b, v90
	v_exp_f32_e32 v82, v82
	v_exp_f32_e32 v83, v83
	v_lshlrev_b32_e32 v90, 16, v129
	v_pk_add_f32 v[82:83], v[82:83], 1.0 op_sel_hi:[1,0]
	s_nop 0
	v_mul_f32_e32 v82, v82, v83
	v_rcp_f32_e32 v82, v82
	s_nop 0
	v_mul_f32_e32 v82, v89, v82
	v_lshlrev_b32_e32 v89, 16, v125
	v_cvt_pk_bf16_f32 v88, v88, v82
	v_mul_f32_e32 v82, 0xbfb8aa3b, v84
	v_mul_f32_e32 v83, 0xbfb8aa3b, v89
	v_exp_f32_e32 v82, v82
	v_exp_f32_e32 v83, v83
	v_mul_f32_e32 v84, v90, v89
	v_and_b32_e32 v90, 0xffff0000, v125
	v_and_b32_e32 v89, 0xffff0000, v129
	v_pk_add_f32 v[82:83], v[82:83], 1.0 op_sel_hi:[1,0]
	s_nop 0
	v_mul_f32_e32 v82, v82, v83
	v_rcp_f32_e32 v82, v82
	v_mul_f32_e32 v83, 0xbfb8aa3b, v90
	v_exp_f32_e32 v83, v83
	v_mul_f32_e32 v84, v84, v82
	v_mul_f32_e32 v82, 0xbfb8aa3b, v85
	v_exp_f32_e32 v82, v82
	v_mul_f32_e32 v85, v89, v90
	v_pk_add_f32 v[82:83], v[82:83], 1.0 op_sel_hi:[1,0]
	s_nop 0
	v_mul_f32_e32 v82, v82, v83
	v_rcp_f32_e32 v82, v82
	s_nop 0
	v_mul_f32_e32 v82, v85, v82
	v_cvt_pk_bf16_f32 v89, v84, v82
	v_lshlrev_b64 v[82:83], 13, v[172:173]
	v_lshl_add_u64 v[82:83], s[44:45], 0, v[82:83]
	v_lshlrev_b32_e32 v84, 16, v114
	v_lshl_add_u64 v[110:111], v[82:83], 0, v[204:205]
	v_exp_f32_e32 v82, v78
	v_mul_f32_e32 v78, 0xbfb8aa3b, v84
	v_exp_f32_e32 v83, v78
	v_lshlrev_b32_e32 v85, 16, v118
	v_mul_f32_e32 v78, v85, v84
	v_and_b32_e32 v84, 0xffff0000, v114
	v_pk_add_f32 v[82:83], v[82:83], 1.0 op_sel_hi:[1,0]
	global_store_dwordx4 v[110:111], v[86:89], off
	v_mul_f32_e32 v82, v82, v83
	v_rcp_f32_e32 v82, v82
	v_and_b32_e32 v83, 0xffff0000, v118
	v_mul_f32_e32 v83, v83, v84
	v_exp_f32_e32 v118, v70
	v_mul_f32_e32 v82, v78, v82
	v_mul_f32_e32 v78, 0xbfb8aa3b, v79
	v_mul_f32_e32 v79, 0xbfb8aa3b, v84
	v_exp_f32_e32 v78, v78
	v_exp_f32_e32 v79, v79
	v_lshlrev_b32_e32 v84, 16, v119
	v_pk_add_f32 v[78:79], v[78:79], 1.0 op_sel_hi:[1,0]
	s_nop 0
	v_mul_f32_e32 v78, v78, v79
	v_rcp_f32_e32 v78, v78
	v_lshlrev_b32_e32 v79, 16, v115
	v_mul_f32_e32 v78, v83, v78
	v_cvt_pk_bf16_f32 v78, v82, v78
	v_exp_f32_e32 v82, v80
	v_mul_f32_e32 v80, 0xbfb8aa3b, v79
	v_exp_f32_e32 v83, v80
	v_mul_f32_e32 v79, v84, v79
	v_pk_add_f32 v[82:83], v[82:83], 1.0 op_sel_hi:[1,0]
	s_nop 0
	v_mul_f32_e32 v80, v82, v83
	v_rcp_f32_e32 v80, v80
	v_and_b32_e32 v83, 0xffff0000, v115
	v_and_b32_e32 v82, 0xffff0000, v119
	v_mul_f32_e32 v82, v82, v83
	v_mul_f32_e32 v79, v79, v80
	v_mul_f32_e32 v80, 0xbfb8aa3b, v81
	v_mul_f32_e32 v81, 0xbfb8aa3b, v83
	v_exp_f32_e32 v80, v80
	v_exp_f32_e32 v81, v81
	v_lshlrev_b32_e32 v83, 16, v120
	v_pk_add_f32 v[80:81], v[80:81], 1.0 op_sel_hi:[1,0]
	s_nop 0
	v_mul_f32_e32 v80, v80, v81
	v_rcp_f32_e32 v80, v80
	s_nop 0
	v_mul_f32_e32 v80, v82, v80
	v_lshlrev_b32_e32 v82, 16, v116
	v_cvt_pk_bf16_f32 v79, v79, v80
	v_exp_f32_e32 v80, v74
; __device__ __forceinline__ unsigned cvt_pk_bf16(float lo, float hi) { unsigned r; asm volatile("v_cvt_pk_bf16_f32 %0, %1, %2" : "=v"(r) : "v"(lo), "v"(hi)); return r; }
; __device__ __forceinline__ float bf_lo(unsigned w) { return __uint_as_float(w << 16); }
; __device__ __forceinline__ float bf_hi(unsigned w) { return __uint_as_float(w & 0xffff0000u); }
;     __device__ __forceinline__ void operator()(const f32x4 (&acc)[2][2][4][2], const Unit& u, int wr, int wc, int fr, int fq, const Pre&) const {
;     ...
;         for (int bj = 0; bj < 2; ++bj) { const int c = col0 + bj * HALF;
; #pragma unroll
;             for (int ai = 0; ai < 2; ++ai) { u32x4 zv[4], gv[4];
; #pragma unroll
;                 for (int m = 0; m < 4; ++m) { const int r = row0 + ai * HALF + m * 16; zv[m] = *(const u32x4*)(Z + (size_t)r * DE2 + c); gv[m] = *(const u32x4*)(Gm + (size_t)(c >> 4) * GSTR + r * 16 + (c & 15)); }
; #pragma unroll
;                 for (int m = 0; m < 4; ++m) { const int r = row0 + ai * HALF + m * 16;
;                     const u32x4 zw = zv[m], gw = gv[m];
;                     const f32x4 a0 = acc[ai][bj][m][0] + bs[bj][0], a1 = acc[ai][bj][m][1] + bs[bj][1];
;                     u32x4 w;
;                     w.x = cvt_pk_bf16(glu_gate_f(bf_lo(gw.x), a0[0], bf_lo(zw.x)), glu_gate_f(bf_hi(gw.x), a0[1], bf_hi(zw.x)));
;                     w.y = cvt_pk_bf16(glu_gate_f(bf_lo(gw.y), a0[2], bf_lo(zw.y)), glu_gate_f(bf_hi(gw.y), a0[3], bf_hi(zw.y)));
;                     w.z = cvt_pk_bf16(glu_gate_f(bf_lo(gw.z), a1[0], bf_lo(zw.z)), glu_gate_f(bf_hi(gw.z), a1[1], bf_hi(zw.z)));
;                     w.w = cvt_pk_bf16(glu_gate_f(bf_lo(gw.w), a1[2], bf_lo(zw.w)), glu_gate_f(bf_hi(gw.w), a1[3], bf_hi(zw.w)));
;                     *(u32x4*)(O + (size_t)r * DE + c) = w; } } }
	v_mul_f32_e32 v74, 0xbfb8aa3b, v82
	v_exp_f32_e32 v81, v74
	v_mul_f32_e32 v74, v83, v82
	v_and_b32_e32 v82, 0xffff0000, v116
	v_pk_add_f32 v[80:81], v[80:81], 1.0 op_sel_hi:[1,0]
	s_nop 0
	v_mul_f32_e32 v80, v80, v81
	v_rcp_f32_e32 v80, v80
	v_and_b32_e32 v81, 0xffff0000, v120
	v_mul_f32_e32 v81, v81, v82
	v_mul_f32_e32 v80, v74, v80
	v_mul_f32_e32 v74, 0xbfb8aa3b, v75
	v_mul_f32_e32 v75, 0xbfb8aa3b, v82
	v_exp_f32_e32 v74, v74
	v_exp_f32_e32 v75, v75
	v_lshlrev_b32_e32 v82, 16, v121
	v_pk_add_f32 v[74:75], v[74:75], 1.0 op_sel_hi:[1,0]
	s_nop 0
	v_mul_f32_e32 v74, v74, v75
	v_rcp_f32_e32 v74, v74
	s_nop 0
	v_mul_f32_e32 v74, v81, v74
	v_lshlrev_b32_e32 v81, 16, v117
	v_cvt_pk_bf16_f32 v80, v80, v74
	v_mul_f32_e32 v74, 0xbfb8aa3b, v76
	v_mul_f32_e32 v75, 0xbfb8aa3b, v81
	v_exp_f32_e32 v74, v74
	v_exp_f32_e32 v75, v75
	v_mul_f32_e32 v76, v82, v81
	v_and_b32_e32 v82, 0xffff0000, v117
	v_and_b32_e32 v81, 0xffff0000, v121
	v_pk_add_f32 v[74:75], v[74:75], 1.0 op_sel_hi:[1,0]
	s_nop 0
	v_mul_f32_e32 v74, v74, v75
	v_rcp_f32_e32 v74, v74
	v_mul_f32_e32 v75, 0xbfb8aa3b, v82
	v_exp_f32_e32 v75, v75
	v_mul_f32_e32 v76, v76, v74
	v_mul_f32_e32 v74, 0xbfb8aa3b, v77
	v_exp_f32_e32 v74, v74
	v_mul_f32_e32 v77, v81, v82
	v_pk_add_f32 v[74:75], v[74:75], 1.0 op_sel_hi:[1,0]
	s_nop 0
	v_mul_f32_e32 v74, v74, v75
	v_rcp_f32_e32 v74, v74
	s_nop 0
	v_mul_f32_e32 v74, v77, v74
	v_cvt_pk_bf16_f32 v81, v76, v74
	v_lshlrev_b64 v[74:75], 13, v[170:171]
	v_lshl_add_u64 v[74:75], s[44:45], 0, v[74:75]
	v_lshl_add_u64 v[112:113], v[74:75], 0, v[204:205]
	v_or_b32_e32 v74, 0x80, v200
	v_ashrrev_i32_e32 v75, 31, v74
	v_ashrrev_i32_e32 v76, 4, v74
	v_mad_i64_i32 v[114:115], s[4:5], v76, s94, v[194:195]
	v_lshl_add_u64 v[76:77], s[46:47], 0, v[202:203]
	v_lshlrev_b64 v[116:117], 1, v[74:75]
	v_lshl_add_u64 v[74:75], v[76:77], 0, v[116:117]
	global_load_dwordx4 v[98:101], v[74:75], off
	s_nop 0
	global_store_dwordx4 v[112:113], v[78:81], off
	s_nop 1
	v_lshl_add_u64 v[78:79], v[114:115], 0, v[218:219]
	global_load_dwordx4 v[78:81], v[78:79], off
	v_lshl_add_u64 v[74:75], v[114:115], 0, v[206:207]
	global_load_dwordx4 v[102:105], v[74:75], off
	v_lshl_add_u64 v[74:75], s[46:47], 0, v[210:211]
	v_lshl_add_u64 v[74:75], v[74:75], 0, v[116:117]
	global_load_dwordx4 v[90:93], v[74:75], off
	v_lshl_add_u64 v[74:75], v[114:115], 0, v[208:209]
	global_load_dwordx4 v[94:97], v[74:75], off
	v_lshl_add_u64 v[74:75], s[46:47], 0, v[214:215]
	v_lshl_add_u64 v[74:75], v[74:75], 0, v[116:117]
	global_load_dwordx4 v[82:85], v[74:75], off
	v_lshl_add_u64 v[74:75], v[114:115], 0, v[212:213]
	global_load_dwordx4 v[86:89], v[74:75], off
	v_lshl_add_u64 v[74:75], s[46:47], 0, v[216:217]
	v_lshl_add_u64 v[74:75], v[74:75], 0, v[116:117]
	global_load_dwordx4 v[74:77], v[74:75], off
	s_waitcnt vmcnt(0)
	v_lshlrev_b32_e32 v120, 16, v98
	v_mul_f32_e32 v70, 0xbfb8aa3b, v120
	v_exp_f32_e32 v119, v70
	v_and_b32_e32 v98, 0xffff0000, v98
	v_pk_add_f32 v[118:119], v[118:119], 1.0 op_sel_hi:[1,0]
	s_nop 0
	v_mul_f32_e32 v118, v118, v119
	v_rcp_f32_e32 v118, v118
	v_lshlrev_b32_e32 v121, 16, v102
	v_mul_f32_e32 v70, v121, v120
	v_and_b32_e32 v102, 0xffff0000, v102
	v_mul_f32_e32 v118, v70, v118
	v_mul_f32_e32 v70, 0xbfb8aa3b, v71
	v_mul_f32_e32 v71, 0xbfb8aa3b, v98
	v_exp_f32_e32 v70, v70
	v_exp_f32_e32 v71, v71
	v_mul_f32_e32 v98, v102, v98
	v_pk_add_f32 v[70:71], v[70:71], 1.0 op_sel_hi:[1,0]
	s_nop 0
	v_mul_f32_e32 v70, v70, v71
	v_rcp_f32_e32 v70, v70
	v_lshlrev_b32_e32 v71, 16, v99
	v_and_b32_e32 v99, 0xffff0000, v99
	v_mul_f32_e32 v70, v98, v70
	v_cvt_pk_bf16_f32 v70, v118, v70
	v_exp_f32_e32 v118, v72
	v_mul_f32_e32 v72, 0xbfb8aa3b, v71
	v_exp_f32_e32 v119, v72
	v_lshlrev_b32_e32 v98, 16, v103
	v_mul_f32_e32 v71, v98, v71
	v_and_b32_e32 v98, 0xffff0000, v103
	v_pk_add_f32 v[118:119], v[118:119], 1.0 op_sel_hi:[1,0]
	v_mul_f32_e32 v98, v98, v99
	v_mul_f32_e32 v72, v118, v119
	v_rcp_f32_e32 v72, v72
	s_nop 0
	v_mul_f32_e32 v71, v71, v72
	v_mul_f32_e32 v72, 0xbfb8aa3b, v73
	v_mul_f32_e32 v73, 0xbfb8aa3b, v99
	v_exp_f32_e32 v72, v72
	v_exp_f32_e32 v73, v73
	v_lshlrev_b32_e32 v99, 16, v104
	v_pk_add_f32 v[72:73], v[72:73], 1.0 op_sel_hi:[1,0]
	s_nop 0
	v_mul_f32_e32 v72, v72, v73
	v_rcp_f32_e32 v72, v72
	s_nop 0
	v_mul_f32_e32 v72, v98, v72
	v_lshlrev_b32_e32 v98, 16, v100
	v_cvt_pk_bf16_f32 v71, v71, v72
	v_exp_f32_e32 v72, v66
	v_mul_f32_e32 v66, 0xbfb8aa3b, v98
	v_exp_f32_e32 v73, v66
	v_mul_f32_e32 v66, v99, v98
	v_and_b32_e32 v98, 0xffff0000, v100
	v_pk_add_f32 v[72:73], v[72:73], 1.0 op_sel_hi:[1,0]
	s_nop 0
	v_mul_f32_e32 v72, v72, v73
	v_rcp_f32_e32 v72, v72
	v_and_b32_e32 v73, 0xffff0000, v104
	v_mul_f32_e32 v73, v73, v98
	v_mul_f32_e32 v72, v66, v72
	v_mul_f32_e32 v66, 0xbfb8aa3b, v67
	v_mul_f32_e32 v67, 0xbfb8aa3b, v98
	v_exp_f32_e32 v66, v66
	v_exp_f32_e32 v67, v67
	v_lshlrev_b32_e32 v98, 16, v105
	v_pk_add_f32 v[66:67], v[66:67], 1.0 op_sel_hi:[1,0]
	s_nop 0
	v_mul_f32_e32 v66, v66, v67
	v_rcp_f32_e32 v66, v66
	s_nop 0
	v_mul_f32_e32 v66, v73, v66
	v_lshlrev_b32_e32 v73, 16, v101
	v_cvt_pk_bf16_f32 v72, v72, v66
	v_mul_f32_e32 v66, 0xbfb8aa3b, v68
	v_mul_f32_e32 v67, 0xbfb8aa3b, v73
	v_exp_f32_e32 v66, v66
	v_exp_f32_e32 v67, v67
	v_mul_f32_e32 v68, v98, v73
	v_and_b32_e32 v98, 0xffff0000, v101
	v_and_b32_e32 v73, 0xffff0000, v105
	v_pk_add_f32 v[66:67], v[66:67], 1.0 op_sel_hi:[1,0]
	s_nop 0
	v_mul_f32_e32 v66, v66, v67
	v_rcp_f32_e32 v66, v66
	v_mul_f32_e32 v67, 0xbfb8aa3b, v98
	v_exp_f32_e32 v67, v67
	v_mul_f32_e32 v68, v68, v66
	v_mul_f32_e32 v66, 0xbfb8aa3b, v69
	v_exp_f32_e32 v66, v66
	v_mul_f32_e32 v69, v73, v98
	v_pk_add_f32 v[66:67], v[66:67], 1.0 op_sel_hi:[1,0]
	s_nop 0
; __device__ __forceinline__ unsigned cvt_pk_bf16(float lo, float hi) { unsigned r; asm volatile("v_cvt_pk_bf16_f32 %0, %1, %2" : "=v"(r) : "v"(lo), "v"(hi)); return r; }
; __device__ __forceinline__ float bf_lo(unsigned w) { return __uint_as_float(w << 16); }
; __device__ __forceinline__ float bf_hi(unsigned w) { return __uint_as_float(w & 0xffff0000u); }
; __device__ __forceinline__ float fast_rcp(float x) { return __builtin_amdgcn_rcpf(x); }
; __device__ __forceinline__ float glu_gate_f(float g, float v, float z) {
;     const float ev = __builtin_amdgcn_exp2f(v * -1.44269504f), ez = __builtin_amdgcn_exp2f(z * -1.44269504f);
;     return g * z * fast_rcp((1.0f + ev) * (1.0f + ez));
;     __device__ __forceinline__ void operator()(const f32x4 (&acc)[2][2][4][2], const Unit& u, int wr, int wc, int fr, int fq, const Pre&) const {
;     ...
;                 for (int m = 0; m < 4; ++m) { const int r = row0 + ai * HALF + m * 16;
;                     const u32x4 zw = zv[m], gw = gv[m];
;                     const f32x4 a0 = acc[ai][bj][m][0] + bs[bj][0], a1 = acc[ai][bj][m][1] + bs[bj][1];
;                     u32x4 w;
;                     w.x = cvt_pk_bf16(glu_gate_f(bf_lo(gw.x), a0[0], bf_lo(zw.x)), glu_gate_f(bf_hi(gw.x), a0[1], bf_hi(zw.x)));
;                     w.y = cvt_pk_bf16(glu_gate_f(bf_lo(gw.y), a0[2], bf_lo(zw.y)), glu_gate_f(bf_hi(gw.y), a0[3], bf_hi(zw.y)));
;                     w.z = cvt_pk_bf16(glu_gate_f(bf_lo(gw.z), a1[0], bf_lo(zw.z)), glu_gate_f(bf_hi(gw.z), a1[1], bf_hi(zw.z)));
;                     w.w = cvt_pk_bf16(glu_gate_f(bf_lo(gw.w), a1[2], bf_lo(zw.w)), glu_gate_f(bf_hi(gw.w), a1[3], bf_hi(zw.w)));
;                     *(u32x4*)(O + (size_t)r * DE + c) = w; } } }
	v_mul_f32_e32 v66, v66, v67
	v_rcp_f32_e32 v66, v66
	s_nop 0
	v_mul_f32_e32 v66, v69, v66
	v_cvt_pk_bf16_f32 v73, v68, v66
	v_lshlrev_b32_e32 v68, 16, v90
	v_exp_f32_e32 v66, v62
	v_mul_f32_e32 v62, 0xbfb8aa3b, v68
	v_exp_f32_e32 v67, v62
	v_lshlrev_b32_e32 v69, 16, v94
	v_mul_f32_e32 v62, v69, v68
	v_and_b32_e32 v68, 0xffff0000, v90
	v_pk_add_f32 v[66:67], v[66:67], 1.0 op_sel_hi:[1,0]
	global_store_dwordx4 v[162:163], v[70:73], off offset:256
	v_mul_f32_e32 v66, v66, v67
	v_rcp_f32_e32 v66, v66
	v_and_b32_e32 v67, 0xffff0000, v94
	v_mul_f32_e32 v67, v67, v68
	v_mul_f32_e32 v66, v62, v66
	v_mul_f32_e32 v62, 0xbfb8aa3b, v63
	v_mul_f32_e32 v63, 0xbfb8aa3b, v68
	v_exp_f32_e32 v62, v62
	v_exp_f32_e32 v63, v63
	v_lshlrev_b32_e32 v68, 16, v95
	v_pk_add_f32 v[62:63], v[62:63], 1.0 op_sel_hi:[1,0]
	s_nop 0
	v_mul_f32_e32 v62, v62, v63
	v_rcp_f32_e32 v62, v62
	v_lshlrev_b32_e32 v63, 16, v91
	v_mul_f32_e32 v62, v67, v62
	v_cvt_pk_bf16_f32 v62, v66, v62
	v_exp_f32_e32 v66, v64
	v_mul_f32_e32 v64, 0xbfb8aa3b, v63
	v_exp_f32_e32 v67, v64
	v_mul_f32_e32 v63, v68, v63
	v_pk_add_f32 v[66:67], v[66:67], 1.0 op_sel_hi:[1,0]
	s_nop 0
	v_mul_f32_e32 v64, v66, v67
	v_rcp_f32_e32 v64, v64
	v_and_b32_e32 v67, 0xffff0000, v91
	v_and_b32_e32 v66, 0xffff0000, v95
	v_mul_f32_e32 v66, v66, v67
	v_mul_f32_e32 v63, v63, v64
	v_mul_f32_e32 v64, 0xbfb8aa3b, v65
	v_mul_f32_e32 v65, 0xbfb8aa3b, v67
	v_exp_f32_e32 v64, v64
	v_exp_f32_e32 v65, v65
	v_lshlrev_b32_e32 v67, 16, v96
	v_pk_add_f32 v[64:65], v[64:65], 1.0 op_sel_hi:[1,0]
	s_nop 0
	v_mul_f32_e32 v64, v64, v65
	v_rcp_f32_e32 v64, v64
	s_nop 0
	v_mul_f32_e32 v64, v66, v64
	v_lshlrev_b32_e32 v66, 16, v92
	v_cvt_pk_bf16_f32 v63, v63, v64
	v_exp_f32_e32 v64, v58
	v_mul_f32_e32 v58, 0xbfb8aa3b, v66
	v_exp_f32_e32 v65, v58
	v_mul_f32_e32 v58, v67, v66
	v_and_b32_e32 v66, 0xffff0000, v92
	v_pk_add_f32 v[64:65], v[64:65], 1.0 op_sel_hi:[1,0]
	s_nop 0
	v_mul_f32_e32 v64, v64, v65
	v_rcp_f32_e32 v64, v64
	v_and_b32_e32 v65, 0xffff0000, v96
	v_mul_f32_e32 v65, v65, v66
	v_mul_f32_e32 v64, v58, v64
	v_mul_f32_e32 v58, 0xbfb8aa3b, v59
	v_mul_f32_e32 v59, 0xbfb8aa3b, v66
	v_exp_f32_e32 v58, v58
	v_exp_f32_e32 v59, v59
	v_lshlrev_b32_e32 v66, 16, v97
	v_pk_add_f32 v[58:59], v[58:59], 1.0 op_sel_hi:[1,0]
	s_nop 0
	v_mul_f32_e32 v58, v58, v59
	v_rcp_f32_e32 v58, v58
	s_nop 0
	v_mul_f32_e32 v58, v65, v58
	v_lshlrev_b32_e32 v65, 16, v93
	v_cvt_pk_bf16_f32 v64, v64, v58
	v_mul_f32_e32 v58, 0xbfb8aa3b, v60
	v_mul_f32_e32 v59, 0xbfb8aa3b, v65
	v_exp_f32_e32 v58, v58
	v_exp_f32_e32 v59, v59
	v_mul_f32_e32 v60, v66, v65
	v_and_b32_e32 v66, 0xffff0000, v93
	v_and_b32_e32 v65, 0xffff0000, v97
	v_pk_add_f32 v[58:59], v[58:59], 1.0 op_sel_hi:[1,0]
	s_nop 0
	v_mul_f32_e32 v58, v58, v59
	v_rcp_f32_e32 v58, v58
	v_mul_f32_e32 v59, 0xbfb8aa3b, v66
	v_exp_f32_e32 v59, v59
	v_mul_f32_e32 v60, v60, v58
	v_mul_f32_e32 v58, 0xbfb8aa3b, v61
	v_exp_f32_e32 v58, v58
	v_mul_f32_e32 v61, v65, v66
	v_pk_add_f32 v[58:59], v[58:59], 1.0 op_sel_hi:[1,0]
	s_nop 0
	v_mul_f32_e32 v58, v58, v59
	v_rcp_f32_e32 v58, v58
	s_nop 0
	v_mul_f32_e32 v58, v61, v58
	v_cvt_pk_bf16_f32 v65, v60, v58
	v_lshlrev_b32_e32 v60, 16, v82
	v_exp_f32_e32 v58, v54
	v_mul_f32_e32 v54, 0xbfb8aa3b, v60
	v_exp_f32_e32 v59, v54
	v_lshlrev_b32_e32 v61, 16, v86
	v_mul_f32_e32 v54, v61, v60
	v_and_b32_e32 v60, 0xffff0000, v82
	v_pk_add_f32 v[58:59], v[58:59], 1.0 op_sel_hi:[1,0]
	global_store_dwordx4 v[154:155], v[62:65], off offset:256
	v_mul_f32_e32 v58, v58, v59
	v_rcp_f32_e32 v58, v58
	v_and_b32_e32 v59, 0xffff0000, v86
	v_mul_f32_e32 v59, v59, v60
	v_mul_f32_e32 v58, v54, v58
	v_mul_f32_e32 v54, 0xbfb8aa3b, v55
	v_mul_f32_e32 v55, 0xbfb8aa3b, v60
	v_exp_f32_e32 v54, v54
	v_exp_f32_e32 v55, v55
	v_lshlrev_b32_e32 v60, 16, v87
	v_pk_add_f32 v[54:55], v[54:55], 1.0 op_sel_hi:[1,0]
	s_nop 0
	v_mul_f32_e32 v54, v54, v55
	v_rcp_f32_e32 v54, v54
	v_lshlrev_b32_e32 v55, 16, v83
	v_mul_f32_e32 v54, v59, v54
	v_cvt_pk_bf16_f32 v54, v58, v54
	v_exp_f32_e32 v58, v56
	v_mul_f32_e32 v56, 0xbfb8aa3b, v55
	v_exp_f32_e32 v59, v56
	v_mul_f32_e32 v55, v60, v55
	v_pk_add_f32 v[58:59], v[58:59], 1.0 op_sel_hi:[1,0]
	s_nop 0
	v_mul_f32_e32 v56, v58, v59
	v_rcp_f32_e32 v56, v56
	v_and_b32_e32 v59, 0xffff0000, v83
	v_and_b32_e32 v58, 0xffff0000, v87
	v_mul_f32_e32 v58, v58, v59
	v_mul_f32_e32 v55, v55, v56
	v_mul_f32_e32 v56, 0xbfb8aa3b, v57
	v_mul_f32_e32 v57, 0xbfb8aa3b, v59
	v_exp_f32_e32 v56, v56
	v_exp_f32_e32 v57, v57
	v_lshlrev_b32_e32 v59, 16, v88
	v_pk_add_f32 v[56:57], v[56:57], 1.0 op_sel_hi:[1,0]
	s_nop 0
	v_mul_f32_e32 v56, v56, v57
	v_rcp_f32_e32 v56, v56
	s_nop 0
	v_mul_f32_e32 v56, v58, v56
	v_lshlrev_b32_e32 v58, 16, v84
	v_cvt_pk_bf16_f32 v55, v55, v56
	v_exp_f32_e32 v56, v50
	v_mul_f32_e32 v50, 0xbfb8aa3b, v58
	v_exp_f32_e32 v57, v50
	v_mul_f32_e32 v50, v59, v58
	v_and_b32_e32 v58, 0xffff0000, v84
	v_pk_add_f32 v[56:57], v[56:57], 1.0 op_sel_hi:[1,0]
	s_nop 0
	v_mul_f32_e32 v56, v56, v57
	v_rcp_f32_e32 v56, v56
	v_and_b32_e32 v57, 0xffff0000, v88
	v_mul_f32_e32 v57, v57, v58
	v_mul_f32_e32 v56, v50, v56
	v_mul_f32_e32 v50, 0xbfb8aa3b, v51
	v_mul_f32_e32 v51, 0xbfb8aa3b, v58
	v_exp_f32_e32 v50, v50
	v_exp_f32_e32 v51, v51
	v_lshlrev_b32_e32 v58, 16, v89
	v_pk_add_f32 v[50:51], v[50:51], 1.0 op_sel_hi:[1,0]
	s_nop 0
	v_mul_f32_e32 v50, v50, v51
	v_rcp_f32_e32 v50, v50
	s_nop 0
	v_mul_f32_e32 v50, v57, v50
	v_lshlrev_b32_e32 v57, 16, v85
	v_cvt_pk_bf16_f32 v56, v56, v50
	v_mul_f32_e32 v50, 0xbfb8aa3b, v52
	v_mul_f32_e32 v51, 0xbfb8aa3b, v57
	v_exp_f32_e32 v50, v50
	v_exp_f32_e32 v51, v51
	v_mul_f32_e32 v52, v58, v57
	v_and_b32_e32 v58, 0xffff0000, v85
	v_and_b32_e32 v57, 0xffff0000, v89
; __device__ __forceinline__ unsigned cvt_pk_bf16(float lo, float hi) { unsigned r; asm volatile("v_cvt_pk_bf16_f32 %0, %1, %2" : "=v"(r) : "v"(lo), "v"(hi)); return r; }
; __device__ __forceinline__ float bf_lo(unsigned w) { return __uint_as_float(w << 16); }
; __device__ __forceinline__ float bf_hi(unsigned w) { return __uint_as_float(w & 0xffff0000u); }
;     __device__ __forceinline__ void operator()(const f32x4 (&acc)[2][2][4][2], const Unit& u, int wr, int wc, int fr, int fq, const Pre&) const {
;     ...
;             for (int ai = 0; ai < 2; ++ai) { u32x4 zv[4], gv[4];
; #pragma unroll
;                 for (int m = 0; m < 4; ++m) { const int r = row0 + ai * HALF + m * 16; zv[m] = *(const u32x4*)(Z + (size_t)r * DE2 + c); gv[m] = *(const u32x4*)(Gm + (size_t)(c >> 4) * GSTR + r * 16 + (c & 15)); }
; #pragma unroll
;                 for (int m = 0; m < 4; ++m) { const int r = row0 + ai * HALF + m * 16;
;                     const u32x4 zw = zv[m], gw = gv[m];
;                     const f32x4 a0 = acc[ai][bj][m][0] + bs[bj][0], a1 = acc[ai][bj][m][1] + bs[bj][1];
;                     u32x4 w;
;                     w.x = cvt_pk_bf16(glu_gate_f(bf_lo(gw.x), a0[0], bf_lo(zw.x)), glu_gate_f(bf_hi(gw.x), a0[1], bf_hi(zw.x)));
;                     w.y = cvt_pk_bf16(glu_gate_f(bf_lo(gw.y), a0[2], bf_lo(zw.y)), glu_gate_f(bf_hi(gw.y), a0[3], bf_hi(zw.y)));
;                     w.z = cvt_pk_bf16(glu_gate_f(bf_lo(gw.z), a1[0], bf_lo(zw.z)), glu_gate_f(bf_hi(gw.z), a1[1], bf_hi(zw.z)));
;                     w.w = cvt_pk_bf16(glu_gate_f(bf_lo(gw.w), a1[2], bf_lo(zw.w)), glu_gate_f(bf_hi(gw.w), a1[3], bf_hi(zw.w)));
;                     *(u32x4*)(O + (size_t)r * DE + c) = w; } } }
	v_pk_add_f32 v[50:51], v[50:51], 1.0 op_sel_hi:[1,0]
	s_nop 0
	v_mul_f32_e32 v50, v50, v51
	v_rcp_f32_e32 v50, v50
	v_mul_f32_e32 v51, 0xbfb8aa3b, v58
	v_exp_f32_e32 v51, v51
	v_mul_f32_e32 v52, v52, v50
	v_mul_f32_e32 v50, 0xbfb8aa3b, v53
	v_exp_f32_e32 v50, v50
	v_mul_f32_e32 v53, v57, v58
	v_pk_add_f32 v[50:51], v[50:51], 1.0 op_sel_hi:[1,0]
	s_nop 0
	v_mul_f32_e32 v50, v50, v51
	v_rcp_f32_e32 v50, v50
	s_nop 0
	v_mul_f32_e32 v50, v53, v50
	v_cvt_pk_bf16_f32 v57, v52, v50
	v_lshlrev_b32_e32 v52, 16, v74
	v_exp_f32_e32 v50, v46
	v_mul_f32_e32 v46, 0xbfb8aa3b, v52
	v_exp_f32_e32 v51, v46
	v_lshlrev_b32_e32 v53, 16, v78
	v_mul_f32_e32 v46, v53, v52
	v_and_b32_e32 v52, 0xffff0000, v74
	v_pk_add_f32 v[50:51], v[50:51], 1.0 op_sel_hi:[1,0]
	global_store_dwordx4 v[146:147], v[54:57], off offset:256
	v_mul_f32_e32 v50, v50, v51
	v_rcp_f32_e32 v50, v50
	v_and_b32_e32 v51, 0xffff0000, v78
	v_mul_f32_e32 v51, v51, v52
	v_exp_f32_e32 v74, v38
	v_mul_f32_e32 v50, v46, v50
	v_mul_f32_e32 v46, 0xbfb8aa3b, v47
	v_mul_f32_e32 v47, 0xbfb8aa3b, v52
	v_exp_f32_e32 v46, v46
	v_exp_f32_e32 v47, v47
	v_lshlrev_b32_e32 v52, 16, v79
	v_pk_add_f32 v[46:47], v[46:47], 1.0 op_sel_hi:[1,0]
	s_nop 0
	v_mul_f32_e32 v46, v46, v47
	v_rcp_f32_e32 v46, v46
	v_lshlrev_b32_e32 v47, 16, v75
	v_mul_f32_e32 v46, v51, v46
	v_cvt_pk_bf16_f32 v46, v50, v46
	v_exp_f32_e32 v50, v48
	v_mul_f32_e32 v48, 0xbfb8aa3b, v47
	v_exp_f32_e32 v51, v48
	v_mul_f32_e32 v47, v52, v47
	v_pk_add_f32 v[50:51], v[50:51], 1.0 op_sel_hi:[1,0]
	s_nop 0
	v_mul_f32_e32 v48, v50, v51
	v_rcp_f32_e32 v48, v48
	v_and_b32_e32 v51, 0xffff0000, v75
	v_and_b32_e32 v50, 0xffff0000, v79
	v_mul_f32_e32 v50, v50, v51
	v_mul_f32_e32 v47, v47, v48
	v_mul_f32_e32 v48, 0xbfb8aa3b, v49
	v_mul_f32_e32 v49, 0xbfb8aa3b, v51
	v_exp_f32_e32 v48, v48
	v_exp_f32_e32 v49, v49
	v_lshlrev_b32_e32 v51, 16, v80
	v_pk_add_f32 v[48:49], v[48:49], 1.0 op_sel_hi:[1,0]
	s_nop 0
	v_mul_f32_e32 v48, v48, v49
	v_rcp_f32_e32 v48, v48
	s_nop 0
	v_mul_f32_e32 v48, v50, v48
	v_lshlrev_b32_e32 v50, 16, v76
	v_cvt_pk_bf16_f32 v47, v47, v48
	v_exp_f32_e32 v48, v42
	v_mul_f32_e32 v42, 0xbfb8aa3b, v50
	v_exp_f32_e32 v49, v42
	v_mul_f32_e32 v42, v51, v50
	v_and_b32_e32 v50, 0xffff0000, v76
	v_pk_add_f32 v[48:49], v[48:49], 1.0 op_sel_hi:[1,0]
	s_nop 0
	v_mul_f32_e32 v48, v48, v49
	v_rcp_f32_e32 v48, v48
	v_and_b32_e32 v49, 0xffff0000, v80
	v_mul_f32_e32 v49, v49, v50
	v_mul_f32_e32 v48, v42, v48
	v_mul_f32_e32 v42, 0xbfb8aa3b, v43
	v_mul_f32_e32 v43, 0xbfb8aa3b, v50
	v_exp_f32_e32 v42, v42
	v_exp_f32_e32 v43, v43
	v_lshlrev_b32_e32 v50, 16, v81
	v_pk_add_f32 v[42:43], v[42:43], 1.0 op_sel_hi:[1,0]
	s_nop 0
	v_mul_f32_e32 v42, v42, v43
	v_rcp_f32_e32 v42, v42
	s_nop 0
	v_mul_f32_e32 v42, v49, v42
	v_lshlrev_b32_e32 v49, 16, v77
	v_cvt_pk_bf16_f32 v48, v48, v42
	v_mul_f32_e32 v42, 0xbfb8aa3b, v44
	v_mul_f32_e32 v43, 0xbfb8aa3b, v49
	v_exp_f32_e32 v42, v42
	v_exp_f32_e32 v43, v43
	v_mul_f32_e32 v44, v50, v49
	v_and_b32_e32 v50, 0xffff0000, v77
	v_and_b32_e32 v49, 0xffff0000, v81
	v_pk_add_f32 v[42:43], v[42:43], 1.0 op_sel_hi:[1,0]
	s_nop 0
	v_mul_f32_e32 v42, v42, v43
	v_rcp_f32_e32 v42, v42
	v_mul_f32_e32 v43, 0xbfb8aa3b, v50
	v_exp_f32_e32 v43, v43
	v_mul_f32_e32 v44, v44, v42
	v_mul_f32_e32 v42, 0xbfb8aa3b, v45
	v_exp_f32_e32 v42, v42
	v_mul_f32_e32 v45, v49, v50
	v_pk_add_f32 v[42:43], v[42:43], 1.0 op_sel_hi:[1,0]
	s_nop 0
	v_mul_f32_e32 v42, v42, v43
	v_rcp_f32_e32 v42, v42
	s_nop 0
	v_mul_f32_e32 v42, v45, v42
	v_cvt_pk_bf16_f32 v49, v44, v42
	v_lshl_add_u64 v[42:43], s[46:47], 0, v[150:151]
	global_store_dwordx4 v[148:149], v[46:49], off offset:256
	v_lshl_add_u64 v[42:43], v[42:43], 0, v[116:117]
	global_load_dwordx4 v[66:69], v[42:43], off
	v_lshl_add_u64 v[46:47], v[114:115], 0, v[168:169]
	global_load_dwordx4 v[46:49], v[46:47], off
	v_lshl_add_u64 v[42:43], v[114:115], 0, v[152:153]
	global_load_dwordx4 v[70:73], v[42:43], off
	v_lshl_add_u64 v[42:43], s[46:47], 0, v[156:157]
	v_lshl_add_u64 v[42:43], v[42:43], 0, v[116:117]
	global_load_dwordx4 v[58:61], v[42:43], off
	v_lshl_add_u64 v[42:43], v[114:115], 0, v[158:159]
	global_load_dwordx4 v[62:65], v[42:43], off
	v_lshl_add_u64 v[42:43], s[46:47], 0, v[160:161]
	v_lshl_add_u64 v[42:43], v[42:43], 0, v[116:117]
	global_load_dwordx4 v[50:53], v[42:43], off
	v_lshl_add_u64 v[42:43], v[114:115], 0, v[164:165]
	global_load_dwordx4 v[54:57], v[42:43], off
	v_lshl_add_u64 v[42:43], s[46:47], 0, v[166:167]
	v_lshl_add_u64 v[42:43], v[42:43], 0, v[116:117]
	global_load_dwordx4 v[42:45], v[42:43], off
	s_waitcnt vmcnt(0)
; __device__ __forceinline__ unsigned cvt_pk_bf16(float lo, float hi) { unsigned r; asm volatile("v_cvt_pk_bf16_f32 %0, %1, %2" : "=v"(r) : "v"(lo), "v"(hi)); return r; }
; __device__ __forceinline__ float bf_lo(unsigned w) { return __uint_as_float(w << 16); }
; __device__ __forceinline__ float bf_hi(unsigned w) { return __uint_as_float(w & 0xffff0000u); }
; __device__ __forceinline__ float fast_rcp(float x) { return __builtin_amdgcn_rcpf(x); }
; __device__ __forceinline__ float glu_gate_f(float g, float v, float z) {
;     const float ev = __builtin_amdgcn_exp2f(v * -1.44269504f), ez = __builtin_amdgcn_exp2f(z * -1.44269504f);
;     return g * z * fast_rcp((1.0f + ev) * (1.0f + ez));
;     __device__ __forceinline__ void operator()(const f32x4 (&acc)[2][2][4][2], const Unit& u, int wr, int wc, int fr, int fq, const Pre&) const {
;     ...
;                 for (int m = 0; m < 4; ++m) { const int r = row0 + ai * HALF + m * 16;
;                     const u32x4 zw = zv[m], gw = gv[m];
;                     const f32x4 a0 = acc[ai][bj][m][0] + bs[bj][0], a1 = acc[ai][bj][m][1] + bs[bj][1];
;                     u32x4 w;
;                     w.x = cvt_pk_bf16(glu_gate_f(bf_lo(gw.x), a0[0], bf_lo(zw.x)), glu_gate_f(bf_hi(gw.x), a0[1], bf_hi(zw.x)));
;                     w.y = cvt_pk_bf16(glu_gate_f(bf_lo(gw.y), a0[2], bf_lo(zw.y)), glu_gate_f(bf_hi(gw.y), a0[3], bf_hi(zw.y)));
;                     w.z = cvt_pk_bf16(glu_gate_f(bf_lo(gw.z), a1[0], bf_lo(zw.z)), glu_gate_f(bf_hi(gw.z), a1[1], bf_hi(zw.z)));
;                     w.w = cvt_pk_bf16(glu_gate_f(bf_lo(gw.w), a1[2], bf_lo(zw.w)), glu_gate_f(bf_hi(gw.w), a1[3], bf_hi(zw.w)));
;                     *(u32x4*)(O + (size_t)r * DE + c) = w; } } }
	v_lshlrev_b32_e32 v76, 16, v66
	v_mul_f32_e32 v38, 0xbfb8aa3b, v76
	v_exp_f32_e32 v75, v38
	v_and_b32_e32 v66, 0xffff0000, v66
	v_lshlrev_b32_e32 v77, 16, v70
	v_mul_f32_e32 v38, v77, v76
	v_pk_add_f32 v[74:75], v[74:75], 1.0 op_sel_hi:[1,0]
	v_and_b32_e32 v70, 0xffff0000, v70
	v_mul_f32_e32 v74, v74, v75
	v_rcp_f32_e32 v74, v74
	s_nop 0
	v_mul_f32_e32 v74, v38, v74
	v_mul_f32_e32 v38, 0xbfb8aa3b, v39
	v_mul_f32_e32 v39, 0xbfb8aa3b, v66
	v_exp_f32_e32 v38, v38
	v_exp_f32_e32 v39, v39
	v_mul_f32_e32 v66, v70, v66
	v_pk_add_f32 v[38:39], v[38:39], 1.0 op_sel_hi:[1,0]
	s_nop 0
	v_mul_f32_e32 v38, v38, v39
	v_rcp_f32_e32 v38, v38
	v_lshlrev_b32_e32 v39, 16, v67
	v_and_b32_e32 v67, 0xffff0000, v67
	v_mul_f32_e32 v38, v66, v38
	v_cvt_pk_bf16_f32 v38, v74, v38
	v_exp_f32_e32 v74, v40
	v_mul_f32_e32 v40, 0xbfb8aa3b, v39
	v_exp_f32_e32 v75, v40
	v_lshlrev_b32_e32 v66, 16, v71
	v_mul_f32_e32 v39, v66, v39
	v_and_b32_e32 v66, 0xffff0000, v71
	v_pk_add_f32 v[74:75], v[74:75], 1.0 op_sel_hi:[1,0]
	v_mul_f32_e32 v66, v66, v67
	v_mul_f32_e32 v40, v74, v75
	v_rcp_f32_e32 v40, v40
	s_nop 0
	v_mul_f32_e32 v39, v39, v40
	v_mul_f32_e32 v40, 0xbfb8aa3b, v41
	v_mul_f32_e32 v41, 0xbfb8aa3b, v67
	v_exp_f32_e32 v40, v40
	v_exp_f32_e32 v41, v41
	v_lshlrev_b32_e32 v67, 16, v72
	v_pk_add_f32 v[40:41], v[40:41], 1.0 op_sel_hi:[1,0]
	s_nop 0
	v_mul_f32_e32 v40, v40, v41
	v_rcp_f32_e32 v40, v40
	s_nop 0
	v_mul_f32_e32 v40, v66, v40
	v_lshlrev_b32_e32 v66, 16, v68
	v_cvt_pk_bf16_f32 v39, v39, v40
	v_exp_f32_e32 v40, v34
	v_mul_f32_e32 v34, 0xbfb8aa3b, v66
	v_exp_f32_e32 v41, v34
	v_mul_f32_e32 v34, v67, v66
	v_and_b32_e32 v66, 0xffff0000, v68
	v_pk_add_f32 v[40:41], v[40:41], 1.0 op_sel_hi:[1,0]
	s_nop 0
	v_mul_f32_e32 v40, v40, v41
	v_rcp_f32_e32 v40, v40
	v_and_b32_e32 v41, 0xffff0000, v72
	v_mul_f32_e32 v41, v41, v66
	v_mul_f32_e32 v40, v34, v40
	v_mul_f32_e32 v34, 0xbfb8aa3b, v35
	v_mul_f32_e32 v35, 0xbfb8aa3b, v66
	v_exp_f32_e32 v34, v34
	v_exp_f32_e32 v35, v35
	v_lshlrev_b32_e32 v66, 16, v73
	v_pk_add_f32 v[34:35], v[34:35], 1.0 op_sel_hi:[1,0]
	s_nop 0
	v_mul_f32_e32 v34, v34, v35
	v_rcp_f32_e32 v34, v34
	s_nop 0
	v_mul_f32_e32 v34, v41, v34
	v_lshlrev_b32_e32 v41, 16, v69
	v_cvt_pk_bf16_f32 v40, v40, v34
	v_mul_f32_e32 v34, 0xbfb8aa3b, v36
	v_mul_f32_e32 v35, 0xbfb8aa3b, v41
	v_exp_f32_e32 v34, v34
	v_exp_f32_e32 v35, v35
	v_mul_f32_e32 v36, v66, v41
	v_and_b32_e32 v66, 0xffff0000, v69
	v_and_b32_e32 v41, 0xffff0000, v73
	v_pk_add_f32 v[34:35], v[34:35], 1.0 op_sel_hi:[1,0]
	s_nop 0
	v_mul_f32_e32 v34, v34, v35
	v_rcp_f32_e32 v34, v34
	v_mul_f32_e32 v35, 0xbfb8aa3b, v66
	v_exp_f32_e32 v35, v35
	v_mul_f32_e32 v36, v36, v34
	v_mul_f32_e32 v34, 0xbfb8aa3b, v37
	v_exp_f32_e32 v34, v34
	v_mul_f32_e32 v37, v41, v66
	v_pk_add_f32 v[34:35], v[34:35], 1.0 op_sel_hi:[1,0]
	s_nop 0
	v_mul_f32_e32 v34, v34, v35
	v_rcp_f32_e32 v34, v34
	s_nop 0
	v_mul_f32_e32 v34, v37, v34
	v_cvt_pk_bf16_f32 v41, v36, v34
	v_lshlrev_b32_e32 v36, 16, v58
	v_exp_f32_e32 v34, v22
	v_mul_f32_e32 v22, 0xbfb8aa3b, v36
	v_exp_f32_e32 v35, v22
	v_lshlrev_b32_e32 v37, 16, v62
	v_mul_f32_e32 v22, v37, v36
	v_and_b32_e32 v36, 0xffff0000, v58
	v_pk_add_f32 v[34:35], v[34:35], 1.0 op_sel_hi:[1,0]
	global_store_dwordx4 v[106:107], v[38:41], off offset:256
	v_mul_f32_e32 v34, v34, v35
	v_rcp_f32_e32 v34, v34
	v_and_b32_e32 v35, 0xffff0000, v62
	v_mul_f32_e32 v35, v35, v36
	v_mul_f32_e32 v34, v22, v34
	v_mul_f32_e32 v22, 0xbfb8aa3b, v23
	v_mul_f32_e32 v23, 0xbfb8aa3b, v36
	v_exp_f32_e32 v22, v22
	v_exp_f32_e32 v23, v23
	v_lshlrev_b32_e32 v36, 16, v63
	v_pk_add_f32 v[22:23], v[22:23], 1.0 op_sel_hi:[1,0]
	s_nop 0
	v_mul_f32_e32 v22, v22, v23
	v_rcp_f32_e32 v22, v22
	v_lshlrev_b32_e32 v23, 16, v59
	v_mul_f32_e32 v22, v35, v22
	v_cvt_pk_bf16_f32 v22, v34, v22
	v_exp_f32_e32 v34, v24
	v_mul_f32_e32 v24, 0xbfb8aa3b, v23
	v_exp_f32_e32 v35, v24
	v_mul_f32_e32 v23, v36, v23
	v_pk_add_f32 v[34:35], v[34:35], 1.0 op_sel_hi:[1,0]
	s_nop 0
	v_mul_f32_e32 v24, v34, v35
	v_rcp_f32_e32 v24, v24
	v_and_b32_e32 v35, 0xffff0000, v59
	v_and_b32_e32 v34, 0xffff0000, v63
	v_mul_f32_e32 v34, v34, v35
	v_mul_f32_e32 v23, v23, v24
	v_mul_f32_e32 v24, 0xbfb8aa3b, v25
	v_mul_f32_e32 v25, 0xbfb8aa3b, v35
	v_exp_f32_e32 v24, v24
	v_exp_f32_e32 v25, v25
	v_lshlrev_b32_e32 v35, 16, v64
	v_pk_add_f32 v[24:25], v[24:25], 1.0 op_sel_hi:[1,0]
	s_nop 0
	v_mul_f32_e32 v24, v24, v25
	v_rcp_f32_e32 v24, v24
	s_nop 0
	v_mul_f32_e32 v24, v34, v24
	v_lshlrev_b32_e32 v34, 16, v60
	v_cvt_pk_bf16_f32 v23, v23, v24
	v_exp_f32_e32 v24, v18
	v_mul_f32_e32 v18, 0xbfb8aa3b, v34
	v_exp_f32_e32 v25, v18
	v_mul_f32_e32 v18, v35, v34
	v_and_b32_e32 v34, 0xffff0000, v60
	v_pk_add_f32 v[24:25], v[24:25], 1.0 op_sel_hi:[1,0]
	s_nop 0
	v_mul_f32_e32 v24, v24, v25
	v_rcp_f32_e32 v24, v24
	v_and_b32_e32 v25, 0xffff0000, v64
	v_mul_f32_e32 v25, v25, v34
	v_mul_f32_e32 v24, v18, v24
	v_mul_f32_e32 v18, 0xbfb8aa3b, v19
	v_mul_f32_e32 v19, 0xbfb8aa3b, v34
	v_exp_f32_e32 v18, v18
	v_exp_f32_e32 v19, v19
	v_lshlrev_b32_e32 v34, 16, v65
	v_pk_add_f32 v[18:19], v[18:19], 1.0 op_sel_hi:[1,0]
	s_nop 0
	v_mul_f32_e32 v18, v18, v19
	v_rcp_f32_e32 v18, v18
	s_nop 0
	v_mul_f32_e32 v18, v25, v18
	v_lshlrev_b32_e32 v25, 16, v61
	v_cvt_pk_bf16_f32 v24, v24, v18
	v_mul_f32_e32 v18, 0xbfb8aa3b, v20
	v_mul_f32_e32 v19, 0xbfb8aa3b, v25
	v_exp_f32_e32 v18, v18
	v_exp_f32_e32 v19, v19
	v_mul_f32_e32 v20, v34, v25
	v_and_b32_e32 v34, 0xffff0000, v61
	v_and_b32_e32 v25, 0xffff0000, v65
	v_pk_add_f32 v[18:19], v[18:19], 1.0 op_sel_hi:[1,0]
	s_nop 0
	v_mul_f32_e32 v18, v18, v19
	v_rcp_f32_e32 v18, v18
	v_mul_f32_e32 v19, 0xbfb8aa3b, v34
	v_exp_f32_e32 v19, v19
	v_mul_f32_e32 v20, v20, v18
; __device__ __forceinline__ unsigned cvt_pk_bf16(float lo, float hi) { unsigned r; asm volatile("v_cvt_pk_bf16_f32 %0, %1, %2" : "=v"(r) : "v"(lo), "v"(hi)); return r; }
; __device__ __forceinline__ float bf_lo(unsigned w) { return __uint_as_float(w << 16); }
; __device__ __forceinline__ float bf_hi(unsigned w) { return __uint_as_float(w & 0xffff0000u); }
; #define PG8_WAIT_V(n) asm volatile("s_waitcnt vmcnt(" #n ")" ::: "memory")
; #define PG8_BAR __builtin_amdgcn_s_barrier()
; template <class Epi>
; __device__ __forceinline__ void gemm_phase(LAS unsigned char* lds, const Gemm g, const StaticOrder& S, const Epi& E) {
;     ...
;         if constexpr (!Epi::AFTER_DRAIN) E(acc, cur, wr, wc, fr, fq, pre);
;         if (!has_next) break;
;     ...
;     PG8_WAIT_V(0);
;     if (wr == 0) PG8_BAR;
;     PG8_BAR;
;     __device__ __forceinline__ void operator()(const f32x4 (&acc)[2][2][4][2], const Unit& u, int wr, int wc, int fr, int fq, const Pre&) const {
;     ...
;                     w.x = cvt_pk_bf16(glu_gate_f(bf_lo(gw.x), a0[0], bf_lo(zw.x)), glu_gate_f(bf_hi(gw.x), a0[1], bf_hi(zw.x)));
;                     w.y = cvt_pk_bf16(glu_gate_f(bf_lo(gw.y), a0[2], bf_lo(zw.y)), glu_gate_f(bf_hi(gw.y), a0[3], bf_hi(zw.y)));
;                     w.z = cvt_pk_bf16(glu_gate_f(bf_lo(gw.z), a1[0], bf_lo(zw.z)), glu_gate_f(bf_hi(gw.z), a1[1], bf_hi(zw.z)));
;                     w.w = cvt_pk_bf16(glu_gate_f(bf_lo(gw.w), a1[2], bf_lo(zw.w)), glu_gate_f(bf_hi(gw.w), a1[3], bf_hi(zw.w)));
;                     *(u32x4*)(O + (size_t)r * DE + c) = w; } } }
	v_mul_f32_e32 v18, 0xbfb8aa3b, v21
	v_exp_f32_e32 v18, v18
	v_mul_f32_e32 v21, v25, v34
	v_pk_add_f32 v[18:19], v[18:19], 1.0 op_sel_hi:[1,0]
	s_nop 0
	v_mul_f32_e32 v18, v18, v19
	v_rcp_f32_e32 v18, v18
	s_nop 0
	v_mul_f32_e32 v18, v21, v18
	v_cvt_pk_bf16_f32 v25, v20, v18
	v_lshlrev_b32_e32 v20, 16, v50
	v_exp_f32_e32 v18, v14
	v_mul_f32_e32 v14, 0xbfb8aa3b, v20
	v_exp_f32_e32 v19, v14
	v_lshlrev_b32_e32 v21, 16, v54
	v_mul_f32_e32 v14, v21, v20
	v_and_b32_e32 v20, 0xffff0000, v50
	v_pk_add_f32 v[18:19], v[18:19], 1.0 op_sel_hi:[1,0]
	global_store_dwordx4 v[108:109], v[22:25], off offset:256
	v_mul_f32_e32 v18, v18, v19
	v_rcp_f32_e32 v18, v18
	v_and_b32_e32 v19, 0xffff0000, v54
	v_mul_f32_e32 v19, v19, v20
	v_mul_f32_e32 v18, v14, v18
	v_mul_f32_e32 v14, 0xbfb8aa3b, v15
	v_mul_f32_e32 v15, 0xbfb8aa3b, v20
	v_exp_f32_e32 v14, v14
	v_exp_f32_e32 v15, v15
	v_lshlrev_b32_e32 v20, 16, v55
	v_pk_add_f32 v[14:15], v[14:15], 1.0 op_sel_hi:[1,0]
	s_nop 0
	v_mul_f32_e32 v14, v14, v15
	v_rcp_f32_e32 v14, v14
	v_lshlrev_b32_e32 v15, 16, v51
	v_mul_f32_e32 v14, v19, v14
	v_cvt_pk_bf16_f32 v14, v18, v14
	v_exp_f32_e32 v18, v16
	v_mul_f32_e32 v16, 0xbfb8aa3b, v15
	v_exp_f32_e32 v19, v16
	v_mul_f32_e32 v15, v20, v15
	v_pk_add_f32 v[18:19], v[18:19], 1.0 op_sel_hi:[1,0]
	s_nop 0
	v_mul_f32_e32 v16, v18, v19
	v_rcp_f32_e32 v16, v16
	v_and_b32_e32 v19, 0xffff0000, v51
	v_and_b32_e32 v18, 0xffff0000, v55
	v_mul_f32_e32 v18, v18, v19
	v_mul_f32_e32 v15, v15, v16
	v_mul_f32_e32 v16, 0xbfb8aa3b, v17
	v_mul_f32_e32 v17, 0xbfb8aa3b, v19
	v_exp_f32_e32 v16, v16
	v_exp_f32_e32 v17, v17
	v_lshlrev_b32_e32 v19, 16, v56
	v_pk_add_f32 v[16:17], v[16:17], 1.0 op_sel_hi:[1,0]
	s_nop 0
	v_mul_f32_e32 v16, v16, v17
	v_rcp_f32_e32 v16, v16
	s_nop 0
	v_mul_f32_e32 v16, v18, v16
	v_lshlrev_b32_e32 v18, 16, v52
	v_cvt_pk_bf16_f32 v15, v15, v16
	v_exp_f32_e32 v16, v10
	v_mul_f32_e32 v10, 0xbfb8aa3b, v18
	v_exp_f32_e32 v17, v10
	v_mul_f32_e32 v10, v19, v18
	v_and_b32_e32 v18, 0xffff0000, v52
	v_pk_add_f32 v[16:17], v[16:17], 1.0 op_sel_hi:[1,0]
	s_nop 0
	v_mul_f32_e32 v16, v16, v17
	v_rcp_f32_e32 v16, v16
	v_and_b32_e32 v17, 0xffff0000, v56
	v_mul_f32_e32 v17, v17, v18
	v_mul_f32_e32 v16, v10, v16
	v_mul_f32_e32 v10, 0xbfb8aa3b, v11
	v_mul_f32_e32 v11, 0xbfb8aa3b, v18
	v_exp_f32_e32 v10, v10
	v_exp_f32_e32 v11, v11
	v_lshlrev_b32_e32 v18, 16, v57
	v_pk_add_f32 v[10:11], v[10:11], 1.0 op_sel_hi:[1,0]
	s_nop 0
	v_mul_f32_e32 v10, v10, v11
	v_rcp_f32_e32 v10, v10
	s_nop 0
	v_mul_f32_e32 v10, v17, v10
	v_lshlrev_b32_e32 v17, 16, v53
	v_cvt_pk_bf16_f32 v16, v16, v10
	v_mul_f32_e32 v10, 0xbfb8aa3b, v12
	v_mul_f32_e32 v11, 0xbfb8aa3b, v17
	v_exp_f32_e32 v10, v10
	v_exp_f32_e32 v11, v11
	v_mul_f32_e32 v12, v18, v17
	v_and_b32_e32 v18, 0xffff0000, v53
	v_and_b32_e32 v17, 0xffff0000, v57
	v_pk_add_f32 v[10:11], v[10:11], 1.0 op_sel_hi:[1,0]
	s_nop 0
	v_mul_f32_e32 v10, v10, v11
	v_rcp_f32_e32 v10, v10
	v_mul_f32_e32 v11, 0xbfb8aa3b, v18
	v_exp_f32_e32 v11, v11
	v_mul_f32_e32 v12, v12, v10
	v_mul_f32_e32 v10, 0xbfb8aa3b, v13
	v_exp_f32_e32 v10, v10
	v_mul_f32_e32 v13, v17, v18
	v_pk_add_f32 v[10:11], v[10:11], 1.0 op_sel_hi:[1,0]
	s_nop 0
	v_mul_f32_e32 v10, v10, v11
	v_rcp_f32_e32 v10, v10
	s_nop 0
	v_mul_f32_e32 v10, v13, v10
	v_cvt_pk_bf16_f32 v17, v12, v10
	v_lshlrev_b32_e32 v12, 16, v42
	v_exp_f32_e32 v10, v6
	v_mul_f32_e32 v6, 0xbfb8aa3b, v12
	v_exp_f32_e32 v11, v6
	v_lshlrev_b32_e32 v13, 16, v46
	v_mul_f32_e32 v6, v13, v12
	v_and_b32_e32 v12, 0xffff0000, v42
	v_pk_add_f32 v[10:11], v[10:11], 1.0 op_sel_hi:[1,0]
	global_store_dwordx4 v[110:111], v[14:17], off offset:256
	v_mul_f32_e32 v10, v10, v11
	v_rcp_f32_e32 v10, v10
	v_and_b32_e32 v11, 0xffff0000, v46
	v_mul_f32_e32 v11, v11, v12
	v_mul_f32_e32 v10, v6, v10
	v_mul_f32_e32 v6, 0xbfb8aa3b, v7
	v_mul_f32_e32 v7, 0xbfb8aa3b, v12
	v_exp_f32_e32 v6, v6
	v_exp_f32_e32 v7, v7
	v_lshlrev_b32_e32 v12, 16, v47
	v_pk_add_f32 v[6:7], v[6:7], 1.0 op_sel_hi:[1,0]
	s_nop 0
	v_mul_f32_e32 v6, v6, v7
	v_rcp_f32_e32 v6, v6
	v_lshlrev_b32_e32 v7, 16, v43
	v_mul_f32_e32 v6, v11, v6
	v_cvt_pk_bf16_f32 v6, v10, v6
	v_exp_f32_e32 v10, v8
	v_mul_f32_e32 v8, 0xbfb8aa3b, v7
	v_exp_f32_e32 v11, v8
	v_mul_f32_e32 v7, v12, v7
	v_pk_add_f32 v[10:11], v[10:11], 1.0 op_sel_hi:[1,0]
	s_nop 0
	v_mul_f32_e32 v8, v10, v11
	v_rcp_f32_e32 v8, v8
	v_and_b32_e32 v11, 0xffff0000, v43
	v_and_b32_e32 v10, 0xffff0000, v47
	v_mul_f32_e32 v10, v10, v11
	v_mul_f32_e32 v7, v7, v8
	v_mul_f32_e32 v8, 0xbfb8aa3b, v9
	v_mul_f32_e32 v9, 0xbfb8aa3b, v11
	v_exp_f32_e32 v8, v8
	v_exp_f32_e32 v9, v9
	v_lshlrev_b32_e32 v11, 16, v48
	v_pk_add_f32 v[8:9], v[8:9], 1.0 op_sel_hi:[1,0]
	s_nop 0
	v_mul_f32_e32 v8, v8, v9
	v_rcp_f32_e32 v8, v8
	s_nop 0
	v_mul_f32_e32 v8, v10, v8
	v_lshlrev_b32_e32 v10, 16, v44
	v_cvt_pk_bf16_f32 v7, v7, v8
	v_exp_f32_e32 v8, v2
	v_mul_f32_e32 v2, 0xbfb8aa3b, v10
	v_exp_f32_e32 v9, v2
	v_mul_f32_e32 v2, v11, v10
	v_and_b32_e32 v10, 0xffff0000, v44
	v_pk_add_f32 v[8:9], v[8:9], 1.0 op_sel_hi:[1,0]
	s_nop 0
	v_mul_f32_e32 v8, v8, v9
	v_rcp_f32_e32 v8, v8
	v_and_b32_e32 v9, 0xffff0000, v48
	v_mul_f32_e32 v9, v9, v10
	v_mul_f32_e32 v8, v2, v8
	v_mul_f32_e32 v2, 0xbfb8aa3b, v3
	v_mul_f32_e32 v3, 0xbfb8aa3b, v10
	v_exp_f32_e32 v2, v2
	v_exp_f32_e32 v3, v3
	v_lshlrev_b32_e32 v10, 16, v49
	v_pk_add_f32 v[2:3], v[2:3], 1.0 op_sel_hi:[1,0]
	s_nop 0
	v_mul_f32_e32 v2, v2, v3
	v_rcp_f32_e32 v2, v2
	s_nop 0
	v_mul_f32_e32 v2, v9, v2
	v_lshlrev_b32_e32 v9, 16, v45
	v_cvt_pk_bf16_f32 v8, v8, v2
	v_mul_f32_e32 v2, 0xbfb8aa3b, v4
	v_mul_f32_e32 v3, 0xbfb8aa3b, v9
	v_exp_f32_e32 v2, v2
	v_exp_f32_e32 v3, v3
	v_mul_f32_e32 v4, v10, v9
	v_and_b32_e32 v10, 0xffff0000, v45
	v_and_b32_e32 v9, 0xffff0000, v49
	v_pk_add_f32 v[2:3], v[2:3], 1.0 op_sel_hi:[1,0]
	s_nop 0
	v_mul_f32_e32 v2, v2, v3
	v_rcp_f32_e32 v2, v2
	v_mul_f32_e32 v3, 0xbfb8aa3b, v10
	v_exp_f32_e32 v3, v3
	v_mul_f32_e32 v4, v4, v2
	v_mul_f32_e32 v2, 0xbfb8aa3b, v5
	v_exp_f32_e32 v2, v2
	v_mul_f32_e32 v5, v9, v10
	v_pk_add_f32 v[2:3], v[2:3], 1.0 op_sel_hi:[1,0]
	s_nop 0
	v_mul_f32_e32 v2, v2, v3
	v_rcp_f32_e32 v2, v2
	s_nop 0
	v_mul_f32_e32 v2, v5, v2
	v_cvt_pk_bf16_f32 v9, v4, v2
	global_store_dwordx4 v[112:113], v[6:9], off offset:256
	s_cbranch_vccz .LBB0_789
	s_waitcnt vmcnt(0)
	v_readlane_b32 s36, v254, 56
	s_cmpk_gt_u32 s18, 0xff
	v_readlane_b32 s37, v254, 57
	s_cbranch_scc1 .LBB0_800
	s_barrier
